# S5 scans: 16-long dependent packed-fma chain per step split into two 8-long chains; S5 pass 2 on waves 3 and 7 only
# baseline (speedup 1.0000x reference)
; #define LAS __attribute__((address_space(3)))
; template <int PASS>
; __device__ __forceinline__ void s5_scan(const Params& p, int l, int widx, int nw, int beff, int nblk, int lane, LAS unsigned char* lds) {
;     ...
;             for (int s = 0; s < 16; ++s) {
;                 const f32x4 u0 = *(LAS f32x4*)(ubc + s * 16), u1 = *(LAS f32x4*)(ubc + s * 16 + 4), u2 = *(LAS f32x4*)(ubc + s * 16 + 8), u3 = *(LAS f32x4*)(ubc + s * 16 + 12);
;                 float bur = 0.f, bui = 0.f;
; #pragma unroll
;                 for (int j = 0; j < 4; ++j) { bur += br[j] * u0[j]; bui += bi[j] * u0[j]; }
; #pragma unroll
;                 for (int j = 0; j < 4; ++j) { bur += br[4 + j] * u1[j]; bui += bi[4 + j] * u1[j]; }
; #pragma unroll
;                 for (int j = 0; j < 4; ++j) { bur += br[8 + j] * u2[j]; bui += bi[8 + j] * u2[j]; }
; #pragma unroll
;                 for (int j = 0; j < 4; ++j) { bur += br[12 + j] * u3[j]; bui += bi[12 + j] * u3[j]; }
;                 const float nxr = ar * xr - ai * xi + bur, nxi = ar * xi + ai * xr + bui; xr = nxr; xi = nxi;
;                 if (PASS == 2) { xb[s * 132 + lane] = xr; xb[s * 132 + 64 + lane] = xi; }
.LBB0_337:
	v_add_u32_e32 v57, s5, v38
	ds_read_b128 v[40:43], v57
	ds_read_b128 v[66:69], v57 offset:16
	ds_read_b128 v[76:79], v57 offset:32
	ds_read_b128 v[80:83], v57 offset:48
	s_addk_i32 s5, 0x100
	s_waitcnt lgkmcnt(0)
	v_pk_fma_f32 v[36:37], v[8:9], v[40:41], 0 op_sel_hi:[1,0,0]
	s_cmpk_eq_i32 s5, 0x400
	v_pk_fma_f32 v[36:37], v[10:11], v[40:41], v[36:37] op_sel:[0,1,0]
	v_mov_b32_e32 v40, v43
	v_pk_fma_f32 v[36:37], v[4:5], v[42:43], v[36:37] op_sel_hi:[1,0,1]
	v_mov_b32_e32 v42, v69
	v_pk_fma_f32 v[36:37], v[6:7], v[40:41], v[36:37] op_sel_hi:[1,0,1]
	v_pk_mul_f32 v[40:41], v[62:63], v[54:55] op_sel:[0,1]
	v_pk_fma_f32 v[36:37], v[0:1], v[66:67], v[36:37] op_sel_hi:[1,0,1]
	s_nop 0
	v_pk_fma_f32 v[36:37], v[2:3], v[66:67], v[36:37] op_sel:[0,1,0]
	s_nop 0
	v_pk_fma_f32 v[36:37], v[24:25], v[68:69], v[36:37] op_sel_hi:[1,0,1]
	s_nop 0
	v_pk_fma_f32 v[36:37], v[26:27], v[42:43], v[36:37] op_sel_hi:[1,0,1]
	v_mov_b32_e32 v42, v79
	v_pk_fma_f32 v[150:151], v[28:29], v[76:77], 0 op_sel_hi:[1,0,0]
	s_nop 0
	v_pk_fma_f32 v[150:151], v[30:31], v[76:77], v[150:151] op_sel:[0,1,0]
	s_nop 0
	v_pk_fma_f32 v[150:151], v[20:21], v[78:79], v[150:151] op_sel_hi:[1,0,1]
	s_nop 0
	v_pk_fma_f32 v[150:151], v[22:23], v[42:43], v[150:151] op_sel_hi:[1,0,1]
	v_mov_b32_e32 v42, v83
	v_pk_fma_f32 v[150:151], v[16:17], v[80:81], v[150:151] op_sel_hi:[1,0,1]
	s_nop 0
	v_pk_fma_f32 v[150:151], v[18:19], v[80:81], v[150:151] op_sel:[0,1,0]
	s_nop 0
	v_pk_fma_f32 v[150:151], v[12:13], v[82:83], v[150:151] op_sel_hi:[1,0,1]
	s_nop 0
	v_pk_fma_f32 v[150:151], v[14:15], v[42:43], v[150:151] op_sel_hi:[1,0,1]
	s_nop 0
	v_pk_add_f32 v[36:37], v[36:37], v[150:151]
	v_pk_fma_f32 v[42:43], v[52:53], v[54:55], v[40:41] neg_lo:[0,0,1] neg_hi:[0,0,1]
	v_pk_fma_f32 v[40:41], v[52:53], v[54:55], v[40:41] op_sel_hi:[1,0,1]
	s_nop 0
	v_mov_b32_e32 v43, v41
	v_pk_add_f32 v[36:37], v[42:43], v[36:37]
	ds_write2st64_b32 v39, v36, v37 offset1:1
	ds_read_b128 v[40:43], v57 offset:64
	ds_read_b128 v[66:69], v57 offset:80
	ds_read_b128 v[76:79], v57 offset:96
	ds_read_b128 v[80:83], v57 offset:112
	s_waitcnt lgkmcnt(3)
	v_pk_fma_f32 v[54:55], v[8:9], v[40:41], 0 op_sel_hi:[1,0,0]
	s_nop 0
	v_pk_fma_f32 v[40:41], v[10:11], v[40:41], v[54:55] op_sel:[0,1,0]
	s_waitcnt lgkmcnt(2)
	v_mov_b32_e32 v54, v69
	v_pk_fma_f32 v[40:41], v[4:5], v[42:43], v[40:41] op_sel_hi:[1,0,1]
	v_mov_b32_e32 v42, v43
	v_pk_fma_f32 v[40:41], v[6:7], v[42:43], v[40:41] op_sel_hi:[1,0,1]
	v_pk_mul_f32 v[42:43], v[62:63], v[36:37] op_sel:[0,1]
	v_pk_fma_f32 v[40:41], v[0:1], v[66:67], v[40:41] op_sel_hi:[1,0,1]
	s_nop 0
	v_pk_fma_f32 v[40:41], v[2:3], v[66:67], v[40:41] op_sel:[0,1,0]
	s_nop 0
	v_pk_fma_f32 v[40:41], v[24:25], v[68:69], v[40:41] op_sel_hi:[1,0,1]
	s_nop 0
	v_pk_fma_f32 v[40:41], v[26:27], v[54:55], v[40:41] op_sel_hi:[1,0,1]
	s_waitcnt lgkmcnt(1)
	v_mov_b32_e32 v54, v79
	v_pk_fma_f32 v[150:151], v[28:29], v[76:77], 0 op_sel_hi:[1,0,0]
	s_nop 0
	v_pk_fma_f32 v[150:151], v[30:31], v[76:77], v[150:151] op_sel:[0,1,0]
	s_nop 0
	v_pk_fma_f32 v[150:151], v[20:21], v[78:79], v[150:151] op_sel_hi:[1,0,1]
	s_nop 0
	v_pk_fma_f32 v[150:151], v[22:23], v[54:55], v[150:151] op_sel_hi:[1,0,1]
	s_waitcnt lgkmcnt(0)
	v_mov_b32_e32 v54, v83
	v_pk_fma_f32 v[150:151], v[16:17], v[80:81], v[150:151] op_sel_hi:[1,0,1]
	s_nop 0
	v_pk_fma_f32 v[150:151], v[18:19], v[80:81], v[150:151] op_sel:[0,1,0]
	s_nop 0
	v_pk_fma_f32 v[150:151], v[12:13], v[82:83], v[150:151] op_sel_hi:[1,0,1]
	s_nop 0
	v_pk_fma_f32 v[150:151], v[14:15], v[54:55], v[150:151] op_sel_hi:[1,0,1]
	s_nop 0
	v_pk_add_f32 v[40:41], v[40:41], v[150:151]
	v_pk_fma_f32 v[54:55], v[52:53], v[36:37], v[42:43] neg_lo:[0,0,1] neg_hi:[0,0,1]
	v_pk_fma_f32 v[36:37], v[52:53], v[36:37], v[42:43] op_sel_hi:[1,0,1]
	s_nop 0
	v_mov_b32_e32 v55, v37
	v_pk_add_f32 v[36:37], v[54:55], v[40:41]
	ds_write2_b32 v39, v36, v37 offset0:132 offset1:196
	ds_read_b128 v[40:43], v57 offset:128
	ds_read_b128 v[66:69], v57 offset:144
	ds_read_b128 v[76:79], v57 offset:160
	ds_read_b128 v[80:83], v57 offset:176
	s_waitcnt lgkmcnt(3)
	v_pk_fma_f32 v[54:55], v[8:9], v[40:41], 0 op_sel_hi:[1,0,0]
	s_nop 0
	v_pk_fma_f32 v[40:41], v[10:11], v[40:41], v[54:55] op_sel:[0,1,0]
	s_waitcnt lgkmcnt(2)
	v_mov_b32_e32 v54, v69
	v_pk_fma_f32 v[40:41], v[4:5], v[42:43], v[40:41] op_sel_hi:[1,0,1]
	v_mov_b32_e32 v42, v43
	v_pk_fma_f32 v[40:41], v[6:7], v[42:43], v[40:41] op_sel_hi:[1,0,1]
	v_pk_mul_f32 v[42:43], v[62:63], v[36:37] op_sel:[0,1]
	v_pk_fma_f32 v[40:41], v[0:1], v[66:67], v[40:41] op_sel_hi:[1,0,1]
	s_nop 0
	v_pk_fma_f32 v[40:41], v[2:3], v[66:67], v[40:41] op_sel:[0,1,0]
	s_nop 0
	v_pk_fma_f32 v[40:41], v[24:25], v[68:69], v[40:41] op_sel_hi:[1,0,1]
	s_nop 0
	v_pk_fma_f32 v[40:41], v[26:27], v[54:55], v[40:41] op_sel_hi:[1,0,1]
	s_waitcnt lgkmcnt(1)
	v_mov_b32_e32 v54, v79
	v_pk_fma_f32 v[150:151], v[28:29], v[76:77], 0 op_sel_hi:[1,0,0]
	s_nop 0
	v_pk_fma_f32 v[150:151], v[30:31], v[76:77], v[150:151] op_sel:[0,1,0]
	s_nop 0
	v_pk_fma_f32 v[150:151], v[20:21], v[78:79], v[150:151] op_sel_hi:[1,0,1]
	s_nop 0
	v_pk_fma_f32 v[150:151], v[22:23], v[54:55], v[150:151] op_sel_hi:[1,0,1]
	s_waitcnt lgkmcnt(0)
	v_mov_b32_e32 v54, v83
	v_pk_fma_f32 v[150:151], v[16:17], v[80:81], v[150:151] op_sel_hi:[1,0,1]
	s_nop 0
	v_pk_fma_f32 v[150:151], v[18:19], v[80:81], v[150:151] op_sel:[0,1,0]
	s_nop 0
	v_pk_fma_f32 v[150:151], v[12:13], v[82:83], v[150:151] op_sel_hi:[1,0,1]
	s_nop 0
	v_pk_fma_f32 v[150:151], v[14:15], v[54:55], v[150:151] op_sel_hi:[1,0,1]
	s_nop 0
	v_pk_add_f32 v[40:41], v[40:41], v[150:151]
	v_pk_fma_f32 v[54:55], v[52:53], v[36:37], v[42:43] neg_lo:[0,0,1] neg_hi:[0,0,1]
	v_pk_fma_f32 v[36:37], v[52:53], v[36:37], v[42:43] op_sel_hi:[1,0,1]
	s_nop 0
	v_mov_b32_e32 v55, v37
	v_pk_add_f32 v[36:37], v[54:55], v[40:41]
	v_add_u32_e32 v40, 32, v39
	ds_write2st64_b32 v40, v36, v37 offset0:4 offset1:5
	ds_read_b128 v[40:43], v57 offset:192
	ds_read_b128 v[66:69], v57 offset:208
	ds_read_b128 v[76:79], v57 offset:224
	ds_read_b128 v[80:83], v57 offset:240
	s_waitcnt lgkmcnt(3)
; #define LAS __attribute__((address_space(3)))
; #define WAVE_SYNC() asm volatile("s_waitcnt lgkmcnt(0)" ::: "memory")
; __device__ __forceinline__ float dot4(f32x4 a, f32x4 b) { return (a.x * b.x + a.y * b.y) + (a.z * b.z + a.w * b.w); }
; __device__ __forceinline__ float gelu_tanh(float x) { const float t = tanhf(0.7978845608028654f * (x + 0.044715f * x * x * x)); return 0.5f * x * (1.0f + t); }
; template <int PASS>
; __device__ __forceinline__ void s5_scan(const Params& p, int l, int widx, int nw, int beff, int nblk, int lane, LAS unsigned char* lds) {
;     ...
;             for (int s = 0; s < 16; ++s) {
;                 const f32x4 u0 = *(LAS f32x4*)(ubc + s * 16), u1 = *(LAS f32x4*)(ubc + s * 16 + 4), u2 = *(LAS f32x4*)(ubc + s * 16 + 8), u3 = *(LAS f32x4*)(ubc + s * 16 + 12);
;                 float bur = 0.f, bui = 0.f;
; #pragma unroll
;                 for (int j = 0; j < 4; ++j) { bur += br[j] * u0[j]; bui += bi[j] * u0[j]; }
; #pragma unroll
;                 for (int j = 0; j < 4; ++j) { bur += br[4 + j] * u1[j]; bui += bi[4 + j] * u1[j]; }
; #pragma unroll
;                 for (int j = 0; j < 4; ++j) { bur += br[8 + j] * u2[j]; bui += bi[8 + j] * u2[j]; }
; #pragma unroll
;                 for (int j = 0; j < 4; ++j) { bur += br[12 + j] * u3[j]; bui += bi[12 + j] * u3[j]; }
;                 const float nxr = ar * xr - ai * xi + bur, nxi = ar * xi + ai * xr + bui; xr = nxr; xi = nxi;
;                 if (PASS == 2) { xb[s * 132 + lane] = xr; xb[s * 132 + 64 + lane] = xi; }
;             }
;             if (PASS == 2) {
;                 WAVE_SYNC();
;                 const int s = lane >> 2, c4 = lane & 3;
;                 f32x4 y = {0.f, 0.f, 0.f, 0.f};
; #pragma unroll 4
;                 for (int n4 = 0; n4 < 32; ++n4) {
;                     const f32x4 xv = *(LAS f32x4*)(xb + s * 132 + n4 * 4);
; #pragma unroll
;                     for (int j = 0; j < 4; ++j) { const f32x4 cv = *(LAS f32x4*)(ct + (c4 * 4 + j) * 132 + n4 * 4); y[j] += dot4(xv, cv); }
;                 }
;                 const f32x4 uu = *(LAS f32x4*)(ubc + s * 16 + c4 * 4);
;                 const f32x4 dsk = *(const f32x4*)(p.in[30] + l * 512 + g * 16 + c4 * 4);
;                 y = y + dsk * uu;
;                 y.x = gelu_tanh(y.x); y.y = gelu_tanh(y.y); y.z = gelu_tanh(y.z); y.w = gelu_tanh(y.w);
	v_pk_fma_f32 v[54:55], v[8:9], v[40:41], 0 op_sel_hi:[1,0,0]
	s_nop 0
	v_pk_fma_f32 v[40:41], v[10:11], v[40:41], v[54:55] op_sel:[0,1,0]
	s_waitcnt lgkmcnt(2)
	v_mov_b32_e32 v54, v69
	v_pk_fma_f32 v[40:41], v[4:5], v[42:43], v[40:41] op_sel_hi:[1,0,1]
	v_mov_b32_e32 v42, v43
	v_pk_fma_f32 v[40:41], v[6:7], v[42:43], v[40:41] op_sel_hi:[1,0,1]
	v_pk_mul_f32 v[42:43], v[62:63], v[36:37] op_sel:[0,1]
	v_pk_fma_f32 v[40:41], v[0:1], v[66:67], v[40:41] op_sel_hi:[1,0,1]
	s_nop 0
	v_pk_fma_f32 v[40:41], v[2:3], v[66:67], v[40:41] op_sel:[0,1,0]
	s_nop 0
	v_pk_fma_f32 v[40:41], v[24:25], v[68:69], v[40:41] op_sel_hi:[1,0,1]
	s_nop 0
	v_pk_fma_f32 v[40:41], v[26:27], v[54:55], v[40:41] op_sel_hi:[1,0,1]
	s_waitcnt lgkmcnt(1)
	v_mov_b32_e32 v54, v79
	v_pk_fma_f32 v[150:151], v[28:29], v[76:77], 0 op_sel_hi:[1,0,0]
	s_nop 0
	v_pk_fma_f32 v[150:151], v[30:31], v[76:77], v[150:151] op_sel:[0,1,0]
	s_nop 0
	v_pk_fma_f32 v[150:151], v[20:21], v[78:79], v[150:151] op_sel_hi:[1,0,1]
	s_nop 0
	v_pk_fma_f32 v[150:151], v[22:23], v[54:55], v[150:151] op_sel_hi:[1,0,1]
	s_waitcnt lgkmcnt(0)
	v_mov_b32_e32 v54, v83
	v_pk_fma_f32 v[150:151], v[16:17], v[80:81], v[150:151] op_sel_hi:[1,0,1]
	s_nop 0
	v_pk_fma_f32 v[150:151], v[18:19], v[80:81], v[150:151] op_sel:[0,1,0]
	s_nop 0
	v_pk_fma_f32 v[150:151], v[12:13], v[82:83], v[150:151] op_sel_hi:[1,0,1]
	s_nop 0
	v_pk_fma_f32 v[150:151], v[14:15], v[54:55], v[150:151] op_sel_hi:[1,0,1]
	s_nop 0
	v_pk_add_f32 v[40:41], v[40:41], v[150:151]
	v_pk_fma_f32 v[54:55], v[52:53], v[36:37], v[42:43] neg_lo:[0,0,1] neg_hi:[0,0,1]
	v_pk_fma_f32 v[36:37], v[52:53], v[36:37], v[42:43] op_sel_hi:[1,0,1]
	s_nop 0
	v_mov_b32_e32 v55, v37
	v_pk_add_f32 v[54:55], v[54:55], v[40:41]
	v_add_u32_e32 v36, 48, v39
	v_add_u32_e32 v39, 0x840, v39
	ds_write2st64_b32 v36, v54, v55 offset0:6 offset1:7
	s_cbranch_scc0 .LBB0_337
	s_waitcnt lgkmcnt(0)
	v_mov_b32_e32 v84, 0
	v_mov_b32_e32 v85, 0
	v_mov_b32_e32 v86, 0
	v_mov_b32_e32 v87, 0
	ds_read_b128 v[148:151], v134
	ds_read_b128 v[152:155], v134 offset:64
	ds_read_b128 v[158:161], v134 offset:128
	ds_read_b128 v[162:165], v134 offset:192
	ds_read_b128 v[166:169], v134 offset:256
	ds_read_b128 v[170:173], v134 offset:320
	ds_read_b128 v[174:177], v134 offset:384
	ds_read_b128 v[178:181], v134 offset:448
	s_waitcnt lgkmcnt(7)
	v_mfma_f32_16x16x4_f32 v[84:87], v148, v106, v[84:87]
	v_mfma_f32_16x16x4_f32 v[84:87], v149, v107, v[84:87]
	v_mfma_f32_16x16x4_f32 v[84:87], v150, v108, v[84:87]
	v_mfma_f32_16x16x4_f32 v[84:87], v151, v109, v[84:87]
	s_waitcnt lgkmcnt(6)
	v_mfma_f32_16x16x4_f32 v[84:87], v152, v110, v[84:87]
	v_mfma_f32_16x16x4_f32 v[84:87], v153, v111, v[84:87]
	v_mfma_f32_16x16x4_f32 v[84:87], v154, v112, v[84:87]
	v_mfma_f32_16x16x4_f32 v[84:87], v155, v113, v[84:87]
	s_waitcnt lgkmcnt(5)
	v_mfma_f32_16x16x4_f32 v[84:87], v158, v114, v[84:87]
	v_mfma_f32_16x16x4_f32 v[84:87], v159, v115, v[84:87]
	v_mfma_f32_16x16x4_f32 v[84:87], v160, v116, v[84:87]
	v_mfma_f32_16x16x4_f32 v[84:87], v161, v117, v[84:87]
	s_waitcnt lgkmcnt(4)
	v_mfma_f32_16x16x4_f32 v[84:87], v162, v118, v[84:87]
	v_mfma_f32_16x16x4_f32 v[84:87], v163, v119, v[84:87]
	v_mfma_f32_16x16x4_f32 v[84:87], v164, v120, v[84:87]
	v_mfma_f32_16x16x4_f32 v[84:87], v165, v121, v[84:87]
	s_waitcnt lgkmcnt(3)
	v_mfma_f32_16x16x4_f32 v[84:87], v166, v122, v[84:87]
	v_mfma_f32_16x16x4_f32 v[84:87], v167, v123, v[84:87]
	v_mfma_f32_16x16x4_f32 v[84:87], v168, v124, v[84:87]
	v_mfma_f32_16x16x4_f32 v[84:87], v169, v125, v[84:87]
	s_waitcnt lgkmcnt(2)
	v_mfma_f32_16x16x4_f32 v[84:87], v170, v126, v[84:87]
	v_mfma_f32_16x16x4_f32 v[84:87], v171, v127, v[84:87]
	v_mfma_f32_16x16x4_f32 v[84:87], v172, v128, v[84:87]
	v_mfma_f32_16x16x4_f32 v[84:87], v173, v129, v[84:87]
	s_waitcnt lgkmcnt(1)
	v_mfma_f32_16x16x4_f32 v[84:87], v174, v130, v[84:87]
	v_mfma_f32_16x16x4_f32 v[84:87], v175, v131, v[84:87]
	v_mfma_f32_16x16x4_f32 v[84:87], v176, v132, v[84:87]
	v_mfma_f32_16x16x4_f32 v[84:87], v177, v133, v[84:87]
	s_waitcnt lgkmcnt(0)
	v_mfma_f32_16x16x4_f32 v[84:87], v178, v144, v[84:87]
	v_mfma_f32_16x16x4_f32 v[84:87], v179, v145, v[84:87]
	v_mfma_f32_16x16x4_f32 v[84:87], v180, v146, v[84:87]
	v_mfma_f32_16x16x4_f32 v[84:87], v181, v147, v[84:87]
	s_nop 7
	s_nop 3
	ds_write_b32 v135, v84
	ds_write_b32 v135, v85 offset:64
	ds_write_b32 v135, v86 offset:128
	ds_write_b32 v135, v87 offset:192
	s_waitcnt lgkmcnt(0)
	ds_read_b64 v[68:69], v138
	ds_read_b64 v[66:67], v138 offset:8
	global_load_dwordx4 v[36:39], v[60:61], off
	v_add3_u32 v40, s4, v71, v136
	ds_read_b128 v[40:43], v40 offset:24576
	s_mov_b32 s3, 0x3f200000
	s_waitcnt vmcnt(0) lgkmcnt(0)
	v_pk_fma_f32 v[36:37], v[40:41], v[36:37], v[68:69]
	s_nop 0
	v_mul_f32_e32 v40, 0x3d372713, v36
	v_mul_f32_e32 v40, v36, v40
	v_fma_f32 v40, v36, v40, v36
	v_mul_f32_e32 v40, 0x3f4c422a, v40
	v_cmp_nlt_f32_e64 s[4:5], |v40|, s3
	s_and_saveexec_b64 s[12:13], s[4:5]
	s_xor_b64 s[4:5], exec, s[12:13]
	s_cbranch_execz .LBB0_342
	v_add_f32_e64 v41, |v40|, |v40|
	v_mul_f32_e32 v57, 0x3fb8aa3b, v41
	v_rndne_f32_e32 v68, v57
	s_mov_b32 s3, 0x3fb8aa3b
	v_sub_f32_e32 v69, v57, v68
	v_fma_f32 v57, v41, s3, -v57
	v_fmac_f32_e32 v57, 0x32a5705f, v41
	v_add_f32_e32 v57, v69, v57
	v_cvt_i32_f32_e32 v68, v68
	v_exp_f32_e32 v57, v57
	s_mov_b32 s3, 0xc2ce8ed0
	v_cmp_ngt_f32_e32 vcc, s3, v41
	s_mov_b32 s3, 0x42b17218
	v_ldexp_f32 v57, v57, v68
	v_cndmask_b32_e32 v57, 0, v57, vcc
	v_cmp_nlt_f32_e32 vcc, s3, v41
	s_nop 1
	v_cndmask_b32_e32 v41, v194, v57, vcc
	v_add_f32_e32 v41, 1.0, v41
	v_rcp_f32_e32 v41, v41
	s_nop 0
	v_fma_f32 v41, v41, -2.0, 1.0

; #define LAS __attribute__((address_space(3)))
; #define WAVE_SYNC() asm volatile("s_waitcnt lgkmcnt(0)" ::: "memory")
; template <int PASS>
; __device__ __forceinline__ void s5_scan(const Params& p, int l, int widx, int nw, int beff, int nblk, int lane, LAS unsigned char* lds) {
;     ...
;         for (int bt = 0; bt < 16; ++bt) {
;             LAS float* ubc = ub + (bt & 1) * 256;
;             *(LAS f32x4*)(ubc + lane * 4) = un;
;             if (bt + 1 < 16) un = *(const f32x4*)(ZS + (size_t)(m0 + (bt + 1) * 16 + (lane >> 2)) * 512 + g * 16 + (lane & 3) * 4);
;             WAVE_SYNC();
; #pragma unroll 4
;             for (int s = 0; s < 16; ++s) {
;                 const f32x4 u0 = *(LAS f32x4*)(ubc + s * 16), u1 = *(LAS f32x4*)(ubc + s * 16 + 4), u2 = *(LAS f32x4*)(ubc + s * 16 + 8), u3 = *(LAS f32x4*)(ubc + s * 16 + 12);
;                 float bur = 0.f, bui = 0.f;
; #pragma unroll
;                 for (int j = 0; j < 4; ++j) { bur += br[j] * u0[j]; bui += bi[j] * u0[j]; }
; #pragma unroll
;                 for (int j = 0; j < 4; ++j) { bur += br[4 + j] * u1[j]; bui += bi[4 + j] * u1[j]; }
; #pragma unroll
;                 for (int j = 0; j < 4; ++j) { bur += br[8 + j] * u2[j]; bui += bi[8 + j] * u2[j]; }
; #pragma unroll
;                 for (int j = 0; j < 4; ++j) { bur += br[12 + j] * u3[j]; bui += bi[12 + j] * u3[j]; }
;                 const float nxr = ar * xr - ai * xi + bur, nxi = ar * xi + ai * xr + bui; xr = nxr; xi = nxi;
;                 if (PASS == 2) { xb[s * 132 + lane] = xr; xb[s * 132 + 64 + lane] = xi; }
;             }
.LBB0_392:
	s_add_i32 s8, s5, s7
	v_mov_b32_e32 v45, s8
	ds_read_b128 v[52:55], v45
	ds_read_b128 v[56:59], v45 offset:16
	ds_read_b128 v[60:63], v45 offset:32
	ds_read_b128 v[64:67], v45 offset:48
	s_addk_i32 s7, 0x100
	s_waitcnt lgkmcnt(0)
	v_pk_fma_f32 v[68:69], v[4:5], v[52:53], 0 op_sel_hi:[1,0,0]
	s_cmpk_eq_i32 s7, 0x400
	v_pk_fma_f32 v[52:53], v[6:7], v[52:53], v[68:69] op_sel:[0,1,0]
	s_nop 0
	v_pk_fma_f32 v[52:53], v[8:9], v[54:55], v[52:53] op_sel_hi:[1,0,1]
	v_mov_b32_e32 v54, v55
	v_pk_fma_f32 v[52:53], v[10:11], v[54:55], v[52:53] op_sel_hi:[1,0,1]
	v_mov_b32_e32 v54, v59
	v_pk_fma_f32 v[52:53], v[12:13], v[56:57], v[52:53] op_sel_hi:[1,0,1]
	s_nop 0
	v_pk_fma_f32 v[52:53], v[14:15], v[56:57], v[52:53] op_sel:[0,1,0]
	s_nop 0
	v_pk_fma_f32 v[52:53], v[0:1], v[58:59], v[52:53] op_sel_hi:[1,0,1]
	s_nop 0
	v_pk_fma_f32 v[52:53], v[2:3], v[54:55], v[52:53] op_sel_hi:[1,0,1]
	v_mov_b32_e32 v54, v63
	v_pk_fma_f32 v[70:71], v[16:17], v[60:61], 0 op_sel_hi:[1,0,0]
	s_nop 0
	v_pk_fma_f32 v[70:71], v[18:19], v[60:61], v[70:71] op_sel:[0,1,0]
	s_nop 0
	v_pk_fma_f32 v[70:71], v[20:21], v[62:63], v[70:71] op_sel_hi:[1,0,1]
	s_nop 0
	v_pk_fma_f32 v[70:71], v[22:23], v[54:55], v[70:71] op_sel_hi:[1,0,1]
	v_mov_b32_e32 v54, v67
	v_pk_fma_f32 v[70:71], v[24:25], v[64:65], v[70:71] op_sel_hi:[1,0,1]
	s_nop 0
	v_pk_fma_f32 v[70:71], v[26:27], v[64:65], v[70:71] op_sel:[0,1,0]
	s_nop 0
	v_pk_fma_f32 v[70:71], v[28:29], v[66:67], v[70:71] op_sel_hi:[1,0,1]
	s_nop 0
	v_pk_fma_f32 v[70:71], v[30:31], v[54:55], v[70:71] op_sel_hi:[1,0,1]
	s_nop 0
	v_pk_add_f32 v[52:53], v[52:53], v[70:71]
	v_pk_mul_f32 v[54:55], v[40:41], v[48:49] op_sel_hi:[1,0]
	s_nop 0
	v_pk_fma_f32 v[56:57], v[38:39], v[42:43], v[54:55] neg_lo:[0,0,1] neg_hi:[0,0,1]
	v_pk_fma_f32 v[42:43], v[38:39], v[42:43], v[54:55] op_sel_hi:[1,0,1]
	s_nop 0
	v_mov_b32_e32 v57, v43
	v_pk_add_f32 v[42:43], v[56:57], v[52:53]
	ds_read_b128 v[52:55], v45 offset:64
	ds_read_b128 v[56:59], v45 offset:80
	ds_read_b128 v[60:63], v45 offset:96
	ds_read_b128 v[64:67], v45 offset:112
	s_waitcnt lgkmcnt(3)
	v_pk_fma_f32 v[68:69], v[4:5], v[52:53], 0 op_sel_hi:[1,0,0]
	s_nop 0
	v_pk_fma_f32 v[52:53], v[6:7], v[52:53], v[68:69] op_sel:[0,1,0]
	v_mov_b32_e32 v48, v55
	v_pk_fma_f32 v[52:53], v[8:9], v[54:55], v[52:53] op_sel_hi:[1,0,1]
	v_pk_mul_f32 v[54:55], v[40:41], v[42:43] op_sel:[0,1]
	v_pk_fma_f32 v[52:53], v[10:11], v[48:49], v[52:53] op_sel_hi:[1,0,1]
	s_waitcnt lgkmcnt(2)
	v_mov_b32_e32 v48, v59
	v_pk_fma_f32 v[52:53], v[12:13], v[56:57], v[52:53] op_sel_hi:[1,0,1]
	s_nop 0
	v_pk_fma_f32 v[52:53], v[14:15], v[56:57], v[52:53] op_sel:[0,1,0]
	v_pk_fma_f32 v[56:57], v[38:39], v[42:43], v[54:55] neg_lo:[0,0,1] neg_hi:[0,0,1]
	v_pk_fma_f32 v[52:53], v[0:1], v[58:59], v[52:53] op_sel_hi:[1,0,1]
	v_pk_fma_f32 v[42:43], v[38:39], v[42:43], v[54:55] op_sel_hi:[1,0,1]
	v_pk_fma_f32 v[52:53], v[2:3], v[48:49], v[52:53] op_sel_hi:[1,0,1]
	s_waitcnt lgkmcnt(1)
	v_mov_b32_e32 v48, v63
	v_pk_fma_f32 v[70:71], v[16:17], v[60:61], 0 op_sel_hi:[1,0,0]
	v_mov_b32_e32 v57, v43
	v_pk_fma_f32 v[70:71], v[18:19], v[60:61], v[70:71] op_sel:[0,1,0]
	s_nop 0
	v_pk_fma_f32 v[70:71], v[20:21], v[62:63], v[70:71] op_sel_hi:[1,0,1]
	s_nop 0
	v_pk_fma_f32 v[70:71], v[22:23], v[48:49], v[70:71] op_sel_hi:[1,0,1]
	s_waitcnt lgkmcnt(0)
	v_mov_b32_e32 v48, v67
	v_pk_fma_f32 v[70:71], v[24:25], v[64:65], v[70:71] op_sel_hi:[1,0,1]
	s_nop 0
	v_pk_fma_f32 v[70:71], v[26:27], v[64:65], v[70:71] op_sel:[0,1,0]
	s_nop 0
	v_pk_fma_f32 v[70:71], v[28:29], v[66:67], v[70:71] op_sel_hi:[1,0,1]
	s_nop 0
	v_pk_fma_f32 v[70:71], v[30:31], v[48:49], v[70:71] op_sel_hi:[1,0,1]
	s_nop 0
	v_pk_add_f32 v[52:53], v[52:53], v[70:71]
	s_nop 0
	v_pk_add_f32 v[42:43], v[56:57], v[52:53]
	ds_read_b128 v[52:55], v45 offset:128
	ds_read_b128 v[56:59], v45 offset:144
	ds_read_b128 v[60:63], v45 offset:160
	ds_read_b128 v[64:67], v45 offset:176
	s_waitcnt lgkmcnt(3)
	v_pk_fma_f32 v[68:69], v[4:5], v[52:53], 0 op_sel_hi:[1,0,0]
	s_nop 0
	v_pk_fma_f32 v[52:53], v[6:7], v[52:53], v[68:69] op_sel:[0,1,0]
	v_mov_b32_e32 v48, v55
	v_pk_fma_f32 v[52:53], v[8:9], v[54:55], v[52:53] op_sel_hi:[1,0,1]
	v_pk_mul_f32 v[54:55], v[40:41], v[42:43] op_sel:[0,1]
	v_pk_fma_f32 v[52:53], v[10:11], v[48:49], v[52:53] op_sel_hi:[1,0,1]
	s_waitcnt lgkmcnt(2)
	v_mov_b32_e32 v48, v59
	v_pk_fma_f32 v[52:53], v[12:13], v[56:57], v[52:53] op_sel_hi:[1,0,1]
	s_nop 0
	v_pk_fma_f32 v[52:53], v[14:15], v[56:57], v[52:53] op_sel:[0,1,0]
	v_pk_fma_f32 v[56:57], v[38:39], v[42:43], v[54:55] neg_lo:[0,0,1] neg_hi:[0,0,1]
	v_pk_fma_f32 v[52:53], v[0:1], v[58:59], v[52:53] op_sel_hi:[1,0,1]
	v_pk_fma_f32 v[42:43], v[38:39], v[42:43], v[54:55] op_sel_hi:[1,0,1]
	v_pk_fma_f32 v[52:53], v[2:3], v[48:49], v[52:53] op_sel_hi:[1,0,1]
	s_waitcnt lgkmcnt(1)
	v_mov_b32_e32 v48, v63
	v_pk_fma_f32 v[70:71], v[16:17], v[60:61], 0 op_sel_hi:[1,0,0]
	v_mov_b32_e32 v57, v43
	v_pk_fma_f32 v[70:71], v[18:19], v[60:61], v[70:71] op_sel:[0,1,0]
	s_nop 0
	v_pk_fma_f32 v[70:71], v[20:21], v[62:63], v[70:71] op_sel_hi:[1,0,1]
	s_nop 0
	v_pk_fma_f32 v[70:71], v[22:23], v[48:49], v[70:71] op_sel_hi:[1,0,1]
	s_waitcnt lgkmcnt(0)
	v_mov_b32_e32 v48, v67
	v_pk_fma_f32 v[70:71], v[24:25], v[64:65], v[70:71] op_sel_hi:[1,0,1]
	s_nop 0
	v_pk_fma_f32 v[70:71], v[26:27], v[64:65], v[70:71] op_sel:[0,1,0]
	s_nop 0
	v_pk_fma_f32 v[70:71], v[28:29], v[66:67], v[70:71] op_sel_hi:[1,0,1]
	s_nop 0
	v_pk_fma_f32 v[70:71], v[30:31], v[48:49], v[70:71] op_sel_hi:[1,0,1]
	s_nop 0
	v_pk_add_f32 v[52:53], v[52:53], v[70:71]
	s_nop 0
	v_pk_add_f32 v[42:43], v[56:57], v[52:53]
	ds_read_b128 v[52:55], v45 offset:192
	ds_read_b128 v[56:59], v45 offset:208
	ds_read_b128 v[60:63], v45 offset:224
	ds_read_b128 v[64:67], v45 offset:240
	s_waitcnt lgkmcnt(3)
; #define LAS __attribute__((address_space(3)))
; #define WAVE_SYNC() asm volatile("s_waitcnt lgkmcnt(0)" ::: "memory")
; template <int PASS>
; __device__ __forceinline__ void s5_scan(const Params& p, int l, int widx, int nw, int beff, int nblk, int lane, LAS unsigned char* lds) {
;     ...
;         for (int bt = 0; bt < 16; ++bt) {
;             LAS float* ubc = ub + (bt & 1) * 256;
;             *(LAS f32x4*)(ubc + lane * 4) = un;
;             if (bt + 1 < 16) un = *(const f32x4*)(ZS + (size_t)(m0 + (bt + 1) * 16 + (lane >> 2)) * 512 + g * 16 + (lane & 3) * 4);
;             WAVE_SYNC();
; #pragma unroll 4
;             for (int s = 0; s < 16; ++s) {
;                 const f32x4 u0 = *(LAS f32x4*)(ubc + s * 16), u1 = *(LAS f32x4*)(ubc + s * 16 + 4), u2 = *(LAS f32x4*)(ubc + s * 16 + 8), u3 = *(LAS f32x4*)(ubc + s * 16 + 12);
;                 float bur = 0.f, bui = 0.f;
; #pragma unroll
;                 for (int j = 0; j < 4; ++j) { bur += br[j] * u0[j]; bui += bi[j] * u0[j]; }
; #pragma unroll
;                 for (int j = 0; j < 4; ++j) { bur += br[4 + j] * u1[j]; bui += bi[4 + j] * u1[j]; }
; #pragma unroll
;                 for (int j = 0; j < 4; ++j) { bur += br[8 + j] * u2[j]; bui += bi[8 + j] * u2[j]; }
; #pragma unroll
;                 for (int j = 0; j < 4; ++j) { bur += br[12 + j] * u3[j]; bui += bi[12 + j] * u3[j]; }
;                 const float nxr = ar * xr - ai * xi + bur, nxi = ar * xi + ai * xr + bui; xr = nxr; xi = nxi;
;                 if (PASS == 2) { xb[s * 132 + lane] = xr; xb[s * 132 + 64 + lane] = xi; }
;             }
	v_pk_fma_f32 v[68:69], v[4:5], v[52:53], 0 op_sel_hi:[1,0,0]
	s_nop 0
	v_pk_fma_f32 v[52:53], v[6:7], v[52:53], v[68:69] op_sel:[0,1,0]
	v_mov_b32_e32 v48, v55
	v_pk_fma_f32 v[52:53], v[8:9], v[54:55], v[52:53] op_sel_hi:[1,0,1]
	v_pk_mul_f32 v[54:55], v[40:41], v[42:43] op_sel:[0,1]
	v_pk_fma_f32 v[52:53], v[10:11], v[48:49], v[52:53] op_sel_hi:[1,0,1]
	s_waitcnt lgkmcnt(2)
	v_mov_b32_e32 v48, v59
	v_pk_fma_f32 v[52:53], v[12:13], v[56:57], v[52:53] op_sel_hi:[1,0,1]
	s_nop 0
	v_pk_fma_f32 v[52:53], v[14:15], v[56:57], v[52:53] op_sel:[0,1,0]
	v_pk_fma_f32 v[56:57], v[38:39], v[42:43], v[54:55] neg_lo:[0,0,1] neg_hi:[0,0,1]
	v_pk_fma_f32 v[52:53], v[0:1], v[58:59], v[52:53] op_sel_hi:[1,0,1]
	v_pk_fma_f32 v[42:43], v[38:39], v[42:43], v[54:55] op_sel_hi:[1,0,1]
	v_pk_fma_f32 v[52:53], v[2:3], v[48:49], v[52:53] op_sel_hi:[1,0,1]
	s_waitcnt lgkmcnt(1)
	v_mov_b32_e32 v48, v63
	v_pk_fma_f32 v[70:71], v[16:17], v[60:61], 0 op_sel_hi:[1,0,0]
	v_mov_b32_e32 v57, v43
	v_pk_fma_f32 v[70:71], v[18:19], v[60:61], v[70:71] op_sel:[0,1,0]
	s_nop 0
	v_pk_fma_f32 v[70:71], v[20:21], v[62:63], v[70:71] op_sel_hi:[1,0,1]
	s_nop 0
	v_pk_fma_f32 v[70:71], v[22:23], v[48:49], v[70:71] op_sel_hi:[1,0,1]
	s_waitcnt lgkmcnt(0)
	v_mov_b32_e32 v48, v67
	v_pk_fma_f32 v[70:71], v[24:25], v[64:65], v[70:71] op_sel_hi:[1,0,1]
	s_nop 0
	v_pk_fma_f32 v[70:71], v[26:27], v[64:65], v[70:71] op_sel:[0,1,0]
	s_nop 0
	v_pk_fma_f32 v[70:71], v[28:29], v[66:67], v[70:71] op_sel_hi:[1,0,1]
	s_nop 0
	v_pk_fma_f32 v[70:71], v[30:31], v[48:49], v[70:71] op_sel_hi:[1,0,1]
	s_nop 0
	v_pk_add_f32 v[52:53], v[52:53], v[70:71]
	s_nop 0
	v_pk_add_f32 v[42:43], v[56:57], v[52:53]
	s_nop 0
	v_mov_b32_e32 v48, v43
	s_cbranch_scc0 .LBB0_392
	s_waitcnt vmcnt(0)
	ds_write_b128 v51, v[32:35] offset:1024
	v_or_b32_e32 v32, 32, v44
	v_ashrrev_i32_e32 v33, 31, v32
	v_lshlrev_b64 v[32:33], 11, v[32:33]
	v_lshl_add_u64 v[32:33], v[46:47], 0, v[32:33]
	global_load_dwordx4 v[32:35], v[32:33], off
	s_waitcnt lgkmcnt(0)
	s_mov_b32 s7, 0
.LBB0_394:
	s_add_i32 s8, s6, s7
	v_mov_b32_e32 v45, s8
	ds_read_b128 v[52:55], v45
	ds_read_b128 v[56:59], v45 offset:16
	ds_read_b128 v[60:63], v45 offset:32
	ds_read_b128 v[64:67], v45 offset:48
	s_addk_i32 s7, 0x100
	s_waitcnt lgkmcnt(3)
	v_pk_fma_f32 v[68:69], v[4:5], v[52:53], 0 op_sel_hi:[1,0,0]
	v_mov_b32_e32 v48, v55
	v_pk_fma_f32 v[52:53], v[6:7], v[52:53], v[68:69] op_sel:[0,1,0]
	s_cmpk_lg_i32 s7, 0x400
	v_pk_fma_f32 v[52:53], v[8:9], v[54:55], v[52:53] op_sel_hi:[1,0,1]
	v_pk_mul_f32 v[54:55], v[40:41], v[42:43] op_sel:[0,1]
	v_pk_fma_f32 v[52:53], v[10:11], v[48:49], v[52:53] op_sel_hi:[1,0,1]
	s_waitcnt lgkmcnt(2)
	v_mov_b32_e32 v48, v59
	v_pk_fma_f32 v[52:53], v[12:13], v[56:57], v[52:53] op_sel_hi:[1,0,1]
	s_nop 0
	v_pk_fma_f32 v[52:53], v[14:15], v[56:57], v[52:53] op_sel:[0,1,0]
	v_pk_fma_f32 v[56:57], v[38:39], v[42:43], v[54:55] neg_lo:[0,0,1] neg_hi:[0,0,1]
	v_pk_fma_f32 v[52:53], v[0:1], v[58:59], v[52:53] op_sel_hi:[1,0,1]
	v_pk_fma_f32 v[42:43], v[38:39], v[42:43], v[54:55] op_sel_hi:[1,0,1]
	v_pk_fma_f32 v[52:53], v[2:3], v[48:49], v[52:53] op_sel_hi:[1,0,1]
	s_waitcnt lgkmcnt(1)
	v_mov_b32_e32 v48, v63
	v_pk_fma_f32 v[70:71], v[16:17], v[60:61], 0 op_sel_hi:[1,0,0]
	v_mov_b32_e32 v57, v43
	v_pk_fma_f32 v[70:71], v[18:19], v[60:61], v[70:71] op_sel:[0,1,0]
	s_nop 0
	v_pk_fma_f32 v[70:71], v[20:21], v[62:63], v[70:71] op_sel_hi:[1,0,1]
	s_nop 0
	v_pk_fma_f32 v[70:71], v[22:23], v[48:49], v[70:71] op_sel_hi:[1,0,1]
	s_waitcnt lgkmcnt(0)
	v_mov_b32_e32 v48, v67
	v_pk_fma_f32 v[70:71], v[24:25], v[64:65], v[70:71] op_sel_hi:[1,0,1]
	s_nop 0
	v_pk_fma_f32 v[70:71], v[26:27], v[64:65], v[70:71] op_sel:[0,1,0]
	s_nop 0
	v_pk_fma_f32 v[70:71], v[28:29], v[66:67], v[70:71] op_sel_hi:[1,0,1]
	s_nop 0
	v_pk_fma_f32 v[70:71], v[30:31], v[48:49], v[70:71] op_sel_hi:[1,0,1]
	s_nop 0
	v_pk_add_f32 v[52:53], v[52:53], v[70:71]
	s_nop 0
	v_pk_add_f32 v[42:43], v[56:57], v[52:53]
	ds_read_b128 v[52:55], v45 offset:64
	ds_read_b128 v[56:59], v45 offset:80
	ds_read_b128 v[60:63], v45 offset:96
	ds_read_b128 v[64:67], v45 offset:112
	s_waitcnt lgkmcnt(3)
	v_pk_fma_f32 v[68:69], v[4:5], v[52:53], 0 op_sel_hi:[1,0,0]
	s_nop 0
	v_pk_fma_f32 v[52:53], v[6:7], v[52:53], v[68:69] op_sel:[0,1,0]
	v_mov_b32_e32 v48, v55
	v_pk_fma_f32 v[52:53], v[8:9], v[54:55], v[52:53] op_sel_hi:[1,0,1]
	v_pk_mul_f32 v[54:55], v[40:41], v[42:43] op_sel:[0,1]
	v_pk_fma_f32 v[52:53], v[10:11], v[48:49], v[52:53] op_sel_hi:[1,0,1]
	s_waitcnt lgkmcnt(2)
	v_mov_b32_e32 v48, v59
	v_pk_fma_f32 v[52:53], v[12:13], v[56:57], v[52:53] op_sel_hi:[1,0,1]
	s_nop 0
	v_pk_fma_f32 v[52:53], v[14:15], v[56:57], v[52:53] op_sel:[0,1,0]
	v_pk_fma_f32 v[56:57], v[38:39], v[42:43], v[54:55] neg_lo:[0,0,1] neg_hi:[0,0,1]
	v_pk_fma_f32 v[52:53], v[0:1], v[58:59], v[52:53] op_sel_hi:[1,0,1]
	v_pk_fma_f32 v[42:43], v[38:39], v[42:43], v[54:55] op_sel_hi:[1,0,1]
	v_pk_fma_f32 v[52:53], v[2:3], v[48:49], v[52:53] op_sel_hi:[1,0,1]
	s_waitcnt lgkmcnt(1)
	v_mov_b32_e32 v48, v63
	v_pk_fma_f32 v[70:71], v[16:17], v[60:61], 0 op_sel_hi:[1,0,0]
	v_mov_b32_e32 v57, v43
	v_pk_fma_f32 v[70:71], v[18:19], v[60:61], v[70:71] op_sel:[0,1,0]
	s_nop 0
	v_pk_fma_f32 v[70:71], v[20:21], v[62:63], v[70:71] op_sel_hi:[1,0,1]
	s_nop 0
	v_pk_fma_f32 v[70:71], v[22:23], v[48:49], v[70:71] op_sel_hi:[1,0,1]
	s_waitcnt lgkmcnt(0)
; #define LAS __attribute__((address_space(3)))
; #define WAVE_SYNC() asm volatile("s_waitcnt lgkmcnt(0)" ::: "memory")
; template <int PASS>
; __device__ __forceinline__ void s5_scan(const Params& p, int l, int widx, int nw, int beff, int nblk, int lane, LAS unsigned char* lds) {
;     ...
;         for (int bt = 0; bt < 16; ++bt) {
;             LAS float* ubc = ub + (bt & 1) * 256;
;             *(LAS f32x4*)(ubc + lane * 4) = un;
;             if (bt + 1 < 16) un = *(const f32x4*)(ZS + (size_t)(m0 + (bt + 1) * 16 + (lane >> 2)) * 512 + g * 16 + (lane & 3) * 4);
;             WAVE_SYNC();
; #pragma unroll 4
;             for (int s = 0; s < 16; ++s) {
;                 const f32x4 u0 = *(LAS f32x4*)(ubc + s * 16), u1 = *(LAS f32x4*)(ubc + s * 16 + 4), u2 = *(LAS f32x4*)(ubc + s * 16 + 8), u3 = *(LAS f32x4*)(ubc + s * 16 + 12);
;                 float bur = 0.f, bui = 0.f;
; #pragma unroll
;                 for (int j = 0; j < 4; ++j) { bur += br[j] * u0[j]; bui += bi[j] * u0[j]; }
; #pragma unroll
;                 for (int j = 0; j < 4; ++j) { bur += br[4 + j] * u1[j]; bui += bi[4 + j] * u1[j]; }
; #pragma unroll
;                 for (int j = 0; j < 4; ++j) { bur += br[8 + j] * u2[j]; bui += bi[8 + j] * u2[j]; }
; #pragma unroll
;                 for (int j = 0; j < 4; ++j) { bur += br[12 + j] * u3[j]; bui += bi[12 + j] * u3[j]; }
;                 const float nxr = ar * xr - ai * xi + bur, nxi = ar * xi + ai * xr + bui; xr = nxr; xi = nxi;
;                 if (PASS == 2) { xb[s * 132 + lane] = xr; xb[s * 132 + 64 + lane] = xi; }
;             }
	v_mov_b32_e32 v48, v67
	v_pk_fma_f32 v[70:71], v[24:25], v[64:65], v[70:71] op_sel_hi:[1,0,1]
	s_nop 0
	v_pk_fma_f32 v[70:71], v[26:27], v[64:65], v[70:71] op_sel:[0,1,0]
	s_nop 0
	v_pk_fma_f32 v[70:71], v[28:29], v[66:67], v[70:71] op_sel_hi:[1,0,1]
	s_nop 0
	v_pk_fma_f32 v[70:71], v[30:31], v[48:49], v[70:71] op_sel_hi:[1,0,1]
	s_nop 0
	v_pk_add_f32 v[52:53], v[52:53], v[70:71]
	s_nop 0
	v_pk_add_f32 v[42:43], v[56:57], v[52:53]
	ds_read_b128 v[52:55], v45 offset:128
	ds_read_b128 v[56:59], v45 offset:144
	ds_read_b128 v[60:63], v45 offset:160
	ds_read_b128 v[64:67], v45 offset:176
	s_waitcnt lgkmcnt(3)
	v_pk_fma_f32 v[68:69], v[4:5], v[52:53], 0 op_sel_hi:[1,0,0]
	s_nop 0
	v_pk_fma_f32 v[52:53], v[6:7], v[52:53], v[68:69] op_sel:[0,1,0]
	v_mov_b32_e32 v48, v55
	v_pk_fma_f32 v[52:53], v[8:9], v[54:55], v[52:53] op_sel_hi:[1,0,1]
	v_pk_mul_f32 v[54:55], v[40:41], v[42:43] op_sel:[0,1]
	v_pk_fma_f32 v[52:53], v[10:11], v[48:49], v[52:53] op_sel_hi:[1,0,1]
	s_waitcnt lgkmcnt(2)
	v_mov_b32_e32 v48, v59
	v_pk_fma_f32 v[52:53], v[12:13], v[56:57], v[52:53] op_sel_hi:[1,0,1]
	s_nop 0
	v_pk_fma_f32 v[52:53], v[14:15], v[56:57], v[52:53] op_sel:[0,1,0]
	v_pk_fma_f32 v[56:57], v[38:39], v[42:43], v[54:55] neg_lo:[0,0,1] neg_hi:[0,0,1]
	v_pk_fma_f32 v[52:53], v[0:1], v[58:59], v[52:53] op_sel_hi:[1,0,1]
	v_pk_fma_f32 v[42:43], v[38:39], v[42:43], v[54:55] op_sel_hi:[1,0,1]
	v_pk_fma_f32 v[52:53], v[2:3], v[48:49], v[52:53] op_sel_hi:[1,0,1]
	s_waitcnt lgkmcnt(1)
	v_mov_b32_e32 v48, v63
	v_pk_fma_f32 v[70:71], v[16:17], v[60:61], 0 op_sel_hi:[1,0,0]
	v_mov_b32_e32 v57, v43
	v_pk_fma_f32 v[70:71], v[18:19], v[60:61], v[70:71] op_sel:[0,1,0]
	s_nop 0
	v_pk_fma_f32 v[70:71], v[20:21], v[62:63], v[70:71] op_sel_hi:[1,0,1]
	s_nop 0
	v_pk_fma_f32 v[70:71], v[22:23], v[48:49], v[70:71] op_sel_hi:[1,0,1]
	s_waitcnt lgkmcnt(0)
	v_mov_b32_e32 v48, v67
	v_pk_fma_f32 v[70:71], v[24:25], v[64:65], v[70:71] op_sel_hi:[1,0,1]
	s_nop 0
	v_pk_fma_f32 v[70:71], v[26:27], v[64:65], v[70:71] op_sel:[0,1,0]
	s_nop 0
	v_pk_fma_f32 v[70:71], v[28:29], v[66:67], v[70:71] op_sel_hi:[1,0,1]
	s_nop 0
	v_pk_fma_f32 v[70:71], v[30:31], v[48:49], v[70:71] op_sel_hi:[1,0,1]
	s_nop 0
	v_pk_add_f32 v[52:53], v[52:53], v[70:71]
	s_nop 0
	v_pk_add_f32 v[42:43], v[56:57], v[52:53]
	ds_read_b128 v[52:55], v45 offset:192
	ds_read_b128 v[56:59], v45 offset:208
	ds_read_b128 v[60:63], v45 offset:224
	ds_read_b128 v[64:67], v45 offset:240
	s_waitcnt lgkmcnt(3)
	v_pk_fma_f32 v[68:69], v[4:5], v[52:53], 0 op_sel_hi:[1,0,0]
	s_nop 0
	v_pk_fma_f32 v[52:53], v[6:7], v[52:53], v[68:69] op_sel:[0,1,0]
	v_mov_b32_e32 v48, v55
	v_pk_fma_f32 v[52:53], v[8:9], v[54:55], v[52:53] op_sel_hi:[1,0,1]
	v_pk_mul_f32 v[54:55], v[40:41], v[42:43] op_sel:[0,1]
	v_pk_fma_f32 v[52:53], v[10:11], v[48:49], v[52:53] op_sel_hi:[1,0,1]
	s_waitcnt lgkmcnt(2)
	v_mov_b32_e32 v48, v59
	v_pk_fma_f32 v[52:53], v[12:13], v[56:57], v[52:53] op_sel_hi:[1,0,1]
	s_nop 0
	v_pk_fma_f32 v[52:53], v[14:15], v[56:57], v[52:53] op_sel:[0,1,0]
	v_pk_fma_f32 v[56:57], v[38:39], v[42:43], v[54:55] neg_lo:[0,0,1] neg_hi:[0,0,1]
	v_pk_fma_f32 v[52:53], v[0:1], v[58:59], v[52:53] op_sel_hi:[1,0,1]
	v_pk_fma_f32 v[42:43], v[38:39], v[42:43], v[54:55] op_sel_hi:[1,0,1]
	v_pk_fma_f32 v[52:53], v[2:3], v[48:49], v[52:53] op_sel_hi:[1,0,1]
	s_waitcnt lgkmcnt(1)
	v_mov_b32_e32 v48, v63
	v_pk_fma_f32 v[70:71], v[16:17], v[60:61], 0 op_sel_hi:[1,0,0]
	v_mov_b32_e32 v57, v43
	v_pk_fma_f32 v[70:71], v[18:19], v[60:61], v[70:71] op_sel:[0,1,0]
	s_nop 0
	v_pk_fma_f32 v[70:71], v[20:21], v[62:63], v[70:71] op_sel_hi:[1,0,1]
	s_nop 0
	v_pk_fma_f32 v[70:71], v[22:23], v[48:49], v[70:71] op_sel_hi:[1,0,1]
	s_waitcnt lgkmcnt(0)
	v_mov_b32_e32 v48, v67
	v_pk_fma_f32 v[70:71], v[24:25], v[64:65], v[70:71] op_sel_hi:[1,0,1]
	s_nop 0
	v_pk_fma_f32 v[70:71], v[26:27], v[64:65], v[70:71] op_sel:[0,1,0]
	s_nop 0
	v_pk_fma_f32 v[70:71], v[28:29], v[66:67], v[70:71] op_sel_hi:[1,0,1]
	s_nop 0
	v_pk_fma_f32 v[70:71], v[30:31], v[48:49], v[70:71] op_sel_hi:[1,0,1]
	s_nop 0
	v_pk_add_f32 v[52:53], v[52:53], v[70:71]
	s_nop 0
	v_pk_add_f32 v[42:43], v[56:57], v[52:53]
	s_cbranch_scc1 .LBB0_394
	s_waitcnt vmcnt(0)
	ds_write_b128 v51, v[32:35]
	v_or_b32_e32 v32, 48, v44
	v_ashrrev_i32_e32 v33, 31, v32
	v_lshlrev_b64 v[32:33], 11, v[32:33]
	v_lshl_add_u64 v[32:33], v[46:47], 0, v[32:33]
	global_load_dwordx4 v[32:35], v[32:33], off
	s_waitcnt lgkmcnt(0)
	s_mov_b32 s7, 0
; #define LAS __attribute__((address_space(3)))
; #define WAVE_SYNC() asm volatile("s_waitcnt lgkmcnt(0)" ::: "memory")
; template <int PASS>
; __device__ __forceinline__ void s5_scan(const Params& p, int l, int widx, int nw, int beff, int nblk, int lane, LAS unsigned char* lds) {
;     ...
;         for (int bt = 0; bt < 16; ++bt) {
;             LAS float* ubc = ub + (bt & 1) * 256;
;             *(LAS f32x4*)(ubc + lane * 4) = un;
;             if (bt + 1 < 16) un = *(const f32x4*)(ZS + (size_t)(m0 + (bt + 1) * 16 + (lane >> 2)) * 512 + g * 16 + (lane & 3) * 4);
;             WAVE_SYNC();
; #pragma unroll 4
;             for (int s = 0; s < 16; ++s) {
;                 const f32x4 u0 = *(LAS f32x4*)(ubc + s * 16), u1 = *(LAS f32x4*)(ubc + s * 16 + 4), u2 = *(LAS f32x4*)(ubc + s * 16 + 8), u3 = *(LAS f32x4*)(ubc + s * 16 + 12);
;                 float bur = 0.f, bui = 0.f;
; #pragma unroll
;                 for (int j = 0; j < 4; ++j) { bur += br[j] * u0[j]; bui += bi[j] * u0[j]; }
; #pragma unroll
;                 for (int j = 0; j < 4; ++j) { bur += br[4 + j] * u1[j]; bui += bi[4 + j] * u1[j]; }
; #pragma unroll
;                 for (int j = 0; j < 4; ++j) { bur += br[8 + j] * u2[j]; bui += bi[8 + j] * u2[j]; }
; #pragma unroll
;                 for (int j = 0; j < 4; ++j) { bur += br[12 + j] * u3[j]; bui += bi[12 + j] * u3[j]; }
;                 const float nxr = ar * xr - ai * xi + bur, nxi = ar * xi + ai * xr + bui; xr = nxr; xi = nxi;
;                 if (PASS == 2) { xb[s * 132 + lane] = xr; xb[s * 132 + 64 + lane] = xi; }
;             }
.LBB0_396:
	s_add_i32 s8, s5, s7
	v_mov_b32_e32 v45, s8
	ds_read_b128 v[52:55], v45
	ds_read_b128 v[56:59], v45 offset:16
	ds_read_b128 v[60:63], v45 offset:32
	ds_read_b128 v[64:67], v45 offset:48
	s_addk_i32 s7, 0x100
	s_waitcnt lgkmcnt(3)
	v_pk_fma_f32 v[68:69], v[4:5], v[52:53], 0 op_sel_hi:[1,0,0]
	v_mov_b32_e32 v48, v55
	v_pk_fma_f32 v[52:53], v[6:7], v[52:53], v[68:69] op_sel:[0,1,0]
	s_cmpk_lg_i32 s7, 0x400
	v_pk_fma_f32 v[52:53], v[8:9], v[54:55], v[52:53] op_sel_hi:[1,0,1]
	v_pk_mul_f32 v[54:55], v[40:41], v[42:43] op_sel:[0,1]
	v_pk_fma_f32 v[52:53], v[10:11], v[48:49], v[52:53] op_sel_hi:[1,0,1]
	s_waitcnt lgkmcnt(2)
	v_mov_b32_e32 v48, v59
	v_pk_fma_f32 v[52:53], v[12:13], v[56:57], v[52:53] op_sel_hi:[1,0,1]
	s_nop 0
	v_pk_fma_f32 v[52:53], v[14:15], v[56:57], v[52:53] op_sel:[0,1,0]
	v_pk_fma_f32 v[56:57], v[38:39], v[42:43], v[54:55] neg_lo:[0,0,1] neg_hi:[0,0,1]
	v_pk_fma_f32 v[52:53], v[0:1], v[58:59], v[52:53] op_sel_hi:[1,0,1]
	v_pk_fma_f32 v[42:43], v[38:39], v[42:43], v[54:55] op_sel_hi:[1,0,1]
	v_pk_fma_f32 v[52:53], v[2:3], v[48:49], v[52:53] op_sel_hi:[1,0,1]
	s_waitcnt lgkmcnt(1)
	v_mov_b32_e32 v48, v63
	v_pk_fma_f32 v[70:71], v[16:17], v[60:61], 0 op_sel_hi:[1,0,0]
	v_mov_b32_e32 v57, v43
	v_pk_fma_f32 v[70:71], v[18:19], v[60:61], v[70:71] op_sel:[0,1,0]
	s_nop 0
	v_pk_fma_f32 v[70:71], v[20:21], v[62:63], v[70:71] op_sel_hi:[1,0,1]
	s_nop 0
	v_pk_fma_f32 v[70:71], v[22:23], v[48:49], v[70:71] op_sel_hi:[1,0,1]
	s_waitcnt lgkmcnt(0)
	v_mov_b32_e32 v48, v67
	v_pk_fma_f32 v[70:71], v[24:25], v[64:65], v[70:71] op_sel_hi:[1,0,1]
	s_nop 0
	v_pk_fma_f32 v[70:71], v[26:27], v[64:65], v[70:71] op_sel:[0,1,0]
	s_nop 0
	v_pk_fma_f32 v[70:71], v[28:29], v[66:67], v[70:71] op_sel_hi:[1,0,1]
	s_nop 0
	v_pk_fma_f32 v[70:71], v[30:31], v[48:49], v[70:71] op_sel_hi:[1,0,1]
	s_nop 0
	v_pk_add_f32 v[52:53], v[52:53], v[70:71]
	s_nop 0
	v_pk_add_f32 v[42:43], v[56:57], v[52:53]
	ds_read_b128 v[52:55], v45 offset:64
	ds_read_b128 v[56:59], v45 offset:80
	ds_read_b128 v[60:63], v45 offset:96
	ds_read_b128 v[64:67], v45 offset:112
	s_waitcnt lgkmcnt(3)
	v_pk_fma_f32 v[68:69], v[4:5], v[52:53], 0 op_sel_hi:[1,0,0]
	s_nop 0
	v_pk_fma_f32 v[52:53], v[6:7], v[52:53], v[68:69] op_sel:[0,1,0]
	v_mov_b32_e32 v48, v55
	v_pk_fma_f32 v[52:53], v[8:9], v[54:55], v[52:53] op_sel_hi:[1,0,1]
	v_pk_mul_f32 v[54:55], v[40:41], v[42:43] op_sel:[0,1]
	v_pk_fma_f32 v[52:53], v[10:11], v[48:49], v[52:53] op_sel_hi:[1,0,1]
	s_waitcnt lgkmcnt(2)
	v_mov_b32_e32 v48, v59
	v_pk_fma_f32 v[52:53], v[12:13], v[56:57], v[52:53] op_sel_hi:[1,0,1]
	s_nop 0
	v_pk_fma_f32 v[52:53], v[14:15], v[56:57], v[52:53] op_sel:[0,1,0]
	v_pk_fma_f32 v[56:57], v[38:39], v[42:43], v[54:55] neg_lo:[0,0,1] neg_hi:[0,0,1]
	v_pk_fma_f32 v[52:53], v[0:1], v[58:59], v[52:53] op_sel_hi:[1,0,1]
	v_pk_fma_f32 v[42:43], v[38:39], v[42:43], v[54:55] op_sel_hi:[1,0,1]
	v_pk_fma_f32 v[52:53], v[2:3], v[48:49], v[52:53] op_sel_hi:[1,0,1]
	s_waitcnt lgkmcnt(1)
	v_mov_b32_e32 v48, v63
	v_pk_fma_f32 v[70:71], v[16:17], v[60:61], 0 op_sel_hi:[1,0,0]
	v_mov_b32_e32 v57, v43
	v_pk_fma_f32 v[70:71], v[18:19], v[60:61], v[70:71] op_sel:[0,1,0]
	s_nop 0
	v_pk_fma_f32 v[70:71], v[20:21], v[62:63], v[70:71] op_sel_hi:[1,0,1]
	s_nop 0
	v_pk_fma_f32 v[70:71], v[22:23], v[48:49], v[70:71] op_sel_hi:[1,0,1]
	s_waitcnt lgkmcnt(0)
	v_mov_b32_e32 v48, v67
	v_pk_fma_f32 v[70:71], v[24:25], v[64:65], v[70:71] op_sel_hi:[1,0,1]
	s_nop 0
	v_pk_fma_f32 v[70:71], v[26:27], v[64:65], v[70:71] op_sel:[0,1,0]
	s_nop 0
	v_pk_fma_f32 v[70:71], v[28:29], v[66:67], v[70:71] op_sel_hi:[1,0,1]
	s_nop 0
	v_pk_fma_f32 v[70:71], v[30:31], v[48:49], v[70:71] op_sel_hi:[1,0,1]
	s_nop 0
	v_pk_add_f32 v[52:53], v[52:53], v[70:71]
	s_nop 0
	v_pk_add_f32 v[42:43], v[56:57], v[52:53]
	ds_read_b128 v[52:55], v45 offset:128
	ds_read_b128 v[56:59], v45 offset:144
	ds_read_b128 v[60:63], v45 offset:160
	ds_read_b128 v[64:67], v45 offset:176
	s_waitcnt lgkmcnt(3)
	v_pk_fma_f32 v[68:69], v[4:5], v[52:53], 0 op_sel_hi:[1,0,0]
	s_nop 0
	v_pk_fma_f32 v[52:53], v[6:7], v[52:53], v[68:69] op_sel:[0,1,0]
	v_mov_b32_e32 v48, v55
	v_pk_fma_f32 v[52:53], v[8:9], v[54:55], v[52:53] op_sel_hi:[1,0,1]
	v_pk_mul_f32 v[54:55], v[40:41], v[42:43] op_sel:[0,1]
	v_pk_fma_f32 v[52:53], v[10:11], v[48:49], v[52:53] op_sel_hi:[1,0,1]
	s_waitcnt lgkmcnt(2)
	v_mov_b32_e32 v48, v59
	v_pk_fma_f32 v[52:53], v[12:13], v[56:57], v[52:53] op_sel_hi:[1,0,1]
	s_nop 0
	v_pk_fma_f32 v[52:53], v[14:15], v[56:57], v[52:53] op_sel:[0,1,0]
	v_pk_fma_f32 v[56:57], v[38:39], v[42:43], v[54:55] neg_lo:[0,0,1] neg_hi:[0,0,1]
	v_pk_fma_f32 v[52:53], v[0:1], v[58:59], v[52:53] op_sel_hi:[1,0,1]
	v_pk_fma_f32 v[42:43], v[38:39], v[42:43], v[54:55] op_sel_hi:[1,0,1]
	v_pk_fma_f32 v[52:53], v[2:3], v[48:49], v[52:53] op_sel_hi:[1,0,1]
	s_waitcnt lgkmcnt(1)
	v_mov_b32_e32 v48, v63
	v_pk_fma_f32 v[70:71], v[16:17], v[60:61], 0 op_sel_hi:[1,0,0]
	v_mov_b32_e32 v57, v43
	v_pk_fma_f32 v[70:71], v[18:19], v[60:61], v[70:71] op_sel:[0,1,0]
	s_nop 0
	v_pk_fma_f32 v[70:71], v[20:21], v[62:63], v[70:71] op_sel_hi:[1,0,1]
	s_nop 0
	v_pk_fma_f32 v[70:71], v[22:23], v[48:49], v[70:71] op_sel_hi:[1,0,1]
	s_waitcnt lgkmcnt(0)
	v_mov_b32_e32 v48, v67
	v_pk_fma_f32 v[70:71], v[24:25], v[64:65], v[70:71] op_sel_hi:[1,0,1]
	s_nop 0
	v_pk_fma_f32 v[70:71], v[26:27], v[64:65], v[70:71] op_sel:[0,1,0]
	s_nop 0
	v_pk_fma_f32 v[70:71], v[28:29], v[66:67], v[70:71] op_sel_hi:[1,0,1]
	s_nop 0
	v_pk_fma_f32 v[70:71], v[30:31], v[48:49], v[70:71] op_sel_hi:[1,0,1]
	s_nop 0
	v_pk_add_f32 v[52:53], v[52:53], v[70:71]
	s_nop 0
	v_pk_add_f32 v[42:43], v[56:57], v[52:53]
	ds_read_b128 v[52:55], v45 offset:192
	ds_read_b128 v[56:59], v45 offset:208
	ds_read_b128 v[60:63], v45 offset:224
	ds_read_b128 v[64:67], v45 offset:240
	s_waitcnt lgkmcnt(3)
; #define LAS __attribute__((address_space(3)))
; #define WAVE_SYNC() asm volatile("s_waitcnt lgkmcnt(0)" ::: "memory")
; template <int PASS>
; __device__ __forceinline__ void s5_scan(const Params& p, int l, int widx, int nw, int beff, int nblk, int lane, LAS unsigned char* lds) {
;     ...
;         for (int bt = 0; bt < 16; ++bt) {
;             LAS float* ubc = ub + (bt & 1) * 256;
;             *(LAS f32x4*)(ubc + lane * 4) = un;
;             if (bt + 1 < 16) un = *(const f32x4*)(ZS + (size_t)(m0 + (bt + 1) * 16 + (lane >> 2)) * 512 + g * 16 + (lane & 3) * 4);
;             WAVE_SYNC();
; #pragma unroll 4
;             for (int s = 0; s < 16; ++s) {
;                 const f32x4 u0 = *(LAS f32x4*)(ubc + s * 16), u1 = *(LAS f32x4*)(ubc + s * 16 + 4), u2 = *(LAS f32x4*)(ubc + s * 16 + 8), u3 = *(LAS f32x4*)(ubc + s * 16 + 12);
;                 float bur = 0.f, bui = 0.f;
; #pragma unroll
;                 for (int j = 0; j < 4; ++j) { bur += br[j] * u0[j]; bui += bi[j] * u0[j]; }
; #pragma unroll
;                 for (int j = 0; j < 4; ++j) { bur += br[4 + j] * u1[j]; bui += bi[4 + j] * u1[j]; }
; #pragma unroll
;                 for (int j = 0; j < 4; ++j) { bur += br[8 + j] * u2[j]; bui += bi[8 + j] * u2[j]; }
; #pragma unroll
;                 for (int j = 0; j < 4; ++j) { bur += br[12 + j] * u3[j]; bui += bi[12 + j] * u3[j]; }
;                 const float nxr = ar * xr - ai * xi + bur, nxi = ar * xi + ai * xr + bui; xr = nxr; xi = nxi;
;                 if (PASS == 2) { xb[s * 132 + lane] = xr; xb[s * 132 + 64 + lane] = xi; }
;             }
	v_pk_fma_f32 v[68:69], v[4:5], v[52:53], 0 op_sel_hi:[1,0,0]
	s_nop 0
	v_pk_fma_f32 v[52:53], v[6:7], v[52:53], v[68:69] op_sel:[0,1,0]
	v_mov_b32_e32 v48, v55
	v_pk_fma_f32 v[52:53], v[8:9], v[54:55], v[52:53] op_sel_hi:[1,0,1]
	v_pk_mul_f32 v[54:55], v[40:41], v[42:43] op_sel:[0,1]
	v_pk_fma_f32 v[52:53], v[10:11], v[48:49], v[52:53] op_sel_hi:[1,0,1]
	s_waitcnt lgkmcnt(2)
	v_mov_b32_e32 v48, v59
	v_pk_fma_f32 v[52:53], v[12:13], v[56:57], v[52:53] op_sel_hi:[1,0,1]
	s_nop 0
	v_pk_fma_f32 v[52:53], v[14:15], v[56:57], v[52:53] op_sel:[0,1,0]
	v_pk_fma_f32 v[56:57], v[38:39], v[42:43], v[54:55] neg_lo:[0,0,1] neg_hi:[0,0,1]
	v_pk_fma_f32 v[52:53], v[0:1], v[58:59], v[52:53] op_sel_hi:[1,0,1]
	v_pk_fma_f32 v[42:43], v[38:39], v[42:43], v[54:55] op_sel_hi:[1,0,1]
	v_pk_fma_f32 v[52:53], v[2:3], v[48:49], v[52:53] op_sel_hi:[1,0,1]
	s_waitcnt lgkmcnt(1)
	v_mov_b32_e32 v48, v63
	v_pk_fma_f32 v[70:71], v[16:17], v[60:61], 0 op_sel_hi:[1,0,0]
	v_mov_b32_e32 v57, v43
	v_pk_fma_f32 v[70:71], v[18:19], v[60:61], v[70:71] op_sel:[0,1,0]
	s_nop 0
	v_pk_fma_f32 v[70:71], v[20:21], v[62:63], v[70:71] op_sel_hi:[1,0,1]
	s_nop 0
	v_pk_fma_f32 v[70:71], v[22:23], v[48:49], v[70:71] op_sel_hi:[1,0,1]
	s_waitcnt lgkmcnt(0)
	v_mov_b32_e32 v48, v67
	v_pk_fma_f32 v[70:71], v[24:25], v[64:65], v[70:71] op_sel_hi:[1,0,1]
	s_nop 0
	v_pk_fma_f32 v[70:71], v[26:27], v[64:65], v[70:71] op_sel:[0,1,0]
	s_nop 0
	v_pk_fma_f32 v[70:71], v[28:29], v[66:67], v[70:71] op_sel_hi:[1,0,1]
	s_nop 0
	v_pk_fma_f32 v[70:71], v[30:31], v[48:49], v[70:71] op_sel_hi:[1,0,1]
	s_nop 0
	v_pk_add_f32 v[52:53], v[52:53], v[70:71]
	s_nop 0
	v_pk_add_f32 v[42:43], v[56:57], v[52:53]
	s_cbranch_scc1 .LBB0_396
	s_waitcnt vmcnt(0)
	ds_write_b128 v51, v[32:35] offset:1024
	v_or_b32_e32 v32, 64, v44
	v_ashrrev_i32_e32 v33, 31, v32
	v_lshlrev_b64 v[32:33], 11, v[32:33]
	v_lshl_add_u64 v[32:33], v[46:47], 0, v[32:33]
	global_load_dwordx4 v[32:35], v[32:33], off
	s_waitcnt lgkmcnt(0)
	s_mov_b32 s7, 0
.LBB0_398:
	s_add_i32 s8, s6, s7
	v_mov_b32_e32 v45, s8
	ds_read_b128 v[52:55], v45
	ds_read_b128 v[56:59], v45 offset:16
	ds_read_b128 v[60:63], v45 offset:32
	ds_read_b128 v[64:67], v45 offset:48
	s_addk_i32 s7, 0x100
	s_waitcnt lgkmcnt(3)
	v_pk_fma_f32 v[68:69], v[4:5], v[52:53], 0 op_sel_hi:[1,0,0]
	v_mov_b32_e32 v48, v55
	v_pk_fma_f32 v[52:53], v[6:7], v[52:53], v[68:69] op_sel:[0,1,0]
	s_cmpk_lg_i32 s7, 0x400
	v_pk_fma_f32 v[52:53], v[8:9], v[54:55], v[52:53] op_sel_hi:[1,0,1]
	v_pk_mul_f32 v[54:55], v[40:41], v[42:43] op_sel:[0,1]
	v_pk_fma_f32 v[52:53], v[10:11], v[48:49], v[52:53] op_sel_hi:[1,0,1]
	s_waitcnt lgkmcnt(2)
	v_mov_b32_e32 v48, v59
	v_pk_fma_f32 v[52:53], v[12:13], v[56:57], v[52:53] op_sel_hi:[1,0,1]
	s_nop 0
	v_pk_fma_f32 v[52:53], v[14:15], v[56:57], v[52:53] op_sel:[0,1,0]
	v_pk_fma_f32 v[56:57], v[38:39], v[42:43], v[54:55] neg_lo:[0,0,1] neg_hi:[0,0,1]
	v_pk_fma_f32 v[52:53], v[0:1], v[58:59], v[52:53] op_sel_hi:[1,0,1]
	v_pk_fma_f32 v[42:43], v[38:39], v[42:43], v[54:55] op_sel_hi:[1,0,1]
	v_pk_fma_f32 v[52:53], v[2:3], v[48:49], v[52:53] op_sel_hi:[1,0,1]
	s_waitcnt lgkmcnt(1)
	v_mov_b32_e32 v48, v63
	v_pk_fma_f32 v[70:71], v[16:17], v[60:61], 0 op_sel_hi:[1,0,0]
	v_mov_b32_e32 v57, v43
	v_pk_fma_f32 v[70:71], v[18:19], v[60:61], v[70:71] op_sel:[0,1,0]
	s_nop 0
	v_pk_fma_f32 v[70:71], v[20:21], v[62:63], v[70:71] op_sel_hi:[1,0,1]
	s_nop 0
	v_pk_fma_f32 v[70:71], v[22:23], v[48:49], v[70:71] op_sel_hi:[1,0,1]
	s_waitcnt lgkmcnt(0)
	v_mov_b32_e32 v48, v67
	v_pk_fma_f32 v[70:71], v[24:25], v[64:65], v[70:71] op_sel_hi:[1,0,1]
	s_nop 0
	v_pk_fma_f32 v[70:71], v[26:27], v[64:65], v[70:71] op_sel:[0,1,0]
	s_nop 0
	v_pk_fma_f32 v[70:71], v[28:29], v[66:67], v[70:71] op_sel_hi:[1,0,1]
	s_nop 0
	v_pk_fma_f32 v[70:71], v[30:31], v[48:49], v[70:71] op_sel_hi:[1,0,1]
	s_nop 0
	v_pk_add_f32 v[52:53], v[52:53], v[70:71]
	s_nop 0
	v_pk_add_f32 v[42:43], v[56:57], v[52:53]
	ds_read_b128 v[52:55], v45 offset:64
	ds_read_b128 v[56:59], v45 offset:80
	ds_read_b128 v[60:63], v45 offset:96
	ds_read_b128 v[64:67], v45 offset:112
	s_waitcnt lgkmcnt(3)
	v_pk_fma_f32 v[68:69], v[4:5], v[52:53], 0 op_sel_hi:[1,0,0]
	s_nop 0
	v_pk_fma_f32 v[52:53], v[6:7], v[52:53], v[68:69] op_sel:[0,1,0]
	v_mov_b32_e32 v48, v55
	v_pk_fma_f32 v[52:53], v[8:9], v[54:55], v[52:53] op_sel_hi:[1,0,1]
	v_pk_mul_f32 v[54:55], v[40:41], v[42:43] op_sel:[0,1]
	v_pk_fma_f32 v[52:53], v[10:11], v[48:49], v[52:53] op_sel_hi:[1,0,1]
	s_waitcnt lgkmcnt(2)
	v_mov_b32_e32 v48, v59
	v_pk_fma_f32 v[52:53], v[12:13], v[56:57], v[52:53] op_sel_hi:[1,0,1]
	s_nop 0
	v_pk_fma_f32 v[52:53], v[14:15], v[56:57], v[52:53] op_sel:[0,1,0]
	v_pk_fma_f32 v[56:57], v[38:39], v[42:43], v[54:55] neg_lo:[0,0,1] neg_hi:[0,0,1]
	v_pk_fma_f32 v[52:53], v[0:1], v[58:59], v[52:53] op_sel_hi:[1,0,1]
	v_pk_fma_f32 v[42:43], v[38:39], v[42:43], v[54:55] op_sel_hi:[1,0,1]
	v_pk_fma_f32 v[52:53], v[2:3], v[48:49], v[52:53] op_sel_hi:[1,0,1]
	s_waitcnt lgkmcnt(1)
	v_mov_b32_e32 v48, v63
	v_pk_fma_f32 v[70:71], v[16:17], v[60:61], 0 op_sel_hi:[1,0,0]
	v_mov_b32_e32 v57, v43
	v_pk_fma_f32 v[70:71], v[18:19], v[60:61], v[70:71] op_sel:[0,1,0]
	s_nop 0
	v_pk_fma_f32 v[70:71], v[20:21], v[62:63], v[70:71] op_sel_hi:[1,0,1]
	s_nop 0
	v_pk_fma_f32 v[70:71], v[22:23], v[48:49], v[70:71] op_sel_hi:[1,0,1]
	s_waitcnt lgkmcnt(0)
	v_mov_b32_e32 v48, v67
	v_pk_fma_f32 v[70:71], v[24:25], v[64:65], v[70:71] op_sel_hi:[1,0,1]
	s_nop 0
	v_pk_fma_f32 v[70:71], v[26:27], v[64:65], v[70:71] op_sel:[0,1,0]
	s_nop 0
	v_pk_fma_f32 v[70:71], v[28:29], v[66:67], v[70:71] op_sel_hi:[1,0,1]
	s_nop 0
	v_pk_fma_f32 v[70:71], v[30:31], v[48:49], v[70:71] op_sel_hi:[1,0,1]
	s_nop 0
	v_pk_add_f32 v[52:53], v[52:53], v[70:71]
	s_nop 0
	v_pk_add_f32 v[42:43], v[56:57], v[52:53]
	ds_read_b128 v[52:55], v45 offset:128
	ds_read_b128 v[56:59], v45 offset:144
	ds_read_b128 v[60:63], v45 offset:160
	ds_read_b128 v[64:67], v45 offset:176
	s_waitcnt lgkmcnt(3)
; #define LAS __attribute__((address_space(3)))
; #define WAVE_SYNC() asm volatile("s_waitcnt lgkmcnt(0)" ::: "memory")
; template <int PASS>
; __device__ __forceinline__ void s5_scan(const Params& p, int l, int widx, int nw, int beff, int nblk, int lane, LAS unsigned char* lds) {
;     ...
;         for (int bt = 0; bt < 16; ++bt) {
;             LAS float* ubc = ub + (bt & 1) * 256;
;             *(LAS f32x4*)(ubc + lane * 4) = un;
;             if (bt + 1 < 16) un = *(const f32x4*)(ZS + (size_t)(m0 + (bt + 1) * 16 + (lane >> 2)) * 512 + g * 16 + (lane & 3) * 4);
;             WAVE_SYNC();
; #pragma unroll 4
;             for (int s = 0; s < 16; ++s) {
;                 const f32x4 u0 = *(LAS f32x4*)(ubc + s * 16), u1 = *(LAS f32x4*)(ubc + s * 16 + 4), u2 = *(LAS f32x4*)(ubc + s * 16 + 8), u3 = *(LAS f32x4*)(ubc + s * 16 + 12);
;                 float bur = 0.f, bui = 0.f;
; #pragma unroll
;                 for (int j = 0; j < 4; ++j) { bur += br[j] * u0[j]; bui += bi[j] * u0[j]; }
; #pragma unroll
;                 for (int j = 0; j < 4; ++j) { bur += br[4 + j] * u1[j]; bui += bi[4 + j] * u1[j]; }
; #pragma unroll
;                 for (int j = 0; j < 4; ++j) { bur += br[8 + j] * u2[j]; bui += bi[8 + j] * u2[j]; }
; #pragma unroll
;                 for (int j = 0; j < 4; ++j) { bur += br[12 + j] * u3[j]; bui += bi[12 + j] * u3[j]; }
;                 const float nxr = ar * xr - ai * xi + bur, nxi = ar * xi + ai * xr + bui; xr = nxr; xi = nxi;
;                 if (PASS == 2) { xb[s * 132 + lane] = xr; xb[s * 132 + 64 + lane] = xi; }
;             }
	v_pk_fma_f32 v[68:69], v[4:5], v[52:53], 0 op_sel_hi:[1,0,0]
	s_nop 0
	v_pk_fma_f32 v[52:53], v[6:7], v[52:53], v[68:69] op_sel:[0,1,0]
	v_mov_b32_e32 v48, v55
	v_pk_fma_f32 v[52:53], v[8:9], v[54:55], v[52:53] op_sel_hi:[1,0,1]
	v_pk_mul_f32 v[54:55], v[40:41], v[42:43] op_sel:[0,1]
	v_pk_fma_f32 v[52:53], v[10:11], v[48:49], v[52:53] op_sel_hi:[1,0,1]
	s_waitcnt lgkmcnt(2)
	v_mov_b32_e32 v48, v59
	v_pk_fma_f32 v[52:53], v[12:13], v[56:57], v[52:53] op_sel_hi:[1,0,1]
	s_nop 0
	v_pk_fma_f32 v[52:53], v[14:15], v[56:57], v[52:53] op_sel:[0,1,0]
	v_pk_fma_f32 v[56:57], v[38:39], v[42:43], v[54:55] neg_lo:[0,0,1] neg_hi:[0,0,1]
	v_pk_fma_f32 v[52:53], v[0:1], v[58:59], v[52:53] op_sel_hi:[1,0,1]
	v_pk_fma_f32 v[42:43], v[38:39], v[42:43], v[54:55] op_sel_hi:[1,0,1]
	v_pk_fma_f32 v[52:53], v[2:3], v[48:49], v[52:53] op_sel_hi:[1,0,1]
	s_waitcnt lgkmcnt(1)
	v_mov_b32_e32 v48, v63
	v_pk_fma_f32 v[70:71], v[16:17], v[60:61], 0 op_sel_hi:[1,0,0]
	v_mov_b32_e32 v57, v43
	v_pk_fma_f32 v[70:71], v[18:19], v[60:61], v[70:71] op_sel:[0,1,0]
	s_nop 0
	v_pk_fma_f32 v[70:71], v[20:21], v[62:63], v[70:71] op_sel_hi:[1,0,1]
	s_nop 0
	v_pk_fma_f32 v[70:71], v[22:23], v[48:49], v[70:71] op_sel_hi:[1,0,1]
	s_waitcnt lgkmcnt(0)
	v_mov_b32_e32 v48, v67
	v_pk_fma_f32 v[70:71], v[24:25], v[64:65], v[70:71] op_sel_hi:[1,0,1]
	s_nop 0
	v_pk_fma_f32 v[70:71], v[26:27], v[64:65], v[70:71] op_sel:[0,1,0]
	s_nop 0
	v_pk_fma_f32 v[70:71], v[28:29], v[66:67], v[70:71] op_sel_hi:[1,0,1]
	s_nop 0
	v_pk_fma_f32 v[70:71], v[30:31], v[48:49], v[70:71] op_sel_hi:[1,0,1]
	s_nop 0
	v_pk_add_f32 v[52:53], v[52:53], v[70:71]
	s_nop 0
	v_pk_add_f32 v[42:43], v[56:57], v[52:53]
	ds_read_b128 v[52:55], v45 offset:192
	ds_read_b128 v[56:59], v45 offset:208
	ds_read_b128 v[60:63], v45 offset:224
	ds_read_b128 v[64:67], v45 offset:240
	s_waitcnt lgkmcnt(3)
	v_pk_fma_f32 v[68:69], v[4:5], v[52:53], 0 op_sel_hi:[1,0,0]
	s_nop 0
	v_pk_fma_f32 v[52:53], v[6:7], v[52:53], v[68:69] op_sel:[0,1,0]
	v_mov_b32_e32 v48, v55
	v_pk_fma_f32 v[52:53], v[8:9], v[54:55], v[52:53] op_sel_hi:[1,0,1]
	v_pk_mul_f32 v[54:55], v[40:41], v[42:43] op_sel:[0,1]
	v_pk_fma_f32 v[52:53], v[10:11], v[48:49], v[52:53] op_sel_hi:[1,0,1]
	s_waitcnt lgkmcnt(2)
	v_mov_b32_e32 v48, v59
	v_pk_fma_f32 v[52:53], v[12:13], v[56:57], v[52:53] op_sel_hi:[1,0,1]
	s_nop 0
	v_pk_fma_f32 v[52:53], v[14:15], v[56:57], v[52:53] op_sel:[0,1,0]
	v_pk_fma_f32 v[56:57], v[38:39], v[42:43], v[54:55] neg_lo:[0,0,1] neg_hi:[0,0,1]
	v_pk_fma_f32 v[52:53], v[0:1], v[58:59], v[52:53] op_sel_hi:[1,0,1]
	v_pk_fma_f32 v[42:43], v[38:39], v[42:43], v[54:55] op_sel_hi:[1,0,1]
	v_pk_fma_f32 v[52:53], v[2:3], v[48:49], v[52:53] op_sel_hi:[1,0,1]
	s_waitcnt lgkmcnt(1)
	v_mov_b32_e32 v48, v63
	v_pk_fma_f32 v[70:71], v[16:17], v[60:61], 0 op_sel_hi:[1,0,0]
	v_mov_b32_e32 v57, v43
	v_pk_fma_f32 v[70:71], v[18:19], v[60:61], v[70:71] op_sel:[0,1,0]
	s_nop 0
	v_pk_fma_f32 v[70:71], v[20:21], v[62:63], v[70:71] op_sel_hi:[1,0,1]
	s_nop 0
	v_pk_fma_f32 v[70:71], v[22:23], v[48:49], v[70:71] op_sel_hi:[1,0,1]
	s_waitcnt lgkmcnt(0)
	v_mov_b32_e32 v48, v67
	v_pk_fma_f32 v[70:71], v[24:25], v[64:65], v[70:71] op_sel_hi:[1,0,1]
	s_nop 0
	v_pk_fma_f32 v[70:71], v[26:27], v[64:65], v[70:71] op_sel:[0,1,0]
	s_nop 0
	v_pk_fma_f32 v[70:71], v[28:29], v[66:67], v[70:71] op_sel_hi:[1,0,1]
	s_nop 0
	v_pk_fma_f32 v[70:71], v[30:31], v[48:49], v[70:71] op_sel_hi:[1,0,1]
	s_nop 0
	v_pk_add_f32 v[52:53], v[52:53], v[70:71]
	s_nop 0
	v_pk_add_f32 v[42:43], v[56:57], v[52:53]
	s_cbranch_scc1 .LBB0_398
	s_waitcnt vmcnt(0)
	ds_write_b128 v51, v[32:35]
	v_or_b32_e32 v32, 0x50, v44
	v_ashrrev_i32_e32 v33, 31, v32
	v_lshlrev_b64 v[32:33], 11, v[32:33]
	v_lshl_add_u64 v[32:33], v[46:47], 0, v[32:33]
	global_load_dwordx4 v[32:35], v[32:33], off
	s_waitcnt lgkmcnt(0)
	s_mov_b32 s7, 0
.LBB0_400:
	s_add_i32 s8, s5, s7
	v_mov_b32_e32 v45, s8
	ds_read_b128 v[52:55], v45
	ds_read_b128 v[56:59], v45 offset:16
	ds_read_b128 v[60:63], v45 offset:32
	ds_read_b128 v[64:67], v45 offset:48
	s_addk_i32 s7, 0x100
	s_waitcnt lgkmcnt(3)
	v_pk_fma_f32 v[68:69], v[4:5], v[52:53], 0 op_sel_hi:[1,0,0]
	v_mov_b32_e32 v48, v55
	v_pk_fma_f32 v[52:53], v[6:7], v[52:53], v[68:69] op_sel:[0,1,0]
	s_cmpk_lg_i32 s7, 0x400
	v_pk_fma_f32 v[52:53], v[8:9], v[54:55], v[52:53] op_sel_hi:[1,0,1]
	v_pk_mul_f32 v[54:55], v[40:41], v[42:43] op_sel:[0,1]
	v_pk_fma_f32 v[52:53], v[10:11], v[48:49], v[52:53] op_sel_hi:[1,0,1]
	s_waitcnt lgkmcnt(2)
	v_mov_b32_e32 v48, v59
	v_pk_fma_f32 v[52:53], v[12:13], v[56:57], v[52:53] op_sel_hi:[1,0,1]
	s_nop 0
	v_pk_fma_f32 v[52:53], v[14:15], v[56:57], v[52:53] op_sel:[0,1,0]
	v_pk_fma_f32 v[56:57], v[38:39], v[42:43], v[54:55] neg_lo:[0,0,1] neg_hi:[0,0,1]
	v_pk_fma_f32 v[52:53], v[0:1], v[58:59], v[52:53] op_sel_hi:[1,0,1]
	v_pk_fma_f32 v[42:43], v[38:39], v[42:43], v[54:55] op_sel_hi:[1,0,1]
	v_pk_fma_f32 v[52:53], v[2:3], v[48:49], v[52:53] op_sel_hi:[1,0,1]
	s_waitcnt lgkmcnt(1)
	v_mov_b32_e32 v48, v63
	v_pk_fma_f32 v[70:71], v[16:17], v[60:61], 0 op_sel_hi:[1,0,0]
	v_mov_b32_e32 v57, v43
	v_pk_fma_f32 v[70:71], v[18:19], v[60:61], v[70:71] op_sel:[0,1,0]
	s_nop 0
	v_pk_fma_f32 v[70:71], v[20:21], v[62:63], v[70:71] op_sel_hi:[1,0,1]
	s_nop 0
	v_pk_fma_f32 v[70:71], v[22:23], v[48:49], v[70:71] op_sel_hi:[1,0,1]
	s_waitcnt lgkmcnt(0)
	v_mov_b32_e32 v48, v67
	v_pk_fma_f32 v[70:71], v[24:25], v[64:65], v[70:71] op_sel_hi:[1,0,1]
	s_nop 0
	v_pk_fma_f32 v[70:71], v[26:27], v[64:65], v[70:71] op_sel:[0,1,0]
	s_nop 0
	v_pk_fma_f32 v[70:71], v[28:29], v[66:67], v[70:71] op_sel_hi:[1,0,1]
	s_nop 0
	v_pk_fma_f32 v[70:71], v[30:31], v[48:49], v[70:71] op_sel_hi:[1,0,1]
	s_nop 0
	v_pk_add_f32 v[52:53], v[52:53], v[70:71]
	s_nop 0
	v_pk_add_f32 v[42:43], v[56:57], v[52:53]
	ds_read_b128 v[52:55], v45 offset:64
	ds_read_b128 v[56:59], v45 offset:80
	ds_read_b128 v[60:63], v45 offset:96
	ds_read_b128 v[64:67], v45 offset:112
	s_waitcnt lgkmcnt(3)
; #define LAS __attribute__((address_space(3)))
; #define WAVE_SYNC() asm volatile("s_waitcnt lgkmcnt(0)" ::: "memory")
; template <int PASS>
; __device__ __forceinline__ void s5_scan(const Params& p, int l, int widx, int nw, int beff, int nblk, int lane, LAS unsigned char* lds) {
;     ...
;         for (int bt = 0; bt < 16; ++bt) {
;             LAS float* ubc = ub + (bt & 1) * 256;
;             *(LAS f32x4*)(ubc + lane * 4) = un;
;             if (bt + 1 < 16) un = *(const f32x4*)(ZS + (size_t)(m0 + (bt + 1) * 16 + (lane >> 2)) * 512 + g * 16 + (lane & 3) * 4);
;             WAVE_SYNC();
; #pragma unroll 4
;             for (int s = 0; s < 16; ++s) {
;                 const f32x4 u0 = *(LAS f32x4*)(ubc + s * 16), u1 = *(LAS f32x4*)(ubc + s * 16 + 4), u2 = *(LAS f32x4*)(ubc + s * 16 + 8), u3 = *(LAS f32x4*)(ubc + s * 16 + 12);
;                 float bur = 0.f, bui = 0.f;
; #pragma unroll
;                 for (int j = 0; j < 4; ++j) { bur += br[j] * u0[j]; bui += bi[j] * u0[j]; }
; #pragma unroll
;                 for (int j = 0; j < 4; ++j) { bur += br[4 + j] * u1[j]; bui += bi[4 + j] * u1[j]; }
; #pragma unroll
;                 for (int j = 0; j < 4; ++j) { bur += br[8 + j] * u2[j]; bui += bi[8 + j] * u2[j]; }
; #pragma unroll
;                 for (int j = 0; j < 4; ++j) { bur += br[12 + j] * u3[j]; bui += bi[12 + j] * u3[j]; }
;                 const float nxr = ar * xr - ai * xi + bur, nxi = ar * xi + ai * xr + bui; xr = nxr; xi = nxi;
;                 if (PASS == 2) { xb[s * 132 + lane] = xr; xb[s * 132 + 64 + lane] = xi; }
;             }
	v_pk_fma_f32 v[68:69], v[4:5], v[52:53], 0 op_sel_hi:[1,0,0]
	s_nop 0
	v_pk_fma_f32 v[52:53], v[6:7], v[52:53], v[68:69] op_sel:[0,1,0]
	v_mov_b32_e32 v48, v55
	v_pk_fma_f32 v[52:53], v[8:9], v[54:55], v[52:53] op_sel_hi:[1,0,1]
	v_pk_mul_f32 v[54:55], v[40:41], v[42:43] op_sel:[0,1]
	v_pk_fma_f32 v[52:53], v[10:11], v[48:49], v[52:53] op_sel_hi:[1,0,1]
	s_waitcnt lgkmcnt(2)
	v_mov_b32_e32 v48, v59
	v_pk_fma_f32 v[52:53], v[12:13], v[56:57], v[52:53] op_sel_hi:[1,0,1]
	s_nop 0
	v_pk_fma_f32 v[52:53], v[14:15], v[56:57], v[52:53] op_sel:[0,1,0]
	v_pk_fma_f32 v[56:57], v[38:39], v[42:43], v[54:55] neg_lo:[0,0,1] neg_hi:[0,0,1]
	v_pk_fma_f32 v[52:53], v[0:1], v[58:59], v[52:53] op_sel_hi:[1,0,1]
	v_pk_fma_f32 v[42:43], v[38:39], v[42:43], v[54:55] op_sel_hi:[1,0,1]
	v_pk_fma_f32 v[52:53], v[2:3], v[48:49], v[52:53] op_sel_hi:[1,0,1]
	s_waitcnt lgkmcnt(1)
	v_mov_b32_e32 v48, v63
	v_pk_fma_f32 v[70:71], v[16:17], v[60:61], 0 op_sel_hi:[1,0,0]
	v_mov_b32_e32 v57, v43
	v_pk_fma_f32 v[70:71], v[18:19], v[60:61], v[70:71] op_sel:[0,1,0]
	s_nop 0
	v_pk_fma_f32 v[70:71], v[20:21], v[62:63], v[70:71] op_sel_hi:[1,0,1]
	s_nop 0
	v_pk_fma_f32 v[70:71], v[22:23], v[48:49], v[70:71] op_sel_hi:[1,0,1]
	s_waitcnt lgkmcnt(0)
	v_mov_b32_e32 v48, v67
	v_pk_fma_f32 v[70:71], v[24:25], v[64:65], v[70:71] op_sel_hi:[1,0,1]
	s_nop 0
	v_pk_fma_f32 v[70:71], v[26:27], v[64:65], v[70:71] op_sel:[0,1,0]
	s_nop 0
	v_pk_fma_f32 v[70:71], v[28:29], v[66:67], v[70:71] op_sel_hi:[1,0,1]
	s_nop 0
	v_pk_fma_f32 v[70:71], v[30:31], v[48:49], v[70:71] op_sel_hi:[1,0,1]
	s_nop 0
	v_pk_add_f32 v[52:53], v[52:53], v[70:71]
	s_nop 0
	v_pk_add_f32 v[42:43], v[56:57], v[52:53]
	ds_read_b128 v[52:55], v45 offset:128
	ds_read_b128 v[56:59], v45 offset:144
	ds_read_b128 v[60:63], v45 offset:160
	ds_read_b128 v[64:67], v45 offset:176
	s_waitcnt lgkmcnt(3)
	v_pk_fma_f32 v[68:69], v[4:5], v[52:53], 0 op_sel_hi:[1,0,0]
	s_nop 0
	v_pk_fma_f32 v[52:53], v[6:7], v[52:53], v[68:69] op_sel:[0,1,0]
	v_mov_b32_e32 v48, v55
	v_pk_fma_f32 v[52:53], v[8:9], v[54:55], v[52:53] op_sel_hi:[1,0,1]
	v_pk_mul_f32 v[54:55], v[40:41], v[42:43] op_sel:[0,1]
	v_pk_fma_f32 v[52:53], v[10:11], v[48:49], v[52:53] op_sel_hi:[1,0,1]
	s_waitcnt lgkmcnt(2)
	v_mov_b32_e32 v48, v59
	v_pk_fma_f32 v[52:53], v[12:13], v[56:57], v[52:53] op_sel_hi:[1,0,1]
	s_nop 0
	v_pk_fma_f32 v[52:53], v[14:15], v[56:57], v[52:53] op_sel:[0,1,0]
	v_pk_fma_f32 v[56:57], v[38:39], v[42:43], v[54:55] neg_lo:[0,0,1] neg_hi:[0,0,1]
	v_pk_fma_f32 v[52:53], v[0:1], v[58:59], v[52:53] op_sel_hi:[1,0,1]
	v_pk_fma_f32 v[42:43], v[38:39], v[42:43], v[54:55] op_sel_hi:[1,0,1]
	v_pk_fma_f32 v[52:53], v[2:3], v[48:49], v[52:53] op_sel_hi:[1,0,1]
	s_waitcnt lgkmcnt(1)
	v_mov_b32_e32 v48, v63
	v_pk_fma_f32 v[70:71], v[16:17], v[60:61], 0 op_sel_hi:[1,0,0]
	v_mov_b32_e32 v57, v43
	v_pk_fma_f32 v[70:71], v[18:19], v[60:61], v[70:71] op_sel:[0,1,0]
	s_nop 0
	v_pk_fma_f32 v[70:71], v[20:21], v[62:63], v[70:71] op_sel_hi:[1,0,1]
	s_nop 0
	v_pk_fma_f32 v[70:71], v[22:23], v[48:49], v[70:71] op_sel_hi:[1,0,1]
	s_waitcnt lgkmcnt(0)
	v_mov_b32_e32 v48, v67
	v_pk_fma_f32 v[70:71], v[24:25], v[64:65], v[70:71] op_sel_hi:[1,0,1]
	s_nop 0
	v_pk_fma_f32 v[70:71], v[26:27], v[64:65], v[70:71] op_sel:[0,1,0]
	s_nop 0
	v_pk_fma_f32 v[70:71], v[28:29], v[66:67], v[70:71] op_sel_hi:[1,0,1]
	s_nop 0
	v_pk_fma_f32 v[70:71], v[30:31], v[48:49], v[70:71] op_sel_hi:[1,0,1]
	s_nop 0
	v_pk_add_f32 v[52:53], v[52:53], v[70:71]
	s_nop 0
	v_pk_add_f32 v[42:43], v[56:57], v[52:53]
	ds_read_b128 v[52:55], v45 offset:192
	ds_read_b128 v[56:59], v45 offset:208
	ds_read_b128 v[60:63], v45 offset:224
	ds_read_b128 v[64:67], v45 offset:240
	s_waitcnt lgkmcnt(3)
	v_pk_fma_f32 v[68:69], v[4:5], v[52:53], 0 op_sel_hi:[1,0,0]
	s_nop 0
	v_pk_fma_f32 v[52:53], v[6:7], v[52:53], v[68:69] op_sel:[0,1,0]
	v_mov_b32_e32 v48, v55
	v_pk_fma_f32 v[52:53], v[8:9], v[54:55], v[52:53] op_sel_hi:[1,0,1]
	v_pk_mul_f32 v[54:55], v[40:41], v[42:43] op_sel:[0,1]
	v_pk_fma_f32 v[52:53], v[10:11], v[48:49], v[52:53] op_sel_hi:[1,0,1]
	s_waitcnt lgkmcnt(2)
	v_mov_b32_e32 v48, v59
	v_pk_fma_f32 v[52:53], v[12:13], v[56:57], v[52:53] op_sel_hi:[1,0,1]
	s_nop 0
	v_pk_fma_f32 v[52:53], v[14:15], v[56:57], v[52:53] op_sel:[0,1,0]
	v_pk_fma_f32 v[56:57], v[38:39], v[42:43], v[54:55] neg_lo:[0,0,1] neg_hi:[0,0,1]
	v_pk_fma_f32 v[52:53], v[0:1], v[58:59], v[52:53] op_sel_hi:[1,0,1]
	v_pk_fma_f32 v[42:43], v[38:39], v[42:43], v[54:55] op_sel_hi:[1,0,1]
	v_pk_fma_f32 v[52:53], v[2:3], v[48:49], v[52:53] op_sel_hi:[1,0,1]
	s_waitcnt lgkmcnt(1)
	v_mov_b32_e32 v48, v63
	v_pk_fma_f32 v[70:71], v[16:17], v[60:61], 0 op_sel_hi:[1,0,0]
	v_mov_b32_e32 v57, v43
	v_pk_fma_f32 v[70:71], v[18:19], v[60:61], v[70:71] op_sel:[0,1,0]
	s_nop 0
	v_pk_fma_f32 v[70:71], v[20:21], v[62:63], v[70:71] op_sel_hi:[1,0,1]
	s_nop 0
	v_pk_fma_f32 v[70:71], v[22:23], v[48:49], v[70:71] op_sel_hi:[1,0,1]
	s_waitcnt lgkmcnt(0)
	v_mov_b32_e32 v48, v67
	v_pk_fma_f32 v[70:71], v[24:25], v[64:65], v[70:71] op_sel_hi:[1,0,1]
	s_nop 0
	v_pk_fma_f32 v[70:71], v[26:27], v[64:65], v[70:71] op_sel:[0,1,0]
	s_nop 0
	v_pk_fma_f32 v[70:71], v[28:29], v[66:67], v[70:71] op_sel_hi:[1,0,1]
	s_nop 0
	v_pk_fma_f32 v[70:71], v[30:31], v[48:49], v[70:71] op_sel_hi:[1,0,1]
	s_nop 0
	v_pk_add_f32 v[52:53], v[52:53], v[70:71]
	s_nop 0
	v_pk_add_f32 v[42:43], v[56:57], v[52:53]
	s_cbranch_scc1 .LBB0_400
	s_waitcnt vmcnt(0)
	ds_write_b128 v51, v[32:35] offset:1024
	v_or_b32_e32 v32, 0x60, v44
	v_ashrrev_i32_e32 v33, 31, v32
	v_lshlrev_b64 v[32:33], 11, v[32:33]
	v_lshl_add_u64 v[32:33], v[46:47], 0, v[32:33]
	global_load_dwordx4 v[32:35], v[32:33], off
	s_waitcnt lgkmcnt(0)
	s_mov_b32 s7, 0
; #define LAS __attribute__((address_space(3)))
; #define WAVE_SYNC() asm volatile("s_waitcnt lgkmcnt(0)" ::: "memory")
; template <int PASS>
; __device__ __forceinline__ void s5_scan(const Params& p, int l, int widx, int nw, int beff, int nblk, int lane, LAS unsigned char* lds) {
;     ...
;         for (int bt = 0; bt < 16; ++bt) {
;             LAS float* ubc = ub + (bt & 1) * 256;
;             *(LAS f32x4*)(ubc + lane * 4) = un;
;             if (bt + 1 < 16) un = *(const f32x4*)(ZS + (size_t)(m0 + (bt + 1) * 16 + (lane >> 2)) * 512 + g * 16 + (lane & 3) * 4);
;             WAVE_SYNC();
; #pragma unroll 4
;             for (int s = 0; s < 16; ++s) {
;                 const f32x4 u0 = *(LAS f32x4*)(ubc + s * 16), u1 = *(LAS f32x4*)(ubc + s * 16 + 4), u2 = *(LAS f32x4*)(ubc + s * 16 + 8), u3 = *(LAS f32x4*)(ubc + s * 16 + 12);
;                 float bur = 0.f, bui = 0.f;
; #pragma unroll
;                 for (int j = 0; j < 4; ++j) { bur += br[j] * u0[j]; bui += bi[j] * u0[j]; }
; #pragma unroll
;                 for (int j = 0; j < 4; ++j) { bur += br[4 + j] * u1[j]; bui += bi[4 + j] * u1[j]; }
; #pragma unroll
;                 for (int j = 0; j < 4; ++j) { bur += br[8 + j] * u2[j]; bui += bi[8 + j] * u2[j]; }
; #pragma unroll
;                 for (int j = 0; j < 4; ++j) { bur += br[12 + j] * u3[j]; bui += bi[12 + j] * u3[j]; }
;                 const float nxr = ar * xr - ai * xi + bur, nxi = ar * xi + ai * xr + bui; xr = nxr; xi = nxi;
;                 if (PASS == 2) { xb[s * 132 + lane] = xr; xb[s * 132 + 64 + lane] = xi; }
;             }
.LBB0_402:
	s_add_i32 s8, s6, s7
	v_mov_b32_e32 v45, s8
	ds_read_b128 v[52:55], v45
	ds_read_b128 v[56:59], v45 offset:16
	ds_read_b128 v[60:63], v45 offset:32
	ds_read_b128 v[64:67], v45 offset:48
	s_addk_i32 s7, 0x100
	s_waitcnt lgkmcnt(3)
	v_pk_fma_f32 v[68:69], v[4:5], v[52:53], 0 op_sel_hi:[1,0,0]
	v_mov_b32_e32 v48, v55
	v_pk_fma_f32 v[52:53], v[6:7], v[52:53], v[68:69] op_sel:[0,1,0]
	s_cmpk_lg_i32 s7, 0x400
	v_pk_fma_f32 v[52:53], v[8:9], v[54:55], v[52:53] op_sel_hi:[1,0,1]
	v_pk_mul_f32 v[54:55], v[40:41], v[42:43] op_sel:[0,1]
	v_pk_fma_f32 v[52:53], v[10:11], v[48:49], v[52:53] op_sel_hi:[1,0,1]
	s_waitcnt lgkmcnt(2)
	v_mov_b32_e32 v48, v59
	v_pk_fma_f32 v[52:53], v[12:13], v[56:57], v[52:53] op_sel_hi:[1,0,1]
	s_nop 0
	v_pk_fma_f32 v[52:53], v[14:15], v[56:57], v[52:53] op_sel:[0,1,0]
	v_pk_fma_f32 v[56:57], v[38:39], v[42:43], v[54:55] neg_lo:[0,0,1] neg_hi:[0,0,1]
	v_pk_fma_f32 v[52:53], v[0:1], v[58:59], v[52:53] op_sel_hi:[1,0,1]
	v_pk_fma_f32 v[42:43], v[38:39], v[42:43], v[54:55] op_sel_hi:[1,0,1]
	v_pk_fma_f32 v[52:53], v[2:3], v[48:49], v[52:53] op_sel_hi:[1,0,1]
	s_waitcnt lgkmcnt(1)
	v_mov_b32_e32 v48, v63
	v_pk_fma_f32 v[70:71], v[16:17], v[60:61], 0 op_sel_hi:[1,0,0]
	v_mov_b32_e32 v57, v43
	v_pk_fma_f32 v[70:71], v[18:19], v[60:61], v[70:71] op_sel:[0,1,0]
	s_nop 0
	v_pk_fma_f32 v[70:71], v[20:21], v[62:63], v[70:71] op_sel_hi:[1,0,1]
	s_nop 0
	v_pk_fma_f32 v[70:71], v[22:23], v[48:49], v[70:71] op_sel_hi:[1,0,1]
	s_waitcnt lgkmcnt(0)
	v_mov_b32_e32 v48, v67
	v_pk_fma_f32 v[70:71], v[24:25], v[64:65], v[70:71] op_sel_hi:[1,0,1]
	s_nop 0
	v_pk_fma_f32 v[70:71], v[26:27], v[64:65], v[70:71] op_sel:[0,1,0]
	s_nop 0
	v_pk_fma_f32 v[70:71], v[28:29], v[66:67], v[70:71] op_sel_hi:[1,0,1]
	s_nop 0
	v_pk_fma_f32 v[70:71], v[30:31], v[48:49], v[70:71] op_sel_hi:[1,0,1]
	s_nop 0
	v_pk_add_f32 v[52:53], v[52:53], v[70:71]
	s_nop 0
	v_pk_add_f32 v[42:43], v[56:57], v[52:53]
	ds_read_b128 v[52:55], v45 offset:64
	ds_read_b128 v[56:59], v45 offset:80
	ds_read_b128 v[60:63], v45 offset:96
	ds_read_b128 v[64:67], v45 offset:112
	s_waitcnt lgkmcnt(3)
	v_pk_fma_f32 v[68:69], v[4:5], v[52:53], 0 op_sel_hi:[1,0,0]
	s_nop 0
	v_pk_fma_f32 v[52:53], v[6:7], v[52:53], v[68:69] op_sel:[0,1,0]
	v_mov_b32_e32 v48, v55
	v_pk_fma_f32 v[52:53], v[8:9], v[54:55], v[52:53] op_sel_hi:[1,0,1]
	v_pk_mul_f32 v[54:55], v[40:41], v[42:43] op_sel:[0,1]
	v_pk_fma_f32 v[52:53], v[10:11], v[48:49], v[52:53] op_sel_hi:[1,0,1]
	s_waitcnt lgkmcnt(2)
	v_mov_b32_e32 v48, v59
	v_pk_fma_f32 v[52:53], v[12:13], v[56:57], v[52:53] op_sel_hi:[1,0,1]
	s_nop 0
	v_pk_fma_f32 v[52:53], v[14:15], v[56:57], v[52:53] op_sel:[0,1,0]
	v_pk_fma_f32 v[56:57], v[38:39], v[42:43], v[54:55] neg_lo:[0,0,1] neg_hi:[0,0,1]
	v_pk_fma_f32 v[52:53], v[0:1], v[58:59], v[52:53] op_sel_hi:[1,0,1]
	v_pk_fma_f32 v[42:43], v[38:39], v[42:43], v[54:55] op_sel_hi:[1,0,1]
	v_pk_fma_f32 v[52:53], v[2:3], v[48:49], v[52:53] op_sel_hi:[1,0,1]
	s_waitcnt lgkmcnt(1)
	v_mov_b32_e32 v48, v63
	v_pk_fma_f32 v[70:71], v[16:17], v[60:61], 0 op_sel_hi:[1,0,0]
	v_mov_b32_e32 v57, v43
	v_pk_fma_f32 v[70:71], v[18:19], v[60:61], v[70:71] op_sel:[0,1,0]
	s_nop 0
	v_pk_fma_f32 v[70:71], v[20:21], v[62:63], v[70:71] op_sel_hi:[1,0,1]
	s_nop 0
	v_pk_fma_f32 v[70:71], v[22:23], v[48:49], v[70:71] op_sel_hi:[1,0,1]
	s_waitcnt lgkmcnt(0)
	v_mov_b32_e32 v48, v67
	v_pk_fma_f32 v[70:71], v[24:25], v[64:65], v[70:71] op_sel_hi:[1,0,1]
	s_nop 0
	v_pk_fma_f32 v[70:71], v[26:27], v[64:65], v[70:71] op_sel:[0,1,0]
	s_nop 0
	v_pk_fma_f32 v[70:71], v[28:29], v[66:67], v[70:71] op_sel_hi:[1,0,1]
	s_nop 0
	v_pk_fma_f32 v[70:71], v[30:31], v[48:49], v[70:71] op_sel_hi:[1,0,1]
	s_nop 0
	v_pk_add_f32 v[52:53], v[52:53], v[70:71]
	s_nop 0
	v_pk_add_f32 v[42:43], v[56:57], v[52:53]
	ds_read_b128 v[52:55], v45 offset:128
	ds_read_b128 v[56:59], v45 offset:144
	ds_read_b128 v[60:63], v45 offset:160
	ds_read_b128 v[64:67], v45 offset:176
	s_waitcnt lgkmcnt(3)
	v_pk_fma_f32 v[68:69], v[4:5], v[52:53], 0 op_sel_hi:[1,0,0]
	s_nop 0
	v_pk_fma_f32 v[52:53], v[6:7], v[52:53], v[68:69] op_sel:[0,1,0]
	v_mov_b32_e32 v48, v55
	v_pk_fma_f32 v[52:53], v[8:9], v[54:55], v[52:53] op_sel_hi:[1,0,1]
	v_pk_mul_f32 v[54:55], v[40:41], v[42:43] op_sel:[0,1]
	v_pk_fma_f32 v[52:53], v[10:11], v[48:49], v[52:53] op_sel_hi:[1,0,1]
	s_waitcnt lgkmcnt(2)
	v_mov_b32_e32 v48, v59
	v_pk_fma_f32 v[52:53], v[12:13], v[56:57], v[52:53] op_sel_hi:[1,0,1]
	s_nop 0
	v_pk_fma_f32 v[52:53], v[14:15], v[56:57], v[52:53] op_sel:[0,1,0]
	v_pk_fma_f32 v[56:57], v[38:39], v[42:43], v[54:55] neg_lo:[0,0,1] neg_hi:[0,0,1]
	v_pk_fma_f32 v[52:53], v[0:1], v[58:59], v[52:53] op_sel_hi:[1,0,1]
	v_pk_fma_f32 v[42:43], v[38:39], v[42:43], v[54:55] op_sel_hi:[1,0,1]
	v_pk_fma_f32 v[52:53], v[2:3], v[48:49], v[52:53] op_sel_hi:[1,0,1]
	s_waitcnt lgkmcnt(1)
	v_mov_b32_e32 v48, v63
	v_pk_fma_f32 v[70:71], v[16:17], v[60:61], 0 op_sel_hi:[1,0,0]
	v_mov_b32_e32 v57, v43
	v_pk_fma_f32 v[70:71], v[18:19], v[60:61], v[70:71] op_sel:[0,1,0]
	s_nop 0
	v_pk_fma_f32 v[70:71], v[20:21], v[62:63], v[70:71] op_sel_hi:[1,0,1]
	s_nop 0
	v_pk_fma_f32 v[70:71], v[22:23], v[48:49], v[70:71] op_sel_hi:[1,0,1]
	s_waitcnt lgkmcnt(0)
	v_mov_b32_e32 v48, v67
	v_pk_fma_f32 v[70:71], v[24:25], v[64:65], v[70:71] op_sel_hi:[1,0,1]
	s_nop 0
	v_pk_fma_f32 v[70:71], v[26:27], v[64:65], v[70:71] op_sel:[0,1,0]
	s_nop 0
	v_pk_fma_f32 v[70:71], v[28:29], v[66:67], v[70:71] op_sel_hi:[1,0,1]
	s_nop 0
	v_pk_fma_f32 v[70:71], v[30:31], v[48:49], v[70:71] op_sel_hi:[1,0,1]
	s_nop 0
	v_pk_add_f32 v[52:53], v[52:53], v[70:71]
	s_nop 0
	v_pk_add_f32 v[42:43], v[56:57], v[52:53]
	ds_read_b128 v[52:55], v45 offset:192
	ds_read_b128 v[56:59], v45 offset:208
	ds_read_b128 v[60:63], v45 offset:224
	ds_read_b128 v[64:67], v45 offset:240
	s_waitcnt lgkmcnt(3)
; #define LAS __attribute__((address_space(3)))
; #define WAVE_SYNC() asm volatile("s_waitcnt lgkmcnt(0)" ::: "memory")
; template <int PASS>
; __device__ __forceinline__ void s5_scan(const Params& p, int l, int widx, int nw, int beff, int nblk, int lane, LAS unsigned char* lds) {
;     ...
;         for (int bt = 0; bt < 16; ++bt) {
;             LAS float* ubc = ub + (bt & 1) * 256;
;             *(LAS f32x4*)(ubc + lane * 4) = un;
;             if (bt + 1 < 16) un = *(const f32x4*)(ZS + (size_t)(m0 + (bt + 1) * 16 + (lane >> 2)) * 512 + g * 16 + (lane & 3) * 4);
;             WAVE_SYNC();
; #pragma unroll 4
;             for (int s = 0; s < 16; ++s) {
;                 const f32x4 u0 = *(LAS f32x4*)(ubc + s * 16), u1 = *(LAS f32x4*)(ubc + s * 16 + 4), u2 = *(LAS f32x4*)(ubc + s * 16 + 8), u3 = *(LAS f32x4*)(ubc + s * 16 + 12);
;                 float bur = 0.f, bui = 0.f;
; #pragma unroll
;                 for (int j = 0; j < 4; ++j) { bur += br[j] * u0[j]; bui += bi[j] * u0[j]; }
; #pragma unroll
;                 for (int j = 0; j < 4; ++j) { bur += br[4 + j] * u1[j]; bui += bi[4 + j] * u1[j]; }
; #pragma unroll
;                 for (int j = 0; j < 4; ++j) { bur += br[8 + j] * u2[j]; bui += bi[8 + j] * u2[j]; }
; #pragma unroll
;                 for (int j = 0; j < 4; ++j) { bur += br[12 + j] * u3[j]; bui += bi[12 + j] * u3[j]; }
;                 const float nxr = ar * xr - ai * xi + bur, nxi = ar * xi + ai * xr + bui; xr = nxr; xi = nxi;
;                 if (PASS == 2) { xb[s * 132 + lane] = xr; xb[s * 132 + 64 + lane] = xi; }
;             }
	v_pk_fma_f32 v[68:69], v[4:5], v[52:53], 0 op_sel_hi:[1,0,0]
	s_nop 0
	v_pk_fma_f32 v[52:53], v[6:7], v[52:53], v[68:69] op_sel:[0,1,0]
	v_mov_b32_e32 v48, v55
	v_pk_fma_f32 v[52:53], v[8:9], v[54:55], v[52:53] op_sel_hi:[1,0,1]
	v_pk_mul_f32 v[54:55], v[40:41], v[42:43] op_sel:[0,1]
	v_pk_fma_f32 v[52:53], v[10:11], v[48:49], v[52:53] op_sel_hi:[1,0,1]
	s_waitcnt lgkmcnt(2)
	v_mov_b32_e32 v48, v59
	v_pk_fma_f32 v[52:53], v[12:13], v[56:57], v[52:53] op_sel_hi:[1,0,1]
	s_nop 0
	v_pk_fma_f32 v[52:53], v[14:15], v[56:57], v[52:53] op_sel:[0,1,0]
	v_pk_fma_f32 v[56:57], v[38:39], v[42:43], v[54:55] neg_lo:[0,0,1] neg_hi:[0,0,1]
	v_pk_fma_f32 v[52:53], v[0:1], v[58:59], v[52:53] op_sel_hi:[1,0,1]
	v_pk_fma_f32 v[42:43], v[38:39], v[42:43], v[54:55] op_sel_hi:[1,0,1]
	v_pk_fma_f32 v[52:53], v[2:3], v[48:49], v[52:53] op_sel_hi:[1,0,1]
	s_waitcnt lgkmcnt(1)
	v_mov_b32_e32 v48, v63
	v_pk_fma_f32 v[70:71], v[16:17], v[60:61], 0 op_sel_hi:[1,0,0]
	v_mov_b32_e32 v57, v43
	v_pk_fma_f32 v[70:71], v[18:19], v[60:61], v[70:71] op_sel:[0,1,0]
	s_nop 0
	v_pk_fma_f32 v[70:71], v[20:21], v[62:63], v[70:71] op_sel_hi:[1,0,1]
	s_nop 0
	v_pk_fma_f32 v[70:71], v[22:23], v[48:49], v[70:71] op_sel_hi:[1,0,1]
	s_waitcnt lgkmcnt(0)
	v_mov_b32_e32 v48, v67
	v_pk_fma_f32 v[70:71], v[24:25], v[64:65], v[70:71] op_sel_hi:[1,0,1]
	s_nop 0
	v_pk_fma_f32 v[70:71], v[26:27], v[64:65], v[70:71] op_sel:[0,1,0]
	s_nop 0
	v_pk_fma_f32 v[70:71], v[28:29], v[66:67], v[70:71] op_sel_hi:[1,0,1]
	s_nop 0
	v_pk_fma_f32 v[70:71], v[30:31], v[48:49], v[70:71] op_sel_hi:[1,0,1]
	s_nop 0
	v_pk_add_f32 v[52:53], v[52:53], v[70:71]
	s_nop 0
	v_pk_add_f32 v[42:43], v[56:57], v[52:53]
	s_cbranch_scc1 .LBB0_402
	s_waitcnt vmcnt(0)
	ds_write_b128 v51, v[32:35]
	v_or_b32_e32 v32, 0x70, v44
	v_ashrrev_i32_e32 v33, 31, v32
	v_lshlrev_b64 v[32:33], 11, v[32:33]
	v_lshl_add_u64 v[32:33], v[46:47], 0, v[32:33]
	global_load_dwordx4 v[32:35], v[32:33], off
	s_waitcnt lgkmcnt(0)
	s_mov_b32 s7, 0
.LBB0_404:
	s_add_i32 s8, s5, s7
	v_mov_b32_e32 v45, s8
	ds_read_b128 v[52:55], v45
	ds_read_b128 v[56:59], v45 offset:16
	ds_read_b128 v[60:63], v45 offset:32
	ds_read_b128 v[64:67], v45 offset:48
	s_addk_i32 s7, 0x100
	s_waitcnt lgkmcnt(3)
	v_pk_fma_f32 v[68:69], v[4:5], v[52:53], 0 op_sel_hi:[1,0,0]
	v_mov_b32_e32 v48, v55
	v_pk_fma_f32 v[52:53], v[6:7], v[52:53], v[68:69] op_sel:[0,1,0]
	s_cmpk_lg_i32 s7, 0x400
	v_pk_fma_f32 v[52:53], v[8:9], v[54:55], v[52:53] op_sel_hi:[1,0,1]
	v_pk_mul_f32 v[54:55], v[40:41], v[42:43] op_sel:[0,1]
	v_pk_fma_f32 v[52:53], v[10:11], v[48:49], v[52:53] op_sel_hi:[1,0,1]
	s_waitcnt lgkmcnt(2)
	v_mov_b32_e32 v48, v59
	v_pk_fma_f32 v[52:53], v[12:13], v[56:57], v[52:53] op_sel_hi:[1,0,1]
	s_nop 0
	v_pk_fma_f32 v[52:53], v[14:15], v[56:57], v[52:53] op_sel:[0,1,0]
	v_pk_fma_f32 v[56:57], v[38:39], v[42:43], v[54:55] neg_lo:[0,0,1] neg_hi:[0,0,1]
	v_pk_fma_f32 v[52:53], v[0:1], v[58:59], v[52:53] op_sel_hi:[1,0,1]
	v_pk_fma_f32 v[42:43], v[38:39], v[42:43], v[54:55] op_sel_hi:[1,0,1]
	v_pk_fma_f32 v[52:53], v[2:3], v[48:49], v[52:53] op_sel_hi:[1,0,1]
	s_waitcnt lgkmcnt(1)
	v_mov_b32_e32 v48, v63
	v_pk_fma_f32 v[70:71], v[16:17], v[60:61], 0 op_sel_hi:[1,0,0]
	v_mov_b32_e32 v57, v43
	v_pk_fma_f32 v[70:71], v[18:19], v[60:61], v[70:71] op_sel:[0,1,0]
	s_nop 0
	v_pk_fma_f32 v[70:71], v[20:21], v[62:63], v[70:71] op_sel_hi:[1,0,1]
	s_nop 0
	v_pk_fma_f32 v[70:71], v[22:23], v[48:49], v[70:71] op_sel_hi:[1,0,1]
	s_waitcnt lgkmcnt(0)
	v_mov_b32_e32 v48, v67
	v_pk_fma_f32 v[70:71], v[24:25], v[64:65], v[70:71] op_sel_hi:[1,0,1]
	s_nop 0
	v_pk_fma_f32 v[70:71], v[26:27], v[64:65], v[70:71] op_sel:[0,1,0]
	s_nop 0
	v_pk_fma_f32 v[70:71], v[28:29], v[66:67], v[70:71] op_sel_hi:[1,0,1]
	s_nop 0
	v_pk_fma_f32 v[70:71], v[30:31], v[48:49], v[70:71] op_sel_hi:[1,0,1]
	s_nop 0
	v_pk_add_f32 v[52:53], v[52:53], v[70:71]
	s_nop 0
	v_pk_add_f32 v[42:43], v[56:57], v[52:53]
	ds_read_b128 v[52:55], v45 offset:64
	ds_read_b128 v[56:59], v45 offset:80
	ds_read_b128 v[60:63], v45 offset:96
	ds_read_b128 v[64:67], v45 offset:112
	s_waitcnt lgkmcnt(3)
	v_pk_fma_f32 v[68:69], v[4:5], v[52:53], 0 op_sel_hi:[1,0,0]
	s_nop 0
	v_pk_fma_f32 v[52:53], v[6:7], v[52:53], v[68:69] op_sel:[0,1,0]
	v_mov_b32_e32 v48, v55
	v_pk_fma_f32 v[52:53], v[8:9], v[54:55], v[52:53] op_sel_hi:[1,0,1]
	v_pk_mul_f32 v[54:55], v[40:41], v[42:43] op_sel:[0,1]
	v_pk_fma_f32 v[52:53], v[10:11], v[48:49], v[52:53] op_sel_hi:[1,0,1]
	s_waitcnt lgkmcnt(2)
	v_mov_b32_e32 v48, v59
	v_pk_fma_f32 v[52:53], v[12:13], v[56:57], v[52:53] op_sel_hi:[1,0,1]
	s_nop 0
	v_pk_fma_f32 v[52:53], v[14:15], v[56:57], v[52:53] op_sel:[0,1,0]
	v_pk_fma_f32 v[56:57], v[38:39], v[42:43], v[54:55] neg_lo:[0,0,1] neg_hi:[0,0,1]
	v_pk_fma_f32 v[52:53], v[0:1], v[58:59], v[52:53] op_sel_hi:[1,0,1]
	v_pk_fma_f32 v[42:43], v[38:39], v[42:43], v[54:55] op_sel_hi:[1,0,1]
	v_pk_fma_f32 v[52:53], v[2:3], v[48:49], v[52:53] op_sel_hi:[1,0,1]
	s_waitcnt lgkmcnt(1)
	v_mov_b32_e32 v48, v63
	v_pk_fma_f32 v[70:71], v[16:17], v[60:61], 0 op_sel_hi:[1,0,0]
	v_mov_b32_e32 v57, v43
	v_pk_fma_f32 v[70:71], v[18:19], v[60:61], v[70:71] op_sel:[0,1,0]
	s_nop 0
	v_pk_fma_f32 v[70:71], v[20:21], v[62:63], v[70:71] op_sel_hi:[1,0,1]
	s_nop 0
	v_pk_fma_f32 v[70:71], v[22:23], v[48:49], v[70:71] op_sel_hi:[1,0,1]
	s_waitcnt lgkmcnt(0)
	v_mov_b32_e32 v48, v67
	v_pk_fma_f32 v[70:71], v[24:25], v[64:65], v[70:71] op_sel_hi:[1,0,1]
	s_nop 0
	v_pk_fma_f32 v[70:71], v[26:27], v[64:65], v[70:71] op_sel:[0,1,0]
	s_nop 0
	v_pk_fma_f32 v[70:71], v[28:29], v[66:67], v[70:71] op_sel_hi:[1,0,1]
	s_nop 0
	v_pk_fma_f32 v[70:71], v[30:31], v[48:49], v[70:71] op_sel_hi:[1,0,1]
	s_nop 0
	v_pk_add_f32 v[52:53], v[52:53], v[70:71]
	s_nop 0
	v_pk_add_f32 v[42:43], v[56:57], v[52:53]
	ds_read_b128 v[52:55], v45 offset:128
	ds_read_b128 v[56:59], v45 offset:144
	ds_read_b128 v[60:63], v45 offset:160
	ds_read_b128 v[64:67], v45 offset:176
	s_waitcnt lgkmcnt(3)
; #define LAS __attribute__((address_space(3)))
; #define WAVE_SYNC() asm volatile("s_waitcnt lgkmcnt(0)" ::: "memory")
; template <int PASS>
; __device__ __forceinline__ void s5_scan(const Params& p, int l, int widx, int nw, int beff, int nblk, int lane, LAS unsigned char* lds) {
;     ...
;         for (int bt = 0; bt < 16; ++bt) {
;             LAS float* ubc = ub + (bt & 1) * 256;
;             *(LAS f32x4*)(ubc + lane * 4) = un;
;             if (bt + 1 < 16) un = *(const f32x4*)(ZS + (size_t)(m0 + (bt + 1) * 16 + (lane >> 2)) * 512 + g * 16 + (lane & 3) * 4);
;             WAVE_SYNC();
; #pragma unroll 4
;             for (int s = 0; s < 16; ++s) {
;                 const f32x4 u0 = *(LAS f32x4*)(ubc + s * 16), u1 = *(LAS f32x4*)(ubc + s * 16 + 4), u2 = *(LAS f32x4*)(ubc + s * 16 + 8), u3 = *(LAS f32x4*)(ubc + s * 16 + 12);
;                 float bur = 0.f, bui = 0.f;
; #pragma unroll
;                 for (int j = 0; j < 4; ++j) { bur += br[j] * u0[j]; bui += bi[j] * u0[j]; }
; #pragma unroll
;                 for (int j = 0; j < 4; ++j) { bur += br[4 + j] * u1[j]; bui += bi[4 + j] * u1[j]; }
; #pragma unroll
;                 for (int j = 0; j < 4; ++j) { bur += br[8 + j] * u2[j]; bui += bi[8 + j] * u2[j]; }
; #pragma unroll
;                 for (int j = 0; j < 4; ++j) { bur += br[12 + j] * u3[j]; bui += bi[12 + j] * u3[j]; }
;                 const float nxr = ar * xr - ai * xi + bur, nxi = ar * xi + ai * xr + bui; xr = nxr; xi = nxi;
;                 if (PASS == 2) { xb[s * 132 + lane] = xr; xb[s * 132 + 64 + lane] = xi; }
;             }
	v_pk_fma_f32 v[68:69], v[4:5], v[52:53], 0 op_sel_hi:[1,0,0]
	s_nop 0
	v_pk_fma_f32 v[52:53], v[6:7], v[52:53], v[68:69] op_sel:[0,1,0]
	v_mov_b32_e32 v48, v55
	v_pk_fma_f32 v[52:53], v[8:9], v[54:55], v[52:53] op_sel_hi:[1,0,1]
	v_pk_mul_f32 v[54:55], v[40:41], v[42:43] op_sel:[0,1]
	v_pk_fma_f32 v[52:53], v[10:11], v[48:49], v[52:53] op_sel_hi:[1,0,1]
	s_waitcnt lgkmcnt(2)
	v_mov_b32_e32 v48, v59
	v_pk_fma_f32 v[52:53], v[12:13], v[56:57], v[52:53] op_sel_hi:[1,0,1]
	s_nop 0
	v_pk_fma_f32 v[52:53], v[14:15], v[56:57], v[52:53] op_sel:[0,1,0]
	v_pk_fma_f32 v[56:57], v[38:39], v[42:43], v[54:55] neg_lo:[0,0,1] neg_hi:[0,0,1]
	v_pk_fma_f32 v[52:53], v[0:1], v[58:59], v[52:53] op_sel_hi:[1,0,1]
	v_pk_fma_f32 v[42:43], v[38:39], v[42:43], v[54:55] op_sel_hi:[1,0,1]
	v_pk_fma_f32 v[52:53], v[2:3], v[48:49], v[52:53] op_sel_hi:[1,0,1]
	s_waitcnt lgkmcnt(1)
	v_mov_b32_e32 v48, v63
	v_pk_fma_f32 v[70:71], v[16:17], v[60:61], 0 op_sel_hi:[1,0,0]
	v_mov_b32_e32 v57, v43
	v_pk_fma_f32 v[70:71], v[18:19], v[60:61], v[70:71] op_sel:[0,1,0]
	s_nop 0
	v_pk_fma_f32 v[70:71], v[20:21], v[62:63], v[70:71] op_sel_hi:[1,0,1]
	s_nop 0
	v_pk_fma_f32 v[70:71], v[22:23], v[48:49], v[70:71] op_sel_hi:[1,0,1]
	s_waitcnt lgkmcnt(0)
	v_mov_b32_e32 v48, v67
	v_pk_fma_f32 v[70:71], v[24:25], v[64:65], v[70:71] op_sel_hi:[1,0,1]
	s_nop 0
	v_pk_fma_f32 v[70:71], v[26:27], v[64:65], v[70:71] op_sel:[0,1,0]
	s_nop 0
	v_pk_fma_f32 v[70:71], v[28:29], v[66:67], v[70:71] op_sel_hi:[1,0,1]
	s_nop 0
	v_pk_fma_f32 v[70:71], v[30:31], v[48:49], v[70:71] op_sel_hi:[1,0,1]
	s_nop 0
	v_pk_add_f32 v[52:53], v[52:53], v[70:71]
	s_nop 0
	v_pk_add_f32 v[42:43], v[56:57], v[52:53]
	ds_read_b128 v[52:55], v45 offset:192
	ds_read_b128 v[56:59], v45 offset:208
	ds_read_b128 v[60:63], v45 offset:224
	ds_read_b128 v[64:67], v45 offset:240
	s_waitcnt lgkmcnt(3)
	v_pk_fma_f32 v[68:69], v[4:5], v[52:53], 0 op_sel_hi:[1,0,0]
	s_nop 0
	v_pk_fma_f32 v[52:53], v[6:7], v[52:53], v[68:69] op_sel:[0,1,0]
	v_mov_b32_e32 v48, v55
	v_pk_fma_f32 v[52:53], v[8:9], v[54:55], v[52:53] op_sel_hi:[1,0,1]
	v_pk_mul_f32 v[54:55], v[40:41], v[42:43] op_sel:[0,1]
	v_pk_fma_f32 v[52:53], v[10:11], v[48:49], v[52:53] op_sel_hi:[1,0,1]
	s_waitcnt lgkmcnt(2)
	v_mov_b32_e32 v48, v59
	v_pk_fma_f32 v[52:53], v[12:13], v[56:57], v[52:53] op_sel_hi:[1,0,1]
	s_nop 0
	v_pk_fma_f32 v[52:53], v[14:15], v[56:57], v[52:53] op_sel:[0,1,0]
	v_pk_fma_f32 v[56:57], v[38:39], v[42:43], v[54:55] neg_lo:[0,0,1] neg_hi:[0,0,1]
	v_pk_fma_f32 v[52:53], v[0:1], v[58:59], v[52:53] op_sel_hi:[1,0,1]
	v_pk_fma_f32 v[42:43], v[38:39], v[42:43], v[54:55] op_sel_hi:[1,0,1]
	v_pk_fma_f32 v[52:53], v[2:3], v[48:49], v[52:53] op_sel_hi:[1,0,1]
	s_waitcnt lgkmcnt(1)
	v_mov_b32_e32 v48, v63
	v_pk_fma_f32 v[70:71], v[16:17], v[60:61], 0 op_sel_hi:[1,0,0]
	v_mov_b32_e32 v57, v43
	v_pk_fma_f32 v[70:71], v[18:19], v[60:61], v[70:71] op_sel:[0,1,0]
	s_nop 0
	v_pk_fma_f32 v[70:71], v[20:21], v[62:63], v[70:71] op_sel_hi:[1,0,1]
	s_nop 0
	v_pk_fma_f32 v[70:71], v[22:23], v[48:49], v[70:71] op_sel_hi:[1,0,1]
	s_waitcnt lgkmcnt(0)
	v_mov_b32_e32 v48, v67
	v_pk_fma_f32 v[70:71], v[24:25], v[64:65], v[70:71] op_sel_hi:[1,0,1]
	s_nop 0
	v_pk_fma_f32 v[70:71], v[26:27], v[64:65], v[70:71] op_sel:[0,1,0]
	s_nop 0
	v_pk_fma_f32 v[70:71], v[28:29], v[66:67], v[70:71] op_sel_hi:[1,0,1]
	s_nop 0
	v_pk_fma_f32 v[70:71], v[30:31], v[48:49], v[70:71] op_sel_hi:[1,0,1]
	s_nop 0
	v_pk_add_f32 v[52:53], v[52:53], v[70:71]
	s_nop 0
	v_pk_add_f32 v[42:43], v[56:57], v[52:53]
	s_cbranch_scc1 .LBB0_404
	s_waitcnt vmcnt(0)
	ds_write_b128 v51, v[32:35] offset:1024
	v_or_b32_e32 v32, 0x80, v44
	v_ashrrev_i32_e32 v33, 31, v32
	v_lshlrev_b64 v[32:33], 11, v[32:33]
	v_lshl_add_u64 v[32:33], v[46:47], 0, v[32:33]
	global_load_dwordx4 v[32:35], v[32:33], off
	s_waitcnt lgkmcnt(0)
	s_mov_b32 s7, 0
.LBB0_406:
	s_add_i32 s8, s6, s7
	v_mov_b32_e32 v45, s8
	ds_read_b128 v[52:55], v45
	ds_read_b128 v[56:59], v45 offset:16
	ds_read_b128 v[60:63], v45 offset:32
	ds_read_b128 v[64:67], v45 offset:48
	s_addk_i32 s7, 0x100
	s_waitcnt lgkmcnt(3)
	v_pk_fma_f32 v[68:69], v[4:5], v[52:53], 0 op_sel_hi:[1,0,0]
	v_mov_b32_e32 v48, v55
	v_pk_fma_f32 v[52:53], v[6:7], v[52:53], v[68:69] op_sel:[0,1,0]
	s_cmpk_lg_i32 s7, 0x400
	v_pk_fma_f32 v[52:53], v[8:9], v[54:55], v[52:53] op_sel_hi:[1,0,1]
	v_pk_mul_f32 v[54:55], v[40:41], v[42:43] op_sel:[0,1]
	v_pk_fma_f32 v[52:53], v[10:11], v[48:49], v[52:53] op_sel_hi:[1,0,1]
	s_waitcnt lgkmcnt(2)
	v_mov_b32_e32 v48, v59
	v_pk_fma_f32 v[52:53], v[12:13], v[56:57], v[52:53] op_sel_hi:[1,0,1]
	s_nop 0
	v_pk_fma_f32 v[52:53], v[14:15], v[56:57], v[52:53] op_sel:[0,1,0]
	v_pk_fma_f32 v[56:57], v[38:39], v[42:43], v[54:55] neg_lo:[0,0,1] neg_hi:[0,0,1]
	v_pk_fma_f32 v[52:53], v[0:1], v[58:59], v[52:53] op_sel_hi:[1,0,1]
	v_pk_fma_f32 v[42:43], v[38:39], v[42:43], v[54:55] op_sel_hi:[1,0,1]
	v_pk_fma_f32 v[52:53], v[2:3], v[48:49], v[52:53] op_sel_hi:[1,0,1]
	s_waitcnt lgkmcnt(1)
	v_mov_b32_e32 v48, v63
	v_pk_fma_f32 v[70:71], v[16:17], v[60:61], 0 op_sel_hi:[1,0,0]
	v_mov_b32_e32 v57, v43
	v_pk_fma_f32 v[70:71], v[18:19], v[60:61], v[70:71] op_sel:[0,1,0]
	s_nop 0
	v_pk_fma_f32 v[70:71], v[20:21], v[62:63], v[70:71] op_sel_hi:[1,0,1]
	s_nop 0
	v_pk_fma_f32 v[70:71], v[22:23], v[48:49], v[70:71] op_sel_hi:[1,0,1]
	s_waitcnt lgkmcnt(0)
	v_mov_b32_e32 v48, v67
	v_pk_fma_f32 v[70:71], v[24:25], v[64:65], v[70:71] op_sel_hi:[1,0,1]
	s_nop 0
	v_pk_fma_f32 v[70:71], v[26:27], v[64:65], v[70:71] op_sel:[0,1,0]
	s_nop 0
	v_pk_fma_f32 v[70:71], v[28:29], v[66:67], v[70:71] op_sel_hi:[1,0,1]
	s_nop 0
	v_pk_fma_f32 v[70:71], v[30:31], v[48:49], v[70:71] op_sel_hi:[1,0,1]
	s_nop 0
	v_pk_add_f32 v[52:53], v[52:53], v[70:71]
	s_nop 0
	v_pk_add_f32 v[42:43], v[56:57], v[52:53]
	ds_read_b128 v[52:55], v45 offset:64
	ds_read_b128 v[56:59], v45 offset:80
	ds_read_b128 v[60:63], v45 offset:96
	ds_read_b128 v[64:67], v45 offset:112
	s_waitcnt lgkmcnt(3)
; #define LAS __attribute__((address_space(3)))
; #define WAVE_SYNC() asm volatile("s_waitcnt lgkmcnt(0)" ::: "memory")
; template <int PASS>
; __device__ __forceinline__ void s5_scan(const Params& p, int l, int widx, int nw, int beff, int nblk, int lane, LAS unsigned char* lds) {
;     ...
;         for (int bt = 0; bt < 16; ++bt) {
;             LAS float* ubc = ub + (bt & 1) * 256;
;             *(LAS f32x4*)(ubc + lane * 4) = un;
;             if (bt + 1 < 16) un = *(const f32x4*)(ZS + (size_t)(m0 + (bt + 1) * 16 + (lane >> 2)) * 512 + g * 16 + (lane & 3) * 4);
;             WAVE_SYNC();
; #pragma unroll 4
;             for (int s = 0; s < 16; ++s) {
;                 const f32x4 u0 = *(LAS f32x4*)(ubc + s * 16), u1 = *(LAS f32x4*)(ubc + s * 16 + 4), u2 = *(LAS f32x4*)(ubc + s * 16 + 8), u3 = *(LAS f32x4*)(ubc + s * 16 + 12);
;                 float bur = 0.f, bui = 0.f;
; #pragma unroll
;                 for (int j = 0; j < 4; ++j) { bur += br[j] * u0[j]; bui += bi[j] * u0[j]; }
; #pragma unroll
;                 for (int j = 0; j < 4; ++j) { bur += br[4 + j] * u1[j]; bui += bi[4 + j] * u1[j]; }
; #pragma unroll
;                 for (int j = 0; j < 4; ++j) { bur += br[8 + j] * u2[j]; bui += bi[8 + j] * u2[j]; }
; #pragma unroll
;                 for (int j = 0; j < 4; ++j) { bur += br[12 + j] * u3[j]; bui += bi[12 + j] * u3[j]; }
;                 const float nxr = ar * xr - ai * xi + bur, nxi = ar * xi + ai * xr + bui; xr = nxr; xi = nxi;
;                 if (PASS == 2) { xb[s * 132 + lane] = xr; xb[s * 132 + 64 + lane] = xi; }
;             }
	v_pk_fma_f32 v[68:69], v[4:5], v[52:53], 0 op_sel_hi:[1,0,0]
	s_nop 0
	v_pk_fma_f32 v[52:53], v[6:7], v[52:53], v[68:69] op_sel:[0,1,0]
	v_mov_b32_e32 v48, v55
	v_pk_fma_f32 v[52:53], v[8:9], v[54:55], v[52:53] op_sel_hi:[1,0,1]
	v_pk_mul_f32 v[54:55], v[40:41], v[42:43] op_sel:[0,1]
	v_pk_fma_f32 v[52:53], v[10:11], v[48:49], v[52:53] op_sel_hi:[1,0,1]
	s_waitcnt lgkmcnt(2)
	v_mov_b32_e32 v48, v59
	v_pk_fma_f32 v[52:53], v[12:13], v[56:57], v[52:53] op_sel_hi:[1,0,1]
	s_nop 0
	v_pk_fma_f32 v[52:53], v[14:15], v[56:57], v[52:53] op_sel:[0,1,0]
	v_pk_fma_f32 v[56:57], v[38:39], v[42:43], v[54:55] neg_lo:[0,0,1] neg_hi:[0,0,1]
	v_pk_fma_f32 v[52:53], v[0:1], v[58:59], v[52:53] op_sel_hi:[1,0,1]
	v_pk_fma_f32 v[42:43], v[38:39], v[42:43], v[54:55] op_sel_hi:[1,0,1]
	v_pk_fma_f32 v[52:53], v[2:3], v[48:49], v[52:53] op_sel_hi:[1,0,1]
	s_waitcnt lgkmcnt(1)
	v_mov_b32_e32 v48, v63
	v_pk_fma_f32 v[70:71], v[16:17], v[60:61], 0 op_sel_hi:[1,0,0]
	v_mov_b32_e32 v57, v43
	v_pk_fma_f32 v[70:71], v[18:19], v[60:61], v[70:71] op_sel:[0,1,0]
	s_nop 0
	v_pk_fma_f32 v[70:71], v[20:21], v[62:63], v[70:71] op_sel_hi:[1,0,1]
	s_nop 0
	v_pk_fma_f32 v[70:71], v[22:23], v[48:49], v[70:71] op_sel_hi:[1,0,1]
	s_waitcnt lgkmcnt(0)
	v_mov_b32_e32 v48, v67
	v_pk_fma_f32 v[70:71], v[24:25], v[64:65], v[70:71] op_sel_hi:[1,0,1]
	s_nop 0
	v_pk_fma_f32 v[70:71], v[26:27], v[64:65], v[70:71] op_sel:[0,1,0]
	s_nop 0
	v_pk_fma_f32 v[70:71], v[28:29], v[66:67], v[70:71] op_sel_hi:[1,0,1]
	s_nop 0
	v_pk_fma_f32 v[70:71], v[30:31], v[48:49], v[70:71] op_sel_hi:[1,0,1]
	s_nop 0
	v_pk_add_f32 v[52:53], v[52:53], v[70:71]
	s_nop 0
	v_pk_add_f32 v[42:43], v[56:57], v[52:53]
	ds_read_b128 v[52:55], v45 offset:128
	ds_read_b128 v[56:59], v45 offset:144
	ds_read_b128 v[60:63], v45 offset:160
	ds_read_b128 v[64:67], v45 offset:176
	s_waitcnt lgkmcnt(3)
	v_pk_fma_f32 v[68:69], v[4:5], v[52:53], 0 op_sel_hi:[1,0,0]
	s_nop 0
	v_pk_fma_f32 v[52:53], v[6:7], v[52:53], v[68:69] op_sel:[0,1,0]
	v_mov_b32_e32 v48, v55
	v_pk_fma_f32 v[52:53], v[8:9], v[54:55], v[52:53] op_sel_hi:[1,0,1]
	v_pk_mul_f32 v[54:55], v[40:41], v[42:43] op_sel:[0,1]
	v_pk_fma_f32 v[52:53], v[10:11], v[48:49], v[52:53] op_sel_hi:[1,0,1]
	s_waitcnt lgkmcnt(2)
	v_mov_b32_e32 v48, v59
	v_pk_fma_f32 v[52:53], v[12:13], v[56:57], v[52:53] op_sel_hi:[1,0,1]
	s_nop 0
	v_pk_fma_f32 v[52:53], v[14:15], v[56:57], v[52:53] op_sel:[0,1,0]
	v_pk_fma_f32 v[56:57], v[38:39], v[42:43], v[54:55] neg_lo:[0,0,1] neg_hi:[0,0,1]
	v_pk_fma_f32 v[52:53], v[0:1], v[58:59], v[52:53] op_sel_hi:[1,0,1]
	v_pk_fma_f32 v[42:43], v[38:39], v[42:43], v[54:55] op_sel_hi:[1,0,1]
	v_pk_fma_f32 v[52:53], v[2:3], v[48:49], v[52:53] op_sel_hi:[1,0,1]
	s_waitcnt lgkmcnt(1)
	v_mov_b32_e32 v48, v63
	v_pk_fma_f32 v[70:71], v[16:17], v[60:61], 0 op_sel_hi:[1,0,0]
	v_mov_b32_e32 v57, v43
	v_pk_fma_f32 v[70:71], v[18:19], v[60:61], v[70:71] op_sel:[0,1,0]
	s_nop 0
	v_pk_fma_f32 v[70:71], v[20:21], v[62:63], v[70:71] op_sel_hi:[1,0,1]
	s_nop 0
	v_pk_fma_f32 v[70:71], v[22:23], v[48:49], v[70:71] op_sel_hi:[1,0,1]
	s_waitcnt lgkmcnt(0)
	v_mov_b32_e32 v48, v67
	v_pk_fma_f32 v[70:71], v[24:25], v[64:65], v[70:71] op_sel_hi:[1,0,1]
	s_nop 0
	v_pk_fma_f32 v[70:71], v[26:27], v[64:65], v[70:71] op_sel:[0,1,0]
	s_nop 0
	v_pk_fma_f32 v[70:71], v[28:29], v[66:67], v[70:71] op_sel_hi:[1,0,1]
	s_nop 0
	v_pk_fma_f32 v[70:71], v[30:31], v[48:49], v[70:71] op_sel_hi:[1,0,1]
	s_nop 0
	v_pk_add_f32 v[52:53], v[52:53], v[70:71]
	s_nop 0
	v_pk_add_f32 v[42:43], v[56:57], v[52:53]
	ds_read_b128 v[52:55], v45 offset:192
	ds_read_b128 v[56:59], v45 offset:208
	ds_read_b128 v[60:63], v45 offset:224
	ds_read_b128 v[64:67], v45 offset:240
	s_waitcnt lgkmcnt(3)
	v_pk_fma_f32 v[68:69], v[4:5], v[52:53], 0 op_sel_hi:[1,0,0]
	s_nop 0
	v_pk_fma_f32 v[52:53], v[6:7], v[52:53], v[68:69] op_sel:[0,1,0]
	v_mov_b32_e32 v48, v55
	v_pk_fma_f32 v[52:53], v[8:9], v[54:55], v[52:53] op_sel_hi:[1,0,1]
	v_pk_mul_f32 v[54:55], v[40:41], v[42:43] op_sel:[0,1]
	v_pk_fma_f32 v[52:53], v[10:11], v[48:49], v[52:53] op_sel_hi:[1,0,1]
	s_waitcnt lgkmcnt(2)
	v_mov_b32_e32 v48, v59
	v_pk_fma_f32 v[52:53], v[12:13], v[56:57], v[52:53] op_sel_hi:[1,0,1]
	s_nop 0
	v_pk_fma_f32 v[52:53], v[14:15], v[56:57], v[52:53] op_sel:[0,1,0]
	v_pk_fma_f32 v[56:57], v[38:39], v[42:43], v[54:55] neg_lo:[0,0,1] neg_hi:[0,0,1]
	v_pk_fma_f32 v[52:53], v[0:1], v[58:59], v[52:53] op_sel_hi:[1,0,1]
	v_pk_fma_f32 v[42:43], v[38:39], v[42:43], v[54:55] op_sel_hi:[1,0,1]
	v_pk_fma_f32 v[52:53], v[2:3], v[48:49], v[52:53] op_sel_hi:[1,0,1]
	s_waitcnt lgkmcnt(1)
	v_mov_b32_e32 v48, v63
	v_pk_fma_f32 v[70:71], v[16:17], v[60:61], 0 op_sel_hi:[1,0,0]
	v_mov_b32_e32 v57, v43
	v_pk_fma_f32 v[70:71], v[18:19], v[60:61], v[70:71] op_sel:[0,1,0]
	s_nop 0
	v_pk_fma_f32 v[70:71], v[20:21], v[62:63], v[70:71] op_sel_hi:[1,0,1]
	s_nop 0
	v_pk_fma_f32 v[70:71], v[22:23], v[48:49], v[70:71] op_sel_hi:[1,0,1]
	s_waitcnt lgkmcnt(0)
	v_mov_b32_e32 v48, v67
	v_pk_fma_f32 v[70:71], v[24:25], v[64:65], v[70:71] op_sel_hi:[1,0,1]
	s_nop 0
	v_pk_fma_f32 v[70:71], v[26:27], v[64:65], v[70:71] op_sel:[0,1,0]
	s_nop 0
	v_pk_fma_f32 v[70:71], v[28:29], v[66:67], v[70:71] op_sel_hi:[1,0,1]
	s_nop 0
	v_pk_fma_f32 v[70:71], v[30:31], v[48:49], v[70:71] op_sel_hi:[1,0,1]
	s_nop 0
	v_pk_add_f32 v[52:53], v[52:53], v[70:71]
	s_nop 0
	v_pk_add_f32 v[42:43], v[56:57], v[52:53]
	s_cbranch_scc1 .LBB0_406
	s_waitcnt vmcnt(0)
	ds_write_b128 v51, v[32:35]
	v_or_b32_e32 v32, 0x90, v44
	v_ashrrev_i32_e32 v33, 31, v32
	v_lshlrev_b64 v[32:33], 11, v[32:33]
	v_lshl_add_u64 v[32:33], v[46:47], 0, v[32:33]
	global_load_dwordx4 v[32:35], v[32:33], off
	s_waitcnt lgkmcnt(0)
	s_mov_b32 s7, 0
; #define LAS __attribute__((address_space(3)))
; #define WAVE_SYNC() asm volatile("s_waitcnt lgkmcnt(0)" ::: "memory")
; template <int PASS>
; __device__ __forceinline__ void s5_scan(const Params& p, int l, int widx, int nw, int beff, int nblk, int lane, LAS unsigned char* lds) {
;     ...
;         for (int bt = 0; bt < 16; ++bt) {
;             LAS float* ubc = ub + (bt & 1) * 256;
;             *(LAS f32x4*)(ubc + lane * 4) = un;
;             if (bt + 1 < 16) un = *(const f32x4*)(ZS + (size_t)(m0 + (bt + 1) * 16 + (lane >> 2)) * 512 + g * 16 + (lane & 3) * 4);
;             WAVE_SYNC();
; #pragma unroll 4
;             for (int s = 0; s < 16; ++s) {
;                 const f32x4 u0 = *(LAS f32x4*)(ubc + s * 16), u1 = *(LAS f32x4*)(ubc + s * 16 + 4), u2 = *(LAS f32x4*)(ubc + s * 16 + 8), u3 = *(LAS f32x4*)(ubc + s * 16 + 12);
;                 float bur = 0.f, bui = 0.f;
; #pragma unroll
;                 for (int j = 0; j < 4; ++j) { bur += br[j] * u0[j]; bui += bi[j] * u0[j]; }
; #pragma unroll
;                 for (int j = 0; j < 4; ++j) { bur += br[4 + j] * u1[j]; bui += bi[4 + j] * u1[j]; }
; #pragma unroll
;                 for (int j = 0; j < 4; ++j) { bur += br[8 + j] * u2[j]; bui += bi[8 + j] * u2[j]; }
; #pragma unroll
;                 for (int j = 0; j < 4; ++j) { bur += br[12 + j] * u3[j]; bui += bi[12 + j] * u3[j]; }
;                 const float nxr = ar * xr - ai * xi + bur, nxi = ar * xi + ai * xr + bui; xr = nxr; xi = nxi;
.LBB0_408:
	s_add_i32 s8, s5, s7
	v_mov_b32_e32 v45, s8
	ds_read_b128 v[52:55], v45
	ds_read_b128 v[56:59], v45 offset:16
	ds_read_b128 v[60:63], v45 offset:32
	ds_read_b128 v[64:67], v45 offset:48
	s_addk_i32 s7, 0x100
	s_waitcnt lgkmcnt(3)
	v_pk_fma_f32 v[68:69], v[4:5], v[52:53], 0 op_sel_hi:[1,0,0]
	v_mov_b32_e32 v48, v55
	v_pk_fma_f32 v[52:53], v[6:7], v[52:53], v[68:69] op_sel:[0,1,0]
	s_cmpk_lg_i32 s7, 0x400
	v_pk_fma_f32 v[52:53], v[8:9], v[54:55], v[52:53] op_sel_hi:[1,0,1]
	v_pk_mul_f32 v[54:55], v[40:41], v[42:43] op_sel:[0,1]
	v_pk_fma_f32 v[52:53], v[10:11], v[48:49], v[52:53] op_sel_hi:[1,0,1]
	s_waitcnt lgkmcnt(2)
	v_mov_b32_e32 v48, v59
	v_pk_fma_f32 v[52:53], v[12:13], v[56:57], v[52:53] op_sel_hi:[1,0,1]
	s_nop 0
	v_pk_fma_f32 v[52:53], v[14:15], v[56:57], v[52:53] op_sel:[0,1,0]
	v_pk_fma_f32 v[56:57], v[38:39], v[42:43], v[54:55] neg_lo:[0,0,1] neg_hi:[0,0,1]
	v_pk_fma_f32 v[52:53], v[0:1], v[58:59], v[52:53] op_sel_hi:[1,0,1]
	v_pk_fma_f32 v[42:43], v[38:39], v[42:43], v[54:55] op_sel_hi:[1,0,1]
	v_pk_fma_f32 v[52:53], v[2:3], v[48:49], v[52:53] op_sel_hi:[1,0,1]
	s_waitcnt lgkmcnt(1)
	v_mov_b32_e32 v48, v63
	v_pk_fma_f32 v[70:71], v[16:17], v[60:61], 0 op_sel_hi:[1,0,0]
	v_mov_b32_e32 v57, v43
	v_pk_fma_f32 v[70:71], v[18:19], v[60:61], v[70:71] op_sel:[0,1,0]
	s_nop 0
	v_pk_fma_f32 v[70:71], v[20:21], v[62:63], v[70:71] op_sel_hi:[1,0,1]
	s_nop 0
	v_pk_fma_f32 v[70:71], v[22:23], v[48:49], v[70:71] op_sel_hi:[1,0,1]
	s_waitcnt lgkmcnt(0)
	v_mov_b32_e32 v48, v67
	v_pk_fma_f32 v[70:71], v[24:25], v[64:65], v[70:71] op_sel_hi:[1,0,1]
	s_nop 0
	v_pk_fma_f32 v[70:71], v[26:27], v[64:65], v[70:71] op_sel:[0,1,0]
	s_nop 0
	v_pk_fma_f32 v[70:71], v[28:29], v[66:67], v[70:71] op_sel_hi:[1,0,1]
	s_nop 0
	v_pk_fma_f32 v[70:71], v[30:31], v[48:49], v[70:71] op_sel_hi:[1,0,1]
	s_nop 0
	v_pk_add_f32 v[52:53], v[52:53], v[70:71]
	s_nop 0
	v_pk_add_f32 v[42:43], v[56:57], v[52:53]
	ds_read_b128 v[52:55], v45 offset:64
	ds_read_b128 v[56:59], v45 offset:80
	ds_read_b128 v[60:63], v45 offset:96
	ds_read_b128 v[64:67], v45 offset:112
	s_waitcnt lgkmcnt(3)
	v_pk_fma_f32 v[68:69], v[4:5], v[52:53], 0 op_sel_hi:[1,0,0]
	s_nop 0
	v_pk_fma_f32 v[52:53], v[6:7], v[52:53], v[68:69] op_sel:[0,1,0]
	v_mov_b32_e32 v48, v55
	v_pk_fma_f32 v[52:53], v[8:9], v[54:55], v[52:53] op_sel_hi:[1,0,1]
	v_pk_mul_f32 v[54:55], v[40:41], v[42:43] op_sel:[0,1]
	v_pk_fma_f32 v[52:53], v[10:11], v[48:49], v[52:53] op_sel_hi:[1,0,1]
	s_waitcnt lgkmcnt(2)
	v_mov_b32_e32 v48, v59
	v_pk_fma_f32 v[52:53], v[12:13], v[56:57], v[52:53] op_sel_hi:[1,0,1]
	s_nop 0
	v_pk_fma_f32 v[52:53], v[14:15], v[56:57], v[52:53] op_sel:[0,1,0]
	v_pk_fma_f32 v[56:57], v[38:39], v[42:43], v[54:55] neg_lo:[0,0,1] neg_hi:[0,0,1]
	v_pk_fma_f32 v[52:53], v[0:1], v[58:59], v[52:53] op_sel_hi:[1,0,1]
	v_pk_fma_f32 v[42:43], v[38:39], v[42:43], v[54:55] op_sel_hi:[1,0,1]
	v_pk_fma_f32 v[52:53], v[2:3], v[48:49], v[52:53] op_sel_hi:[1,0,1]
	s_waitcnt lgkmcnt(1)
	v_mov_b32_e32 v48, v63
	v_pk_fma_f32 v[70:71], v[16:17], v[60:61], 0 op_sel_hi:[1,0,0]
	v_mov_b32_e32 v57, v43
	v_pk_fma_f32 v[70:71], v[18:19], v[60:61], v[70:71] op_sel:[0,1,0]
	s_nop 0
	v_pk_fma_f32 v[70:71], v[20:21], v[62:63], v[70:71] op_sel_hi:[1,0,1]
	s_nop 0
	v_pk_fma_f32 v[70:71], v[22:23], v[48:49], v[70:71] op_sel_hi:[1,0,1]
	s_waitcnt lgkmcnt(0)
	v_mov_b32_e32 v48, v67
	v_pk_fma_f32 v[70:71], v[24:25], v[64:65], v[70:71] op_sel_hi:[1,0,1]
	s_nop 0
	v_pk_fma_f32 v[70:71], v[26:27], v[64:65], v[70:71] op_sel:[0,1,0]
	s_nop 0
	v_pk_fma_f32 v[70:71], v[28:29], v[66:67], v[70:71] op_sel_hi:[1,0,1]
	s_nop 0
	v_pk_fma_f32 v[70:71], v[30:31], v[48:49], v[70:71] op_sel_hi:[1,0,1]
	s_nop 0
	v_pk_add_f32 v[52:53], v[52:53], v[70:71]
	s_nop 0
	v_pk_add_f32 v[42:43], v[56:57], v[52:53]
	ds_read_b128 v[52:55], v45 offset:128
	ds_read_b128 v[56:59], v45 offset:144
	ds_read_b128 v[60:63], v45 offset:160
	ds_read_b128 v[64:67], v45 offset:176
	s_waitcnt lgkmcnt(3)
	v_pk_fma_f32 v[68:69], v[4:5], v[52:53], 0 op_sel_hi:[1,0,0]
	s_nop 0
	v_pk_fma_f32 v[52:53], v[6:7], v[52:53], v[68:69] op_sel:[0,1,0]
	v_mov_b32_e32 v48, v55
	v_pk_fma_f32 v[52:53], v[8:9], v[54:55], v[52:53] op_sel_hi:[1,0,1]
	v_pk_mul_f32 v[54:55], v[40:41], v[42:43] op_sel:[0,1]
	v_pk_fma_f32 v[52:53], v[10:11], v[48:49], v[52:53] op_sel_hi:[1,0,1]
	s_waitcnt lgkmcnt(2)
	v_mov_b32_e32 v48, v59
	v_pk_fma_f32 v[52:53], v[12:13], v[56:57], v[52:53] op_sel_hi:[1,0,1]
	s_nop 0
	v_pk_fma_f32 v[52:53], v[14:15], v[56:57], v[52:53] op_sel:[0,1,0]
	v_pk_fma_f32 v[56:57], v[38:39], v[42:43], v[54:55] neg_lo:[0,0,1] neg_hi:[0,0,1]
	v_pk_fma_f32 v[52:53], v[0:1], v[58:59], v[52:53] op_sel_hi:[1,0,1]
	v_pk_fma_f32 v[42:43], v[38:39], v[42:43], v[54:55] op_sel_hi:[1,0,1]
	v_pk_fma_f32 v[52:53], v[2:3], v[48:49], v[52:53] op_sel_hi:[1,0,1]
	s_waitcnt lgkmcnt(1)
	v_mov_b32_e32 v48, v63
	v_pk_fma_f32 v[70:71], v[16:17], v[60:61], 0 op_sel_hi:[1,0,0]
	v_mov_b32_e32 v57, v43
	v_pk_fma_f32 v[70:71], v[18:19], v[60:61], v[70:71] op_sel:[0,1,0]
	s_nop 0
	v_pk_fma_f32 v[70:71], v[20:21], v[62:63], v[70:71] op_sel_hi:[1,0,1]
	s_nop 0
	v_pk_fma_f32 v[70:71], v[22:23], v[48:49], v[70:71] op_sel_hi:[1,0,1]
	s_waitcnt lgkmcnt(0)
	v_mov_b32_e32 v48, v67
	v_pk_fma_f32 v[70:71], v[24:25], v[64:65], v[70:71] op_sel_hi:[1,0,1]
	s_nop 0
	v_pk_fma_f32 v[70:71], v[26:27], v[64:65], v[70:71] op_sel:[0,1,0]
	s_nop 0
	v_pk_fma_f32 v[70:71], v[28:29], v[66:67], v[70:71] op_sel_hi:[1,0,1]
	s_nop 0
	v_pk_fma_f32 v[70:71], v[30:31], v[48:49], v[70:71] op_sel_hi:[1,0,1]
	s_nop 0
	v_pk_add_f32 v[52:53], v[52:53], v[70:71]
	s_nop 0
	v_pk_add_f32 v[42:43], v[56:57], v[52:53]
	ds_read_b128 v[52:55], v45 offset:192
	ds_read_b128 v[56:59], v45 offset:208
	ds_read_b128 v[60:63], v45 offset:224
	ds_read_b128 v[64:67], v45 offset:240
	s_waitcnt lgkmcnt(3)
; #define LAS __attribute__((address_space(3)))
; #define WAVE_SYNC() asm volatile("s_waitcnt lgkmcnt(0)" ::: "memory")
; template <int PASS>
; __device__ __forceinline__ void s5_scan(const Params& p, int l, int widx, int nw, int beff, int nblk, int lane, LAS unsigned char* lds) {
;     ...
;         for (int bt = 0; bt < 16; ++bt) {
;             LAS float* ubc = ub + (bt & 1) * 256;
;             *(LAS f32x4*)(ubc + lane * 4) = un;
;             if (bt + 1 < 16) un = *(const f32x4*)(ZS + (size_t)(m0 + (bt + 1) * 16 + (lane >> 2)) * 512 + g * 16 + (lane & 3) * 4);
;             WAVE_SYNC();
; #pragma unroll 4
;             for (int s = 0; s < 16; ++s) {
;                 const f32x4 u0 = *(LAS f32x4*)(ubc + s * 16), u1 = *(LAS f32x4*)(ubc + s * 16 + 4), u2 = *(LAS f32x4*)(ubc + s * 16 + 8), u3 = *(LAS f32x4*)(ubc + s * 16 + 12);
;                 float bur = 0.f, bui = 0.f;
; #pragma unroll
;                 for (int j = 0; j < 4; ++j) { bur += br[j] * u0[j]; bui += bi[j] * u0[j]; }
; #pragma unroll
;                 for (int j = 0; j < 4; ++j) { bur += br[4 + j] * u1[j]; bui += bi[4 + j] * u1[j]; }
; #pragma unroll
;                 for (int j = 0; j < 4; ++j) { bur += br[8 + j] * u2[j]; bui += bi[8 + j] * u2[j]; }
; #pragma unroll
;                 for (int j = 0; j < 4; ++j) { bur += br[12 + j] * u3[j]; bui += bi[12 + j] * u3[j]; }
;                 const float nxr = ar * xr - ai * xi + bur, nxi = ar * xi + ai * xr + bui; xr = nxr; xi = nxi;
	v_pk_fma_f32 v[68:69], v[4:5], v[52:53], 0 op_sel_hi:[1,0,0]
	s_nop 0
	v_pk_fma_f32 v[52:53], v[6:7], v[52:53], v[68:69] op_sel:[0,1,0]
	v_mov_b32_e32 v48, v55
	v_pk_fma_f32 v[52:53], v[8:9], v[54:55], v[52:53] op_sel_hi:[1,0,1]
	v_pk_mul_f32 v[54:55], v[40:41], v[42:43] op_sel:[0,1]
	v_pk_fma_f32 v[52:53], v[10:11], v[48:49], v[52:53] op_sel_hi:[1,0,1]
	s_waitcnt lgkmcnt(2)
	v_mov_b32_e32 v48, v59
	v_pk_fma_f32 v[52:53], v[12:13], v[56:57], v[52:53] op_sel_hi:[1,0,1]
	s_nop 0
	v_pk_fma_f32 v[52:53], v[14:15], v[56:57], v[52:53] op_sel:[0,1,0]
	v_pk_fma_f32 v[56:57], v[38:39], v[42:43], v[54:55] neg_lo:[0,0,1] neg_hi:[0,0,1]
	v_pk_fma_f32 v[52:53], v[0:1], v[58:59], v[52:53] op_sel_hi:[1,0,1]
	v_pk_fma_f32 v[42:43], v[38:39], v[42:43], v[54:55] op_sel_hi:[1,0,1]
	v_pk_fma_f32 v[52:53], v[2:3], v[48:49], v[52:53] op_sel_hi:[1,0,1]
	s_waitcnt lgkmcnt(1)
	v_mov_b32_e32 v48, v63
	v_pk_fma_f32 v[70:71], v[16:17], v[60:61], 0 op_sel_hi:[1,0,0]
	v_mov_b32_e32 v57, v43
	v_pk_fma_f32 v[70:71], v[18:19], v[60:61], v[70:71] op_sel:[0,1,0]
	s_nop 0
	v_pk_fma_f32 v[70:71], v[20:21], v[62:63], v[70:71] op_sel_hi:[1,0,1]
	s_nop 0
	v_pk_fma_f32 v[70:71], v[22:23], v[48:49], v[70:71] op_sel_hi:[1,0,1]
	s_waitcnt lgkmcnt(0)
	v_mov_b32_e32 v48, v67
	v_pk_fma_f32 v[70:71], v[24:25], v[64:65], v[70:71] op_sel_hi:[1,0,1]
	s_nop 0
	v_pk_fma_f32 v[70:71], v[26:27], v[64:65], v[70:71] op_sel:[0,1,0]
	s_nop 0
	v_pk_fma_f32 v[70:71], v[28:29], v[66:67], v[70:71] op_sel_hi:[1,0,1]
	s_nop 0
	v_pk_fma_f32 v[70:71], v[30:31], v[48:49], v[70:71] op_sel_hi:[1,0,1]
	s_nop 0
	v_pk_add_f32 v[52:53], v[52:53], v[70:71]
	s_nop 0
	v_pk_add_f32 v[42:43], v[56:57], v[52:53]
	s_cbranch_scc1 .LBB0_408
	s_waitcnt vmcnt(0)
	ds_write_b128 v51, v[32:35] offset:1024
	v_or_b32_e32 v32, 0xa0, v44
	v_ashrrev_i32_e32 v33, 31, v32
	v_lshlrev_b64 v[32:33], 11, v[32:33]
	v_lshl_add_u64 v[32:33], v[46:47], 0, v[32:33]
	global_load_dwordx4 v[32:35], v[32:33], off
	s_waitcnt lgkmcnt(0)
	s_mov_b32 s7, 0
.LBB0_410:
	s_add_i32 s8, s6, s7
	v_mov_b32_e32 v45, s8
	ds_read_b128 v[52:55], v45
	ds_read_b128 v[56:59], v45 offset:16
	ds_read_b128 v[60:63], v45 offset:32
	ds_read_b128 v[64:67], v45 offset:48
	s_addk_i32 s7, 0x100
	s_waitcnt lgkmcnt(3)
	v_pk_fma_f32 v[68:69], v[4:5], v[52:53], 0 op_sel_hi:[1,0,0]
	v_mov_b32_e32 v48, v55
	v_pk_fma_f32 v[52:53], v[6:7], v[52:53], v[68:69] op_sel:[0,1,0]
	s_cmpk_lg_i32 s7, 0x400
	v_pk_fma_f32 v[52:53], v[8:9], v[54:55], v[52:53] op_sel_hi:[1,0,1]
	v_pk_mul_f32 v[54:55], v[40:41], v[42:43] op_sel:[0,1]
	v_pk_fma_f32 v[52:53], v[10:11], v[48:49], v[52:53] op_sel_hi:[1,0,1]
	s_waitcnt lgkmcnt(2)
	v_mov_b32_e32 v48, v59
	v_pk_fma_f32 v[52:53], v[12:13], v[56:57], v[52:53] op_sel_hi:[1,0,1]
	s_nop 0
	v_pk_fma_f32 v[52:53], v[14:15], v[56:57], v[52:53] op_sel:[0,1,0]
	v_pk_fma_f32 v[56:57], v[38:39], v[42:43], v[54:55] neg_lo:[0,0,1] neg_hi:[0,0,1]
	v_pk_fma_f32 v[52:53], v[0:1], v[58:59], v[52:53] op_sel_hi:[1,0,1]
	v_pk_fma_f32 v[42:43], v[38:39], v[42:43], v[54:55] op_sel_hi:[1,0,1]
	v_pk_fma_f32 v[52:53], v[2:3], v[48:49], v[52:53] op_sel_hi:[1,0,1]
	s_waitcnt lgkmcnt(1)
	v_mov_b32_e32 v48, v63
	v_pk_fma_f32 v[70:71], v[16:17], v[60:61], 0 op_sel_hi:[1,0,0]
	v_mov_b32_e32 v57, v43
	v_pk_fma_f32 v[70:71], v[18:19], v[60:61], v[70:71] op_sel:[0,1,0]
	s_nop 0
	v_pk_fma_f32 v[70:71], v[20:21], v[62:63], v[70:71] op_sel_hi:[1,0,1]
	s_nop 0
	v_pk_fma_f32 v[70:71], v[22:23], v[48:49], v[70:71] op_sel_hi:[1,0,1]
	s_waitcnt lgkmcnt(0)
	v_mov_b32_e32 v48, v67
	v_pk_fma_f32 v[70:71], v[24:25], v[64:65], v[70:71] op_sel_hi:[1,0,1]
	s_nop 0
	v_pk_fma_f32 v[70:71], v[26:27], v[64:65], v[70:71] op_sel:[0,1,0]
	s_nop 0
	v_pk_fma_f32 v[70:71], v[28:29], v[66:67], v[70:71] op_sel_hi:[1,0,1]
	s_nop 0
	v_pk_fma_f32 v[70:71], v[30:31], v[48:49], v[70:71] op_sel_hi:[1,0,1]
	s_nop 0
	v_pk_add_f32 v[52:53], v[52:53], v[70:71]
	s_nop 0
	v_pk_add_f32 v[42:43], v[56:57], v[52:53]
	ds_read_b128 v[52:55], v45 offset:64
	ds_read_b128 v[56:59], v45 offset:80
	ds_read_b128 v[60:63], v45 offset:96
	ds_read_b128 v[64:67], v45 offset:112
	s_waitcnt lgkmcnt(3)
	v_pk_fma_f32 v[68:69], v[4:5], v[52:53], 0 op_sel_hi:[1,0,0]
	s_nop 0
	v_pk_fma_f32 v[52:53], v[6:7], v[52:53], v[68:69] op_sel:[0,1,0]
	v_mov_b32_e32 v48, v55
	v_pk_fma_f32 v[52:53], v[8:9], v[54:55], v[52:53] op_sel_hi:[1,0,1]
	v_pk_mul_f32 v[54:55], v[40:41], v[42:43] op_sel:[0,1]
	v_pk_fma_f32 v[52:53], v[10:11], v[48:49], v[52:53] op_sel_hi:[1,0,1]
	s_waitcnt lgkmcnt(2)
	v_mov_b32_e32 v48, v59
	v_pk_fma_f32 v[52:53], v[12:13], v[56:57], v[52:53] op_sel_hi:[1,0,1]
	s_nop 0
	v_pk_fma_f32 v[52:53], v[14:15], v[56:57], v[52:53] op_sel:[0,1,0]
	v_pk_fma_f32 v[56:57], v[38:39], v[42:43], v[54:55] neg_lo:[0,0,1] neg_hi:[0,0,1]
	v_pk_fma_f32 v[52:53], v[0:1], v[58:59], v[52:53] op_sel_hi:[1,0,1]
	v_pk_fma_f32 v[42:43], v[38:39], v[42:43], v[54:55] op_sel_hi:[1,0,1]
	v_pk_fma_f32 v[52:53], v[2:3], v[48:49], v[52:53] op_sel_hi:[1,0,1]
	s_waitcnt lgkmcnt(1)
	v_mov_b32_e32 v48, v63
	v_pk_fma_f32 v[70:71], v[16:17], v[60:61], 0 op_sel_hi:[1,0,0]
	v_mov_b32_e32 v57, v43
	v_pk_fma_f32 v[70:71], v[18:19], v[60:61], v[70:71] op_sel:[0,1,0]
	s_nop 0
	v_pk_fma_f32 v[70:71], v[20:21], v[62:63], v[70:71] op_sel_hi:[1,0,1]
	s_nop 0
	v_pk_fma_f32 v[70:71], v[22:23], v[48:49], v[70:71] op_sel_hi:[1,0,1]
	s_waitcnt lgkmcnt(0)
	v_mov_b32_e32 v48, v67
	v_pk_fma_f32 v[70:71], v[24:25], v[64:65], v[70:71] op_sel_hi:[1,0,1]
	s_nop 0
	v_pk_fma_f32 v[70:71], v[26:27], v[64:65], v[70:71] op_sel:[0,1,0]
	s_nop 0
	v_pk_fma_f32 v[70:71], v[28:29], v[66:67], v[70:71] op_sel_hi:[1,0,1]
	s_nop 0
	v_pk_fma_f32 v[70:71], v[30:31], v[48:49], v[70:71] op_sel_hi:[1,0,1]
	s_nop 0
	v_pk_add_f32 v[52:53], v[52:53], v[70:71]
	s_nop 0
	v_pk_add_f32 v[42:43], v[56:57], v[52:53]
	ds_read_b128 v[52:55], v45 offset:128
	ds_read_b128 v[56:59], v45 offset:144
	ds_read_b128 v[60:63], v45 offset:160
	ds_read_b128 v[64:67], v45 offset:176
	s_waitcnt lgkmcnt(3)
; #define LAS __attribute__((address_space(3)))
; #define WAVE_SYNC() asm volatile("s_waitcnt lgkmcnt(0)" ::: "memory")
; template <int PASS>
; __device__ __forceinline__ void s5_scan(const Params& p, int l, int widx, int nw, int beff, int nblk, int lane, LAS unsigned char* lds) {
;     ...
;         for (int bt = 0; bt < 16; ++bt) {
;             LAS float* ubc = ub + (bt & 1) * 256;
;             *(LAS f32x4*)(ubc + lane * 4) = un;
;             if (bt + 1 < 16) un = *(const f32x4*)(ZS + (size_t)(m0 + (bt + 1) * 16 + (lane >> 2)) * 512 + g * 16 + (lane & 3) * 4);
;             WAVE_SYNC();
; #pragma unroll 4
;             for (int s = 0; s < 16; ++s) {
;                 const f32x4 u0 = *(LAS f32x4*)(ubc + s * 16), u1 = *(LAS f32x4*)(ubc + s * 16 + 4), u2 = *(LAS f32x4*)(ubc + s * 16 + 8), u3 = *(LAS f32x4*)(ubc + s * 16 + 12);
;                 float bur = 0.f, bui = 0.f;
; #pragma unroll
;                 for (int j = 0; j < 4; ++j) { bur += br[j] * u0[j]; bui += bi[j] * u0[j]; }
; #pragma unroll
;                 for (int j = 0; j < 4; ++j) { bur += br[4 + j] * u1[j]; bui += bi[4 + j] * u1[j]; }
; #pragma unroll
;                 for (int j = 0; j < 4; ++j) { bur += br[8 + j] * u2[j]; bui += bi[8 + j] * u2[j]; }
; #pragma unroll
;                 for (int j = 0; j < 4; ++j) { bur += br[12 + j] * u3[j]; bui += bi[12 + j] * u3[j]; }
;                 const float nxr = ar * xr - ai * xi + bur, nxi = ar * xi + ai * xr + bui; xr = nxr; xi = nxi;
	v_pk_fma_f32 v[68:69], v[4:5], v[52:53], 0 op_sel_hi:[1,0,0]
	s_nop 0
	v_pk_fma_f32 v[52:53], v[6:7], v[52:53], v[68:69] op_sel:[0,1,0]
	v_mov_b32_e32 v48, v55
	v_pk_fma_f32 v[52:53], v[8:9], v[54:55], v[52:53] op_sel_hi:[1,0,1]
	v_pk_mul_f32 v[54:55], v[40:41], v[42:43] op_sel:[0,1]
	v_pk_fma_f32 v[52:53], v[10:11], v[48:49], v[52:53] op_sel_hi:[1,0,1]
	s_waitcnt lgkmcnt(2)
	v_mov_b32_e32 v48, v59
	v_pk_fma_f32 v[52:53], v[12:13], v[56:57], v[52:53] op_sel_hi:[1,0,1]
	s_nop 0
	v_pk_fma_f32 v[52:53], v[14:15], v[56:57], v[52:53] op_sel:[0,1,0]
	v_pk_fma_f32 v[56:57], v[38:39], v[42:43], v[54:55] neg_lo:[0,0,1] neg_hi:[0,0,1]
	v_pk_fma_f32 v[52:53], v[0:1], v[58:59], v[52:53] op_sel_hi:[1,0,1]
	v_pk_fma_f32 v[42:43], v[38:39], v[42:43], v[54:55] op_sel_hi:[1,0,1]
	v_pk_fma_f32 v[52:53], v[2:3], v[48:49], v[52:53] op_sel_hi:[1,0,1]
	s_waitcnt lgkmcnt(1)
	v_mov_b32_e32 v48, v63
	v_pk_fma_f32 v[70:71], v[16:17], v[60:61], 0 op_sel_hi:[1,0,0]
	v_mov_b32_e32 v57, v43
	v_pk_fma_f32 v[70:71], v[18:19], v[60:61], v[70:71] op_sel:[0,1,0]
	s_nop 0
	v_pk_fma_f32 v[70:71], v[20:21], v[62:63], v[70:71] op_sel_hi:[1,0,1]
	s_nop 0
	v_pk_fma_f32 v[70:71], v[22:23], v[48:49], v[70:71] op_sel_hi:[1,0,1]
	s_waitcnt lgkmcnt(0)
	v_mov_b32_e32 v48, v67
	v_pk_fma_f32 v[70:71], v[24:25], v[64:65], v[70:71] op_sel_hi:[1,0,1]
	s_nop 0
	v_pk_fma_f32 v[70:71], v[26:27], v[64:65], v[70:71] op_sel:[0,1,0]
	s_nop 0
	v_pk_fma_f32 v[70:71], v[28:29], v[66:67], v[70:71] op_sel_hi:[1,0,1]
	s_nop 0
	v_pk_fma_f32 v[70:71], v[30:31], v[48:49], v[70:71] op_sel_hi:[1,0,1]
	s_nop 0
	v_pk_add_f32 v[52:53], v[52:53], v[70:71]
	s_nop 0
	v_pk_add_f32 v[42:43], v[56:57], v[52:53]
	ds_read_b128 v[52:55], v45 offset:192
	ds_read_b128 v[56:59], v45 offset:208
	ds_read_b128 v[60:63], v45 offset:224
	ds_read_b128 v[64:67], v45 offset:240
	s_waitcnt lgkmcnt(3)
	v_pk_fma_f32 v[68:69], v[4:5], v[52:53], 0 op_sel_hi:[1,0,0]
	s_nop 0
	v_pk_fma_f32 v[52:53], v[6:7], v[52:53], v[68:69] op_sel:[0,1,0]
	v_mov_b32_e32 v48, v55
	v_pk_fma_f32 v[52:53], v[8:9], v[54:55], v[52:53] op_sel_hi:[1,0,1]
	v_pk_mul_f32 v[54:55], v[40:41], v[42:43] op_sel:[0,1]
	v_pk_fma_f32 v[52:53], v[10:11], v[48:49], v[52:53] op_sel_hi:[1,0,1]
	s_waitcnt lgkmcnt(2)
	v_mov_b32_e32 v48, v59
	v_pk_fma_f32 v[52:53], v[12:13], v[56:57], v[52:53] op_sel_hi:[1,0,1]
	s_nop 0
	v_pk_fma_f32 v[52:53], v[14:15], v[56:57], v[52:53] op_sel:[0,1,0]
	v_pk_fma_f32 v[56:57], v[38:39], v[42:43], v[54:55] neg_lo:[0,0,1] neg_hi:[0,0,1]
	v_pk_fma_f32 v[52:53], v[0:1], v[58:59], v[52:53] op_sel_hi:[1,0,1]
	v_pk_fma_f32 v[42:43], v[38:39], v[42:43], v[54:55] op_sel_hi:[1,0,1]
	v_pk_fma_f32 v[52:53], v[2:3], v[48:49], v[52:53] op_sel_hi:[1,0,1]
	s_waitcnt lgkmcnt(1)
	v_mov_b32_e32 v48, v63
	v_pk_fma_f32 v[70:71], v[16:17], v[60:61], 0 op_sel_hi:[1,0,0]
	v_mov_b32_e32 v57, v43
	v_pk_fma_f32 v[70:71], v[18:19], v[60:61], v[70:71] op_sel:[0,1,0]
	s_nop 0
	v_pk_fma_f32 v[70:71], v[20:21], v[62:63], v[70:71] op_sel_hi:[1,0,1]
	s_nop 0
	v_pk_fma_f32 v[70:71], v[22:23], v[48:49], v[70:71] op_sel_hi:[1,0,1]
	s_waitcnt lgkmcnt(0)
	v_mov_b32_e32 v48, v67
	v_pk_fma_f32 v[70:71], v[24:25], v[64:65], v[70:71] op_sel_hi:[1,0,1]
	s_nop 0
	v_pk_fma_f32 v[70:71], v[26:27], v[64:65], v[70:71] op_sel:[0,1,0]
	s_nop 0
	v_pk_fma_f32 v[70:71], v[28:29], v[66:67], v[70:71] op_sel_hi:[1,0,1]
	s_nop 0
	v_pk_fma_f32 v[70:71], v[30:31], v[48:49], v[70:71] op_sel_hi:[1,0,1]
	s_nop 0
	v_pk_add_f32 v[52:53], v[52:53], v[70:71]
	s_nop 0
	v_pk_add_f32 v[42:43], v[56:57], v[52:53]
	s_cbranch_scc1 .LBB0_410
	s_waitcnt vmcnt(0)
	ds_write_b128 v51, v[32:35]
	v_or_b32_e32 v32, 0xb0, v44
	v_ashrrev_i32_e32 v33, 31, v32
	v_lshlrev_b64 v[32:33], 11, v[32:33]
	v_lshl_add_u64 v[32:33], v[46:47], 0, v[32:33]
	global_load_dwordx4 v[32:35], v[32:33], off
	s_waitcnt lgkmcnt(0)
	s_mov_b32 s7, 0
.LBB0_412:
	s_add_i32 s8, s5, s7
	v_mov_b32_e32 v45, s8
	ds_read_b128 v[52:55], v45
	ds_read_b128 v[56:59], v45 offset:16
	ds_read_b128 v[60:63], v45 offset:32
	ds_read_b128 v[64:67], v45 offset:48
	s_addk_i32 s7, 0x100
	s_waitcnt lgkmcnt(3)
	v_pk_fma_f32 v[68:69], v[4:5], v[52:53], 0 op_sel_hi:[1,0,0]
	v_mov_b32_e32 v48, v55
	v_pk_fma_f32 v[52:53], v[6:7], v[52:53], v[68:69] op_sel:[0,1,0]
	s_cmpk_lg_i32 s7, 0x400
	v_pk_fma_f32 v[52:53], v[8:9], v[54:55], v[52:53] op_sel_hi:[1,0,1]
	v_pk_mul_f32 v[54:55], v[40:41], v[42:43] op_sel:[0,1]
	v_pk_fma_f32 v[52:53], v[10:11], v[48:49], v[52:53] op_sel_hi:[1,0,1]
	s_waitcnt lgkmcnt(2)
	v_mov_b32_e32 v48, v59
	v_pk_fma_f32 v[52:53], v[12:13], v[56:57], v[52:53] op_sel_hi:[1,0,1]
	s_nop 0
	v_pk_fma_f32 v[52:53], v[14:15], v[56:57], v[52:53] op_sel:[0,1,0]
	v_pk_fma_f32 v[56:57], v[38:39], v[42:43], v[54:55] neg_lo:[0,0,1] neg_hi:[0,0,1]
	v_pk_fma_f32 v[52:53], v[0:1], v[58:59], v[52:53] op_sel_hi:[1,0,1]
	v_pk_fma_f32 v[42:43], v[38:39], v[42:43], v[54:55] op_sel_hi:[1,0,1]
	v_pk_fma_f32 v[52:53], v[2:3], v[48:49], v[52:53] op_sel_hi:[1,0,1]
	s_waitcnt lgkmcnt(1)
	v_mov_b32_e32 v48, v63
	v_pk_fma_f32 v[70:71], v[16:17], v[60:61], 0 op_sel_hi:[1,0,0]
	v_mov_b32_e32 v57, v43
	v_pk_fma_f32 v[70:71], v[18:19], v[60:61], v[70:71] op_sel:[0,1,0]
	s_nop 0
	v_pk_fma_f32 v[70:71], v[20:21], v[62:63], v[70:71] op_sel_hi:[1,0,1]
	s_nop 0
	v_pk_fma_f32 v[70:71], v[22:23], v[48:49], v[70:71] op_sel_hi:[1,0,1]
	s_waitcnt lgkmcnt(0)
	v_mov_b32_e32 v48, v67
	v_pk_fma_f32 v[70:71], v[24:25], v[64:65], v[70:71] op_sel_hi:[1,0,1]
	s_nop 0
	v_pk_fma_f32 v[70:71], v[26:27], v[64:65], v[70:71] op_sel:[0,1,0]
	s_nop 0
	v_pk_fma_f32 v[70:71], v[28:29], v[66:67], v[70:71] op_sel_hi:[1,0,1]
	s_nop 0
	v_pk_fma_f32 v[70:71], v[30:31], v[48:49], v[70:71] op_sel_hi:[1,0,1]
	s_nop 0
	v_pk_add_f32 v[52:53], v[52:53], v[70:71]
	s_nop 0
	v_pk_add_f32 v[42:43], v[56:57], v[52:53]
	ds_read_b128 v[52:55], v45 offset:64
	ds_read_b128 v[56:59], v45 offset:80
	ds_read_b128 v[60:63], v45 offset:96
	ds_read_b128 v[64:67], v45 offset:112
	s_waitcnt lgkmcnt(3)
; #define LAS __attribute__((address_space(3)))
; #define WAVE_SYNC() asm volatile("s_waitcnt lgkmcnt(0)" ::: "memory")
; template <int PASS>
; __device__ __forceinline__ void s5_scan(const Params& p, int l, int widx, int nw, int beff, int nblk, int lane, LAS unsigned char* lds) {
;     ...
;         for (int bt = 0; bt < 16; ++bt) {
;             LAS float* ubc = ub + (bt & 1) * 256;
;             *(LAS f32x4*)(ubc + lane * 4) = un;
;             if (bt + 1 < 16) un = *(const f32x4*)(ZS + (size_t)(m0 + (bt + 1) * 16 + (lane >> 2)) * 512 + g * 16 + (lane & 3) * 4);
;             WAVE_SYNC();
; #pragma unroll 4
;             for (int s = 0; s < 16; ++s) {
;                 const f32x4 u0 = *(LAS f32x4*)(ubc + s * 16), u1 = *(LAS f32x4*)(ubc + s * 16 + 4), u2 = *(LAS f32x4*)(ubc + s * 16 + 8), u3 = *(LAS f32x4*)(ubc + s * 16 + 12);
;                 float bur = 0.f, bui = 0.f;
; #pragma unroll
;                 for (int j = 0; j < 4; ++j) { bur += br[j] * u0[j]; bui += bi[j] * u0[j]; }
; #pragma unroll
;                 for (int j = 0; j < 4; ++j) { bur += br[4 + j] * u1[j]; bui += bi[4 + j] * u1[j]; }
; #pragma unroll
;                 for (int j = 0; j < 4; ++j) { bur += br[8 + j] * u2[j]; bui += bi[8 + j] * u2[j]; }
; #pragma unroll
;                 for (int j = 0; j < 4; ++j) { bur += br[12 + j] * u3[j]; bui += bi[12 + j] * u3[j]; }
;                 const float nxr = ar * xr - ai * xi + bur, nxi = ar * xi + ai * xr + bui; xr = nxr; xi = nxi;
	v_pk_fma_f32 v[68:69], v[4:5], v[52:53], 0 op_sel_hi:[1,0,0]
	s_nop 0
	v_pk_fma_f32 v[52:53], v[6:7], v[52:53], v[68:69] op_sel:[0,1,0]
	v_mov_b32_e32 v48, v55
	v_pk_fma_f32 v[52:53], v[8:9], v[54:55], v[52:53] op_sel_hi:[1,0,1]
	v_pk_mul_f32 v[54:55], v[40:41], v[42:43] op_sel:[0,1]
	v_pk_fma_f32 v[52:53], v[10:11], v[48:49], v[52:53] op_sel_hi:[1,0,1]
	s_waitcnt lgkmcnt(2)
	v_mov_b32_e32 v48, v59
	v_pk_fma_f32 v[52:53], v[12:13], v[56:57], v[52:53] op_sel_hi:[1,0,1]
	s_nop 0
	v_pk_fma_f32 v[52:53], v[14:15], v[56:57], v[52:53] op_sel:[0,1,0]
	v_pk_fma_f32 v[56:57], v[38:39], v[42:43], v[54:55] neg_lo:[0,0,1] neg_hi:[0,0,1]
	v_pk_fma_f32 v[52:53], v[0:1], v[58:59], v[52:53] op_sel_hi:[1,0,1]
	v_pk_fma_f32 v[42:43], v[38:39], v[42:43], v[54:55] op_sel_hi:[1,0,1]
	v_pk_fma_f32 v[52:53], v[2:3], v[48:49], v[52:53] op_sel_hi:[1,0,1]
	s_waitcnt lgkmcnt(1)
	v_mov_b32_e32 v48, v63
	v_pk_fma_f32 v[70:71], v[16:17], v[60:61], 0 op_sel_hi:[1,0,0]
	v_mov_b32_e32 v57, v43
	v_pk_fma_f32 v[70:71], v[18:19], v[60:61], v[70:71] op_sel:[0,1,0]
	s_nop 0
	v_pk_fma_f32 v[70:71], v[20:21], v[62:63], v[70:71] op_sel_hi:[1,0,1]
	s_nop 0
	v_pk_fma_f32 v[70:71], v[22:23], v[48:49], v[70:71] op_sel_hi:[1,0,1]
	s_waitcnt lgkmcnt(0)
	v_mov_b32_e32 v48, v67
	v_pk_fma_f32 v[70:71], v[24:25], v[64:65], v[70:71] op_sel_hi:[1,0,1]
	s_nop 0
	v_pk_fma_f32 v[70:71], v[26:27], v[64:65], v[70:71] op_sel:[0,1,0]
	s_nop 0
	v_pk_fma_f32 v[70:71], v[28:29], v[66:67], v[70:71] op_sel_hi:[1,0,1]
	s_nop 0
	v_pk_fma_f32 v[70:71], v[30:31], v[48:49], v[70:71] op_sel_hi:[1,0,1]
	s_nop 0
	v_pk_add_f32 v[52:53], v[52:53], v[70:71]
	s_nop 0
	v_pk_add_f32 v[42:43], v[56:57], v[52:53]
	ds_read_b128 v[52:55], v45 offset:128
	ds_read_b128 v[56:59], v45 offset:144
	ds_read_b128 v[60:63], v45 offset:160
	ds_read_b128 v[64:67], v45 offset:176
	s_waitcnt lgkmcnt(3)
	v_pk_fma_f32 v[68:69], v[4:5], v[52:53], 0 op_sel_hi:[1,0,0]
	s_nop 0
	v_pk_fma_f32 v[52:53], v[6:7], v[52:53], v[68:69] op_sel:[0,1,0]
	v_mov_b32_e32 v48, v55
	v_pk_fma_f32 v[52:53], v[8:9], v[54:55], v[52:53] op_sel_hi:[1,0,1]
	v_pk_mul_f32 v[54:55], v[40:41], v[42:43] op_sel:[0,1]
	v_pk_fma_f32 v[52:53], v[10:11], v[48:49], v[52:53] op_sel_hi:[1,0,1]
	s_waitcnt lgkmcnt(2)
	v_mov_b32_e32 v48, v59
	v_pk_fma_f32 v[52:53], v[12:13], v[56:57], v[52:53] op_sel_hi:[1,0,1]
	s_nop 0
	v_pk_fma_f32 v[52:53], v[14:15], v[56:57], v[52:53] op_sel:[0,1,0]
	v_pk_fma_f32 v[56:57], v[38:39], v[42:43], v[54:55] neg_lo:[0,0,1] neg_hi:[0,0,1]
	v_pk_fma_f32 v[52:53], v[0:1], v[58:59], v[52:53] op_sel_hi:[1,0,1]
	v_pk_fma_f32 v[42:43], v[38:39], v[42:43], v[54:55] op_sel_hi:[1,0,1]
	v_pk_fma_f32 v[52:53], v[2:3], v[48:49], v[52:53] op_sel_hi:[1,0,1]
	s_waitcnt lgkmcnt(1)
	v_mov_b32_e32 v48, v63
	v_pk_fma_f32 v[70:71], v[16:17], v[60:61], 0 op_sel_hi:[1,0,0]
	v_mov_b32_e32 v57, v43
	v_pk_fma_f32 v[70:71], v[18:19], v[60:61], v[70:71] op_sel:[0,1,0]
	s_nop 0
	v_pk_fma_f32 v[70:71], v[20:21], v[62:63], v[70:71] op_sel_hi:[1,0,1]
	s_nop 0
	v_pk_fma_f32 v[70:71], v[22:23], v[48:49], v[70:71] op_sel_hi:[1,0,1]
	s_waitcnt lgkmcnt(0)
	v_mov_b32_e32 v48, v67
	v_pk_fma_f32 v[70:71], v[24:25], v[64:65], v[70:71] op_sel_hi:[1,0,1]
	s_nop 0
	v_pk_fma_f32 v[70:71], v[26:27], v[64:65], v[70:71] op_sel:[0,1,0]
	s_nop 0
	v_pk_fma_f32 v[70:71], v[28:29], v[66:67], v[70:71] op_sel_hi:[1,0,1]
	s_nop 0
	v_pk_fma_f32 v[70:71], v[30:31], v[48:49], v[70:71] op_sel_hi:[1,0,1]
	s_nop 0
	v_pk_add_f32 v[52:53], v[52:53], v[70:71]
	s_nop 0
	v_pk_add_f32 v[42:43], v[56:57], v[52:53]
	ds_read_b128 v[52:55], v45 offset:192
	ds_read_b128 v[56:59], v45 offset:208
	ds_read_b128 v[60:63], v45 offset:224
	ds_read_b128 v[64:67], v45 offset:240
	s_waitcnt lgkmcnt(3)
	v_pk_fma_f32 v[68:69], v[4:5], v[52:53], 0 op_sel_hi:[1,0,0]
	s_nop 0
	v_pk_fma_f32 v[52:53], v[6:7], v[52:53], v[68:69] op_sel:[0,1,0]
	v_mov_b32_e32 v48, v55
	v_pk_fma_f32 v[52:53], v[8:9], v[54:55], v[52:53] op_sel_hi:[1,0,1]
	v_pk_mul_f32 v[54:55], v[40:41], v[42:43] op_sel:[0,1]
	v_pk_fma_f32 v[52:53], v[10:11], v[48:49], v[52:53] op_sel_hi:[1,0,1]
	s_waitcnt lgkmcnt(2)
	v_mov_b32_e32 v48, v59
	v_pk_fma_f32 v[52:53], v[12:13], v[56:57], v[52:53] op_sel_hi:[1,0,1]
	s_nop 0
	v_pk_fma_f32 v[52:53], v[14:15], v[56:57], v[52:53] op_sel:[0,1,0]
	v_pk_fma_f32 v[56:57], v[38:39], v[42:43], v[54:55] neg_lo:[0,0,1] neg_hi:[0,0,1]
	v_pk_fma_f32 v[52:53], v[0:1], v[58:59], v[52:53] op_sel_hi:[1,0,1]
	v_pk_fma_f32 v[42:43], v[38:39], v[42:43], v[54:55] op_sel_hi:[1,0,1]
	v_pk_fma_f32 v[52:53], v[2:3], v[48:49], v[52:53] op_sel_hi:[1,0,1]
	s_waitcnt lgkmcnt(1)
	v_mov_b32_e32 v48, v63
	v_pk_fma_f32 v[70:71], v[16:17], v[60:61], 0 op_sel_hi:[1,0,0]
	v_mov_b32_e32 v57, v43
	v_pk_fma_f32 v[70:71], v[18:19], v[60:61], v[70:71] op_sel:[0,1,0]
	s_nop 0
	v_pk_fma_f32 v[70:71], v[20:21], v[62:63], v[70:71] op_sel_hi:[1,0,1]
	s_nop 0
	v_pk_fma_f32 v[70:71], v[22:23], v[48:49], v[70:71] op_sel_hi:[1,0,1]
	s_waitcnt lgkmcnt(0)
	v_mov_b32_e32 v48, v67
	v_pk_fma_f32 v[70:71], v[24:25], v[64:65], v[70:71] op_sel_hi:[1,0,1]
	s_nop 0
	v_pk_fma_f32 v[70:71], v[26:27], v[64:65], v[70:71] op_sel:[0,1,0]
	s_nop 0
	v_pk_fma_f32 v[70:71], v[28:29], v[66:67], v[70:71] op_sel_hi:[1,0,1]
	s_nop 0
	v_pk_fma_f32 v[70:71], v[30:31], v[48:49], v[70:71] op_sel_hi:[1,0,1]
	s_nop 0
	v_pk_add_f32 v[52:53], v[52:53], v[70:71]
	s_nop 0
	v_pk_add_f32 v[42:43], v[56:57], v[52:53]
	s_cbranch_scc1 .LBB0_412
	s_waitcnt vmcnt(0)
	ds_write_b128 v51, v[32:35] offset:1024
	v_or_b32_e32 v32, 0xc0, v44
	v_ashrrev_i32_e32 v33, 31, v32
	v_lshlrev_b64 v[32:33], 11, v[32:33]
	v_lshl_add_u64 v[32:33], v[46:47], 0, v[32:33]
	global_load_dwordx4 v[32:35], v[32:33], off
	s_waitcnt lgkmcnt(0)
	s_mov_b32 s7, 0
; #define LAS __attribute__((address_space(3)))
; #define WAVE_SYNC() asm volatile("s_waitcnt lgkmcnt(0)" ::: "memory")
; template <int PASS>
; __device__ __forceinline__ void s5_scan(const Params& p, int l, int widx, int nw, int beff, int nblk, int lane, LAS unsigned char* lds) {
;     ...
;         for (int bt = 0; bt < 16; ++bt) {
;             LAS float* ubc = ub + (bt & 1) * 256;
;             *(LAS f32x4*)(ubc + lane * 4) = un;
;             if (bt + 1 < 16) un = *(const f32x4*)(ZS + (size_t)(m0 + (bt + 1) * 16 + (lane >> 2)) * 512 + g * 16 + (lane & 3) * 4);
;             WAVE_SYNC();
; #pragma unroll 4
;             for (int s = 0; s < 16; ++s) {
;                 const f32x4 u0 = *(LAS f32x4*)(ubc + s * 16), u1 = *(LAS f32x4*)(ubc + s * 16 + 4), u2 = *(LAS f32x4*)(ubc + s * 16 + 8), u3 = *(LAS f32x4*)(ubc + s * 16 + 12);
;                 float bur = 0.f, bui = 0.f;
; #pragma unroll
;                 for (int j = 0; j < 4; ++j) { bur += br[j] * u0[j]; bui += bi[j] * u0[j]; }
; #pragma unroll
;                 for (int j = 0; j < 4; ++j) { bur += br[4 + j] * u1[j]; bui += bi[4 + j] * u1[j]; }
; #pragma unroll
;                 for (int j = 0; j < 4; ++j) { bur += br[8 + j] * u2[j]; bui += bi[8 + j] * u2[j]; }
; #pragma unroll
;                 for (int j = 0; j < 4; ++j) { bur += br[12 + j] * u3[j]; bui += bi[12 + j] * u3[j]; }
;                 const float nxr = ar * xr - ai * xi + bur, nxi = ar * xi + ai * xr + bui; xr = nxr; xi = nxi;
.LBB0_414:
	s_add_i32 s8, s6, s7
	v_mov_b32_e32 v45, s8
	ds_read_b128 v[52:55], v45
	ds_read_b128 v[56:59], v45 offset:16
	ds_read_b128 v[60:63], v45 offset:32
	ds_read_b128 v[64:67], v45 offset:48
	s_addk_i32 s7, 0x100
	s_waitcnt lgkmcnt(3)
	v_pk_fma_f32 v[68:69], v[4:5], v[52:53], 0 op_sel_hi:[1,0,0]
	v_mov_b32_e32 v48, v55
	v_pk_fma_f32 v[52:53], v[6:7], v[52:53], v[68:69] op_sel:[0,1,0]
	s_cmpk_lg_i32 s7, 0x400
	v_pk_fma_f32 v[52:53], v[8:9], v[54:55], v[52:53] op_sel_hi:[1,0,1]
	v_pk_mul_f32 v[54:55], v[40:41], v[42:43] op_sel:[0,1]
	v_pk_fma_f32 v[52:53], v[10:11], v[48:49], v[52:53] op_sel_hi:[1,0,1]
	s_waitcnt lgkmcnt(2)
	v_mov_b32_e32 v48, v59
	v_pk_fma_f32 v[52:53], v[12:13], v[56:57], v[52:53] op_sel_hi:[1,0,1]
	s_nop 0
	v_pk_fma_f32 v[52:53], v[14:15], v[56:57], v[52:53] op_sel:[0,1,0]
	v_pk_fma_f32 v[56:57], v[38:39], v[42:43], v[54:55] neg_lo:[0,0,1] neg_hi:[0,0,1]
	v_pk_fma_f32 v[52:53], v[0:1], v[58:59], v[52:53] op_sel_hi:[1,0,1]
	v_pk_fma_f32 v[42:43], v[38:39], v[42:43], v[54:55] op_sel_hi:[1,0,1]
	v_pk_fma_f32 v[52:53], v[2:3], v[48:49], v[52:53] op_sel_hi:[1,0,1]
	s_waitcnt lgkmcnt(1)
	v_mov_b32_e32 v48, v63
	v_pk_fma_f32 v[70:71], v[16:17], v[60:61], 0 op_sel_hi:[1,0,0]
	v_mov_b32_e32 v57, v43
	v_pk_fma_f32 v[70:71], v[18:19], v[60:61], v[70:71] op_sel:[0,1,0]
	s_nop 0
	v_pk_fma_f32 v[70:71], v[20:21], v[62:63], v[70:71] op_sel_hi:[1,0,1]
	s_nop 0
	v_pk_fma_f32 v[70:71], v[22:23], v[48:49], v[70:71] op_sel_hi:[1,0,1]
	s_waitcnt lgkmcnt(0)
	v_mov_b32_e32 v48, v67
	v_pk_fma_f32 v[70:71], v[24:25], v[64:65], v[70:71] op_sel_hi:[1,0,1]
	s_nop 0
	v_pk_fma_f32 v[70:71], v[26:27], v[64:65], v[70:71] op_sel:[0,1,0]
	s_nop 0
	v_pk_fma_f32 v[70:71], v[28:29], v[66:67], v[70:71] op_sel_hi:[1,0,1]
	s_nop 0
	v_pk_fma_f32 v[70:71], v[30:31], v[48:49], v[70:71] op_sel_hi:[1,0,1]
	s_nop 0
	v_pk_add_f32 v[52:53], v[52:53], v[70:71]
	s_nop 0
	v_pk_add_f32 v[42:43], v[56:57], v[52:53]
	ds_read_b128 v[52:55], v45 offset:64
	ds_read_b128 v[56:59], v45 offset:80
	ds_read_b128 v[60:63], v45 offset:96
	ds_read_b128 v[64:67], v45 offset:112
	s_waitcnt lgkmcnt(3)
	v_pk_fma_f32 v[68:69], v[4:5], v[52:53], 0 op_sel_hi:[1,0,0]
	s_nop 0
	v_pk_fma_f32 v[52:53], v[6:7], v[52:53], v[68:69] op_sel:[0,1,0]
	v_mov_b32_e32 v48, v55
	v_pk_fma_f32 v[52:53], v[8:9], v[54:55], v[52:53] op_sel_hi:[1,0,1]
	v_pk_mul_f32 v[54:55], v[40:41], v[42:43] op_sel:[0,1]
	v_pk_fma_f32 v[52:53], v[10:11], v[48:49], v[52:53] op_sel_hi:[1,0,1]
	s_waitcnt lgkmcnt(2)
	v_mov_b32_e32 v48, v59
	v_pk_fma_f32 v[52:53], v[12:13], v[56:57], v[52:53] op_sel_hi:[1,0,1]
	s_nop 0
	v_pk_fma_f32 v[52:53], v[14:15], v[56:57], v[52:53] op_sel:[0,1,0]
	v_pk_fma_f32 v[56:57], v[38:39], v[42:43], v[54:55] neg_lo:[0,0,1] neg_hi:[0,0,1]
	v_pk_fma_f32 v[52:53], v[0:1], v[58:59], v[52:53] op_sel_hi:[1,0,1]
	v_pk_fma_f32 v[42:43], v[38:39], v[42:43], v[54:55] op_sel_hi:[1,0,1]
	v_pk_fma_f32 v[52:53], v[2:3], v[48:49], v[52:53] op_sel_hi:[1,0,1]
	s_waitcnt lgkmcnt(1)
	v_mov_b32_e32 v48, v63
	v_pk_fma_f32 v[70:71], v[16:17], v[60:61], 0 op_sel_hi:[1,0,0]
	v_mov_b32_e32 v57, v43
	v_pk_fma_f32 v[70:71], v[18:19], v[60:61], v[70:71] op_sel:[0,1,0]
	s_nop 0
	v_pk_fma_f32 v[70:71], v[20:21], v[62:63], v[70:71] op_sel_hi:[1,0,1]
	s_nop 0
	v_pk_fma_f32 v[70:71], v[22:23], v[48:49], v[70:71] op_sel_hi:[1,0,1]
	s_waitcnt lgkmcnt(0)
	v_mov_b32_e32 v48, v67
	v_pk_fma_f32 v[70:71], v[24:25], v[64:65], v[70:71] op_sel_hi:[1,0,1]
	s_nop 0
	v_pk_fma_f32 v[70:71], v[26:27], v[64:65], v[70:71] op_sel:[0,1,0]
	s_nop 0
	v_pk_fma_f32 v[70:71], v[28:29], v[66:67], v[70:71] op_sel_hi:[1,0,1]
	s_nop 0
	v_pk_fma_f32 v[70:71], v[30:31], v[48:49], v[70:71] op_sel_hi:[1,0,1]
	s_nop 0
	v_pk_add_f32 v[52:53], v[52:53], v[70:71]
	s_nop 0
	v_pk_add_f32 v[42:43], v[56:57], v[52:53]
	ds_read_b128 v[52:55], v45 offset:128
	ds_read_b128 v[56:59], v45 offset:144
	ds_read_b128 v[60:63], v45 offset:160
	ds_read_b128 v[64:67], v45 offset:176
	s_waitcnt lgkmcnt(3)
	v_pk_fma_f32 v[68:69], v[4:5], v[52:53], 0 op_sel_hi:[1,0,0]
	s_nop 0
	v_pk_fma_f32 v[52:53], v[6:7], v[52:53], v[68:69] op_sel:[0,1,0]
	v_mov_b32_e32 v48, v55
	v_pk_fma_f32 v[52:53], v[8:9], v[54:55], v[52:53] op_sel_hi:[1,0,1]
	v_pk_mul_f32 v[54:55], v[40:41], v[42:43] op_sel:[0,1]
	v_pk_fma_f32 v[52:53], v[10:11], v[48:49], v[52:53] op_sel_hi:[1,0,1]
	s_waitcnt lgkmcnt(2)
	v_mov_b32_e32 v48, v59
	v_pk_fma_f32 v[52:53], v[12:13], v[56:57], v[52:53] op_sel_hi:[1,0,1]
	s_nop 0
	v_pk_fma_f32 v[52:53], v[14:15], v[56:57], v[52:53] op_sel:[0,1,0]
	v_pk_fma_f32 v[56:57], v[38:39], v[42:43], v[54:55] neg_lo:[0,0,1] neg_hi:[0,0,1]
	v_pk_fma_f32 v[52:53], v[0:1], v[58:59], v[52:53] op_sel_hi:[1,0,1]
	v_pk_fma_f32 v[42:43], v[38:39], v[42:43], v[54:55] op_sel_hi:[1,0,1]
	v_pk_fma_f32 v[52:53], v[2:3], v[48:49], v[52:53] op_sel_hi:[1,0,1]
	s_waitcnt lgkmcnt(1)
	v_mov_b32_e32 v48, v63
	v_pk_fma_f32 v[70:71], v[16:17], v[60:61], 0 op_sel_hi:[1,0,0]
	v_mov_b32_e32 v57, v43
	v_pk_fma_f32 v[70:71], v[18:19], v[60:61], v[70:71] op_sel:[0,1,0]
	s_nop 0
	v_pk_fma_f32 v[70:71], v[20:21], v[62:63], v[70:71] op_sel_hi:[1,0,1]
	s_nop 0
	v_pk_fma_f32 v[70:71], v[22:23], v[48:49], v[70:71] op_sel_hi:[1,0,1]
	s_waitcnt lgkmcnt(0)
	v_mov_b32_e32 v48, v67
	v_pk_fma_f32 v[70:71], v[24:25], v[64:65], v[70:71] op_sel_hi:[1,0,1]
	s_nop 0
	v_pk_fma_f32 v[70:71], v[26:27], v[64:65], v[70:71] op_sel:[0,1,0]
	s_nop 0
	v_pk_fma_f32 v[70:71], v[28:29], v[66:67], v[70:71] op_sel_hi:[1,0,1]
	s_nop 0
	v_pk_fma_f32 v[70:71], v[30:31], v[48:49], v[70:71] op_sel_hi:[1,0,1]
	s_nop 0
	v_pk_add_f32 v[52:53], v[52:53], v[70:71]
	s_nop 0
	v_pk_add_f32 v[42:43], v[56:57], v[52:53]
	ds_read_b128 v[52:55], v45 offset:192
	ds_read_b128 v[56:59], v45 offset:208
	ds_read_b128 v[60:63], v45 offset:224
	ds_read_b128 v[64:67], v45 offset:240
	s_waitcnt lgkmcnt(3)
; #define LAS __attribute__((address_space(3)))
; #define WAVE_SYNC() asm volatile("s_waitcnt lgkmcnt(0)" ::: "memory")
; template <int PASS>
; __device__ __forceinline__ void s5_scan(const Params& p, int l, int widx, int nw, int beff, int nblk, int lane, LAS unsigned char* lds) {
;     ...
;         for (int bt = 0; bt < 16; ++bt) {
;             LAS float* ubc = ub + (bt & 1) * 256;
;             *(LAS f32x4*)(ubc + lane * 4) = un;
;             if (bt + 1 < 16) un = *(const f32x4*)(ZS + (size_t)(m0 + (bt + 1) * 16 + (lane >> 2)) * 512 + g * 16 + (lane & 3) * 4);
;             WAVE_SYNC();
; #pragma unroll 4
;             for (int s = 0; s < 16; ++s) {
;                 const f32x4 u0 = *(LAS f32x4*)(ubc + s * 16), u1 = *(LAS f32x4*)(ubc + s * 16 + 4), u2 = *(LAS f32x4*)(ubc + s * 16 + 8), u3 = *(LAS f32x4*)(ubc + s * 16 + 12);
;                 float bur = 0.f, bui = 0.f;
; #pragma unroll
;                 for (int j = 0; j < 4; ++j) { bur += br[j] * u0[j]; bui += bi[j] * u0[j]; }
; #pragma unroll
;                 for (int j = 0; j < 4; ++j) { bur += br[4 + j] * u1[j]; bui += bi[4 + j] * u1[j]; }
; #pragma unroll
;                 for (int j = 0; j < 4; ++j) { bur += br[8 + j] * u2[j]; bui += bi[8 + j] * u2[j]; }
; #pragma unroll
;                 for (int j = 0; j < 4; ++j) { bur += br[12 + j] * u3[j]; bui += bi[12 + j] * u3[j]; }
;                 const float nxr = ar * xr - ai * xi + bur, nxi = ar * xi + ai * xr + bui; xr = nxr; xi = nxi;
	v_pk_fma_f32 v[68:69], v[4:5], v[52:53], 0 op_sel_hi:[1,0,0]
	s_nop 0
	v_pk_fma_f32 v[52:53], v[6:7], v[52:53], v[68:69] op_sel:[0,1,0]
	v_mov_b32_e32 v48, v55
	v_pk_fma_f32 v[52:53], v[8:9], v[54:55], v[52:53] op_sel_hi:[1,0,1]
	v_pk_mul_f32 v[54:55], v[40:41], v[42:43] op_sel:[0,1]
	v_pk_fma_f32 v[52:53], v[10:11], v[48:49], v[52:53] op_sel_hi:[1,0,1]
	s_waitcnt lgkmcnt(2)
	v_mov_b32_e32 v48, v59
	v_pk_fma_f32 v[52:53], v[12:13], v[56:57], v[52:53] op_sel_hi:[1,0,1]
	s_nop 0
	v_pk_fma_f32 v[52:53], v[14:15], v[56:57], v[52:53] op_sel:[0,1,0]
	v_pk_fma_f32 v[56:57], v[38:39], v[42:43], v[54:55] neg_lo:[0,0,1] neg_hi:[0,0,1]
	v_pk_fma_f32 v[52:53], v[0:1], v[58:59], v[52:53] op_sel_hi:[1,0,1]
	v_pk_fma_f32 v[42:43], v[38:39], v[42:43], v[54:55] op_sel_hi:[1,0,1]
	v_pk_fma_f32 v[52:53], v[2:3], v[48:49], v[52:53] op_sel_hi:[1,0,1]
	s_waitcnt lgkmcnt(1)
	v_mov_b32_e32 v48, v63
	v_pk_fma_f32 v[70:71], v[16:17], v[60:61], 0 op_sel_hi:[1,0,0]
	v_mov_b32_e32 v57, v43
	v_pk_fma_f32 v[70:71], v[18:19], v[60:61], v[70:71] op_sel:[0,1,0]
	s_nop 0
	v_pk_fma_f32 v[70:71], v[20:21], v[62:63], v[70:71] op_sel_hi:[1,0,1]
	s_nop 0
	v_pk_fma_f32 v[70:71], v[22:23], v[48:49], v[70:71] op_sel_hi:[1,0,1]
	s_waitcnt lgkmcnt(0)
	v_mov_b32_e32 v48, v67
	v_pk_fma_f32 v[70:71], v[24:25], v[64:65], v[70:71] op_sel_hi:[1,0,1]
	s_nop 0
	v_pk_fma_f32 v[70:71], v[26:27], v[64:65], v[70:71] op_sel:[0,1,0]
	s_nop 0
	v_pk_fma_f32 v[70:71], v[28:29], v[66:67], v[70:71] op_sel_hi:[1,0,1]
	s_nop 0
	v_pk_fma_f32 v[70:71], v[30:31], v[48:49], v[70:71] op_sel_hi:[1,0,1]
	s_nop 0
	v_pk_add_f32 v[52:53], v[52:53], v[70:71]
	s_nop 0
	v_pk_add_f32 v[42:43], v[56:57], v[52:53]
	s_cbranch_scc1 .LBB0_414
	s_waitcnt vmcnt(0)
	ds_write_b128 v51, v[32:35]
	v_or_b32_e32 v32, 0xd0, v44
	v_ashrrev_i32_e32 v33, 31, v32
	v_lshlrev_b64 v[32:33], 11, v[32:33]
	v_lshl_add_u64 v[32:33], v[46:47], 0, v[32:33]
	global_load_dwordx4 v[32:35], v[32:33], off
	s_waitcnt lgkmcnt(0)
	s_mov_b32 s7, 0
.LBB0_416:
	s_add_i32 s8, s5, s7
	v_mov_b32_e32 v45, s8
	ds_read_b128 v[52:55], v45
	ds_read_b128 v[56:59], v45 offset:16
	ds_read_b128 v[60:63], v45 offset:32
	ds_read_b128 v[64:67], v45 offset:48
	s_addk_i32 s7, 0x100
	s_waitcnt lgkmcnt(3)
	v_pk_fma_f32 v[68:69], v[4:5], v[52:53], 0 op_sel_hi:[1,0,0]
	v_mov_b32_e32 v48, v55
	v_pk_fma_f32 v[52:53], v[6:7], v[52:53], v[68:69] op_sel:[0,1,0]
	s_cmpk_lg_i32 s7, 0x400
	v_pk_fma_f32 v[52:53], v[8:9], v[54:55], v[52:53] op_sel_hi:[1,0,1]
	v_pk_mul_f32 v[54:55], v[40:41], v[42:43] op_sel:[0,1]
	v_pk_fma_f32 v[52:53], v[10:11], v[48:49], v[52:53] op_sel_hi:[1,0,1]
	s_waitcnt lgkmcnt(2)
	v_mov_b32_e32 v48, v59
	v_pk_fma_f32 v[52:53], v[12:13], v[56:57], v[52:53] op_sel_hi:[1,0,1]
	s_nop 0
	v_pk_fma_f32 v[52:53], v[14:15], v[56:57], v[52:53] op_sel:[0,1,0]
	v_pk_fma_f32 v[56:57], v[38:39], v[42:43], v[54:55] neg_lo:[0,0,1] neg_hi:[0,0,1]
	v_pk_fma_f32 v[52:53], v[0:1], v[58:59], v[52:53] op_sel_hi:[1,0,1]
	v_pk_fma_f32 v[42:43], v[38:39], v[42:43], v[54:55] op_sel_hi:[1,0,1]
	v_pk_fma_f32 v[52:53], v[2:3], v[48:49], v[52:53] op_sel_hi:[1,0,1]
	s_waitcnt lgkmcnt(1)
	v_mov_b32_e32 v48, v63
	v_pk_fma_f32 v[70:71], v[16:17], v[60:61], 0 op_sel_hi:[1,0,0]
	v_mov_b32_e32 v57, v43
	v_pk_fma_f32 v[70:71], v[18:19], v[60:61], v[70:71] op_sel:[0,1,0]
	s_nop 0
	v_pk_fma_f32 v[70:71], v[20:21], v[62:63], v[70:71] op_sel_hi:[1,0,1]
	s_nop 0
	v_pk_fma_f32 v[70:71], v[22:23], v[48:49], v[70:71] op_sel_hi:[1,0,1]
	s_waitcnt lgkmcnt(0)
	v_mov_b32_e32 v48, v67
	v_pk_fma_f32 v[70:71], v[24:25], v[64:65], v[70:71] op_sel_hi:[1,0,1]
	s_nop 0
	v_pk_fma_f32 v[70:71], v[26:27], v[64:65], v[70:71] op_sel:[0,1,0]
	s_nop 0
	v_pk_fma_f32 v[70:71], v[28:29], v[66:67], v[70:71] op_sel_hi:[1,0,1]
	s_nop 0
	v_pk_fma_f32 v[70:71], v[30:31], v[48:49], v[70:71] op_sel_hi:[1,0,1]
	s_nop 0
	v_pk_add_f32 v[52:53], v[52:53], v[70:71]
	s_nop 0
	v_pk_add_f32 v[42:43], v[56:57], v[52:53]
	ds_read_b128 v[52:55], v45 offset:64
	ds_read_b128 v[56:59], v45 offset:80
	ds_read_b128 v[60:63], v45 offset:96
	ds_read_b128 v[64:67], v45 offset:112
	s_waitcnt lgkmcnt(3)
	v_pk_fma_f32 v[68:69], v[4:5], v[52:53], 0 op_sel_hi:[1,0,0]
	s_nop 0
	v_pk_fma_f32 v[52:53], v[6:7], v[52:53], v[68:69] op_sel:[0,1,0]
	v_mov_b32_e32 v48, v55
	v_pk_fma_f32 v[52:53], v[8:9], v[54:55], v[52:53] op_sel_hi:[1,0,1]
	v_pk_mul_f32 v[54:55], v[40:41], v[42:43] op_sel:[0,1]
	v_pk_fma_f32 v[52:53], v[10:11], v[48:49], v[52:53] op_sel_hi:[1,0,1]
	s_waitcnt lgkmcnt(2)
	v_mov_b32_e32 v48, v59
	v_pk_fma_f32 v[52:53], v[12:13], v[56:57], v[52:53] op_sel_hi:[1,0,1]
	s_nop 0
	v_pk_fma_f32 v[52:53], v[14:15], v[56:57], v[52:53] op_sel:[0,1,0]
	v_pk_fma_f32 v[56:57], v[38:39], v[42:43], v[54:55] neg_lo:[0,0,1] neg_hi:[0,0,1]
	v_pk_fma_f32 v[52:53], v[0:1], v[58:59], v[52:53] op_sel_hi:[1,0,1]
	v_pk_fma_f32 v[42:43], v[38:39], v[42:43], v[54:55] op_sel_hi:[1,0,1]
	v_pk_fma_f32 v[52:53], v[2:3], v[48:49], v[52:53] op_sel_hi:[1,0,1]
	s_waitcnt lgkmcnt(1)
	v_mov_b32_e32 v48, v63
	v_pk_fma_f32 v[70:71], v[16:17], v[60:61], 0 op_sel_hi:[1,0,0]
	v_mov_b32_e32 v57, v43
	v_pk_fma_f32 v[70:71], v[18:19], v[60:61], v[70:71] op_sel:[0,1,0]
	s_nop 0
	v_pk_fma_f32 v[70:71], v[20:21], v[62:63], v[70:71] op_sel_hi:[1,0,1]
	s_nop 0
	v_pk_fma_f32 v[70:71], v[22:23], v[48:49], v[70:71] op_sel_hi:[1,0,1]
	s_waitcnt lgkmcnt(0)
	v_mov_b32_e32 v48, v67
	v_pk_fma_f32 v[70:71], v[24:25], v[64:65], v[70:71] op_sel_hi:[1,0,1]
	s_nop 0
	v_pk_fma_f32 v[70:71], v[26:27], v[64:65], v[70:71] op_sel:[0,1,0]
	s_nop 0
	v_pk_fma_f32 v[70:71], v[28:29], v[66:67], v[70:71] op_sel_hi:[1,0,1]
	s_nop 0
	v_pk_fma_f32 v[70:71], v[30:31], v[48:49], v[70:71] op_sel_hi:[1,0,1]
	s_nop 0
	v_pk_add_f32 v[52:53], v[52:53], v[70:71]
	s_nop 0
	v_pk_add_f32 v[42:43], v[56:57], v[52:53]
	ds_read_b128 v[52:55], v45 offset:128
	ds_read_b128 v[56:59], v45 offset:144
	ds_read_b128 v[60:63], v45 offset:160
	ds_read_b128 v[64:67], v45 offset:176
	s_waitcnt lgkmcnt(3)
; #define LAS __attribute__((address_space(3)))
; #define WAVE_SYNC() asm volatile("s_waitcnt lgkmcnt(0)" ::: "memory")
; template <int PASS>
; __device__ __forceinline__ void s5_scan(const Params& p, int l, int widx, int nw, int beff, int nblk, int lane, LAS unsigned char* lds) {
;     ...
;         for (int bt = 0; bt < 16; ++bt) {
;             LAS float* ubc = ub + (bt & 1) * 256;
;             *(LAS f32x4*)(ubc + lane * 4) = un;
;             if (bt + 1 < 16) un = *(const f32x4*)(ZS + (size_t)(m0 + (bt + 1) * 16 + (lane >> 2)) * 512 + g * 16 + (lane & 3) * 4);
;             WAVE_SYNC();
; #pragma unroll 4
;             for (int s = 0; s < 16; ++s) {
;                 const f32x4 u0 = *(LAS f32x4*)(ubc + s * 16), u1 = *(LAS f32x4*)(ubc + s * 16 + 4), u2 = *(LAS f32x4*)(ubc + s * 16 + 8), u3 = *(LAS f32x4*)(ubc + s * 16 + 12);
;                 float bur = 0.f, bui = 0.f;
; #pragma unroll
;                 for (int j = 0; j < 4; ++j) { bur += br[j] * u0[j]; bui += bi[j] * u0[j]; }
; #pragma unroll
;                 for (int j = 0; j < 4; ++j) { bur += br[4 + j] * u1[j]; bui += bi[4 + j] * u1[j]; }
; #pragma unroll
;                 for (int j = 0; j < 4; ++j) { bur += br[8 + j] * u2[j]; bui += bi[8 + j] * u2[j]; }
; #pragma unroll
;                 for (int j = 0; j < 4; ++j) { bur += br[12 + j] * u3[j]; bui += bi[12 + j] * u3[j]; }
;                 const float nxr = ar * xr - ai * xi + bur, nxi = ar * xi + ai * xr + bui; xr = nxr; xi = nxi;
	v_pk_fma_f32 v[68:69], v[4:5], v[52:53], 0 op_sel_hi:[1,0,0]
	s_nop 0
	v_pk_fma_f32 v[52:53], v[6:7], v[52:53], v[68:69] op_sel:[0,1,0]
	v_mov_b32_e32 v48, v55
	v_pk_fma_f32 v[52:53], v[8:9], v[54:55], v[52:53] op_sel_hi:[1,0,1]
	v_pk_mul_f32 v[54:55], v[40:41], v[42:43] op_sel:[0,1]
	v_pk_fma_f32 v[52:53], v[10:11], v[48:49], v[52:53] op_sel_hi:[1,0,1]
	s_waitcnt lgkmcnt(2)
	v_mov_b32_e32 v48, v59
	v_pk_fma_f32 v[52:53], v[12:13], v[56:57], v[52:53] op_sel_hi:[1,0,1]
	s_nop 0
	v_pk_fma_f32 v[52:53], v[14:15], v[56:57], v[52:53] op_sel:[0,1,0]
	v_pk_fma_f32 v[56:57], v[38:39], v[42:43], v[54:55] neg_lo:[0,0,1] neg_hi:[0,0,1]
	v_pk_fma_f32 v[52:53], v[0:1], v[58:59], v[52:53] op_sel_hi:[1,0,1]
	v_pk_fma_f32 v[42:43], v[38:39], v[42:43], v[54:55] op_sel_hi:[1,0,1]
	v_pk_fma_f32 v[52:53], v[2:3], v[48:49], v[52:53] op_sel_hi:[1,0,1]
	s_waitcnt lgkmcnt(1)
	v_mov_b32_e32 v48, v63
	v_pk_fma_f32 v[70:71], v[16:17], v[60:61], 0 op_sel_hi:[1,0,0]
	v_mov_b32_e32 v57, v43
	v_pk_fma_f32 v[70:71], v[18:19], v[60:61], v[70:71] op_sel:[0,1,0]
	s_nop 0
	v_pk_fma_f32 v[70:71], v[20:21], v[62:63], v[70:71] op_sel_hi:[1,0,1]
	s_nop 0
	v_pk_fma_f32 v[70:71], v[22:23], v[48:49], v[70:71] op_sel_hi:[1,0,1]
	s_waitcnt lgkmcnt(0)
	v_mov_b32_e32 v48, v67
	v_pk_fma_f32 v[70:71], v[24:25], v[64:65], v[70:71] op_sel_hi:[1,0,1]
	s_nop 0
	v_pk_fma_f32 v[70:71], v[26:27], v[64:65], v[70:71] op_sel:[0,1,0]
	s_nop 0
	v_pk_fma_f32 v[70:71], v[28:29], v[66:67], v[70:71] op_sel_hi:[1,0,1]
	s_nop 0
	v_pk_fma_f32 v[70:71], v[30:31], v[48:49], v[70:71] op_sel_hi:[1,0,1]
	s_nop 0
	v_pk_add_f32 v[52:53], v[52:53], v[70:71]
	s_nop 0
	v_pk_add_f32 v[42:43], v[56:57], v[52:53]
	ds_read_b128 v[52:55], v45 offset:192
	ds_read_b128 v[56:59], v45 offset:208
	ds_read_b128 v[60:63], v45 offset:224
	ds_read_b128 v[64:67], v45 offset:240
	s_waitcnt lgkmcnt(3)
	v_pk_fma_f32 v[68:69], v[4:5], v[52:53], 0 op_sel_hi:[1,0,0]
	s_nop 0
	v_pk_fma_f32 v[52:53], v[6:7], v[52:53], v[68:69] op_sel:[0,1,0]
	v_mov_b32_e32 v48, v55
	v_pk_fma_f32 v[52:53], v[8:9], v[54:55], v[52:53] op_sel_hi:[1,0,1]
	v_pk_mul_f32 v[54:55], v[40:41], v[42:43] op_sel:[0,1]
	v_pk_fma_f32 v[52:53], v[10:11], v[48:49], v[52:53] op_sel_hi:[1,0,1]
	s_waitcnt lgkmcnt(2)
	v_mov_b32_e32 v48, v59
	v_pk_fma_f32 v[52:53], v[12:13], v[56:57], v[52:53] op_sel_hi:[1,0,1]
	s_nop 0
	v_pk_fma_f32 v[52:53], v[14:15], v[56:57], v[52:53] op_sel:[0,1,0]
	v_pk_fma_f32 v[56:57], v[38:39], v[42:43], v[54:55] neg_lo:[0,0,1] neg_hi:[0,0,1]
	v_pk_fma_f32 v[52:53], v[0:1], v[58:59], v[52:53] op_sel_hi:[1,0,1]
	v_pk_fma_f32 v[42:43], v[38:39], v[42:43], v[54:55] op_sel_hi:[1,0,1]
	v_pk_fma_f32 v[52:53], v[2:3], v[48:49], v[52:53] op_sel_hi:[1,0,1]
	s_waitcnt lgkmcnt(1)
	v_mov_b32_e32 v48, v63
	v_pk_fma_f32 v[70:71], v[16:17], v[60:61], 0 op_sel_hi:[1,0,0]
	v_mov_b32_e32 v57, v43
	v_pk_fma_f32 v[70:71], v[18:19], v[60:61], v[70:71] op_sel:[0,1,0]
	s_nop 0
	v_pk_fma_f32 v[70:71], v[20:21], v[62:63], v[70:71] op_sel_hi:[1,0,1]
	s_nop 0
	v_pk_fma_f32 v[70:71], v[22:23], v[48:49], v[70:71] op_sel_hi:[1,0,1]
	s_waitcnt lgkmcnt(0)
	v_mov_b32_e32 v48, v67
	v_pk_fma_f32 v[70:71], v[24:25], v[64:65], v[70:71] op_sel_hi:[1,0,1]
	s_nop 0
	v_pk_fma_f32 v[70:71], v[26:27], v[64:65], v[70:71] op_sel:[0,1,0]
	s_nop 0
	v_pk_fma_f32 v[70:71], v[28:29], v[66:67], v[70:71] op_sel_hi:[1,0,1]
	s_nop 0
	v_pk_fma_f32 v[70:71], v[30:31], v[48:49], v[70:71] op_sel_hi:[1,0,1]
	s_nop 0
	v_pk_add_f32 v[52:53], v[52:53], v[70:71]
	s_nop 0
	v_pk_add_f32 v[42:43], v[56:57], v[52:53]
	s_cbranch_scc1 .LBB0_416
	s_waitcnt vmcnt(0)
	ds_write_b128 v51, v[32:35] offset:1024
	v_or_b32_e32 v32, 0xe0, v44
	v_ashrrev_i32_e32 v33, 31, v32
	v_lshlrev_b64 v[32:33], 11, v[32:33]
	v_lshl_add_u64 v[32:33], v[46:47], 0, v[32:33]
	global_load_dwordx4 v[32:35], v[32:33], off
	s_waitcnt lgkmcnt(0)
	s_mov_b32 s7, 0
.LBB0_418:
	s_add_i32 s8, s6, s7
	v_mov_b32_e32 v45, s8
	ds_read_b128 v[52:55], v45
	ds_read_b128 v[56:59], v45 offset:16
	ds_read_b128 v[60:63], v45 offset:32
	ds_read_b128 v[64:67], v45 offset:48
	s_addk_i32 s7, 0x100
	s_waitcnt lgkmcnt(3)
	v_pk_fma_f32 v[68:69], v[4:5], v[52:53], 0 op_sel_hi:[1,0,0]
	v_mov_b32_e32 v48, v55
	v_pk_fma_f32 v[52:53], v[6:7], v[52:53], v[68:69] op_sel:[0,1,0]
	s_cmpk_lg_i32 s7, 0x400
	v_pk_fma_f32 v[52:53], v[8:9], v[54:55], v[52:53] op_sel_hi:[1,0,1]
	v_pk_mul_f32 v[54:55], v[40:41], v[42:43] op_sel:[0,1]
	v_pk_fma_f32 v[52:53], v[10:11], v[48:49], v[52:53] op_sel_hi:[1,0,1]
	s_waitcnt lgkmcnt(2)
	v_mov_b32_e32 v48, v59
	v_pk_fma_f32 v[52:53], v[12:13], v[56:57], v[52:53] op_sel_hi:[1,0,1]
	s_nop 0
	v_pk_fma_f32 v[52:53], v[14:15], v[56:57], v[52:53] op_sel:[0,1,0]
	v_pk_fma_f32 v[56:57], v[38:39], v[42:43], v[54:55] neg_lo:[0,0,1] neg_hi:[0,0,1]
	v_pk_fma_f32 v[52:53], v[0:1], v[58:59], v[52:53] op_sel_hi:[1,0,1]
	v_pk_fma_f32 v[42:43], v[38:39], v[42:43], v[54:55] op_sel_hi:[1,0,1]
	v_pk_fma_f32 v[52:53], v[2:3], v[48:49], v[52:53] op_sel_hi:[1,0,1]
	s_waitcnt lgkmcnt(1)
	v_mov_b32_e32 v48, v63
	v_pk_fma_f32 v[70:71], v[16:17], v[60:61], 0 op_sel_hi:[1,0,0]
	v_mov_b32_e32 v57, v43
	v_pk_fma_f32 v[70:71], v[18:19], v[60:61], v[70:71] op_sel:[0,1,0]
	s_nop 0
	v_pk_fma_f32 v[70:71], v[20:21], v[62:63], v[70:71] op_sel_hi:[1,0,1]
	s_nop 0
	v_pk_fma_f32 v[70:71], v[22:23], v[48:49], v[70:71] op_sel_hi:[1,0,1]
	s_waitcnt lgkmcnt(0)
	v_mov_b32_e32 v48, v67
	v_pk_fma_f32 v[70:71], v[24:25], v[64:65], v[70:71] op_sel_hi:[1,0,1]
	s_nop 0
	v_pk_fma_f32 v[70:71], v[26:27], v[64:65], v[70:71] op_sel:[0,1,0]
	s_nop 0
	v_pk_fma_f32 v[70:71], v[28:29], v[66:67], v[70:71] op_sel_hi:[1,0,1]
	s_nop 0
	v_pk_fma_f32 v[70:71], v[30:31], v[48:49], v[70:71] op_sel_hi:[1,0,1]
	s_nop 0
	v_pk_add_f32 v[52:53], v[52:53], v[70:71]
	s_nop 0
	v_pk_add_f32 v[42:43], v[56:57], v[52:53]
	ds_read_b128 v[52:55], v45 offset:64
	ds_read_b128 v[56:59], v45 offset:80
	ds_read_b128 v[60:63], v45 offset:96
	ds_read_b128 v[64:67], v45 offset:112
	s_waitcnt lgkmcnt(3)
; #define LAS __attribute__((address_space(3)))
; #define WAVE_SYNC() asm volatile("s_waitcnt lgkmcnt(0)" ::: "memory")
; template <int PASS>
; __device__ __forceinline__ void s5_scan(const Params& p, int l, int widx, int nw, int beff, int nblk, int lane, LAS unsigned char* lds) {
;     ...
;         for (int bt = 0; bt < 16; ++bt) {
;             LAS float* ubc = ub + (bt & 1) * 256;
;             *(LAS f32x4*)(ubc + lane * 4) = un;
;             if (bt + 1 < 16) un = *(const f32x4*)(ZS + (size_t)(m0 + (bt + 1) * 16 + (lane >> 2)) * 512 + g * 16 + (lane & 3) * 4);
;             WAVE_SYNC();
; #pragma unroll 4
;             for (int s = 0; s < 16; ++s) {
;                 const f32x4 u0 = *(LAS f32x4*)(ubc + s * 16), u1 = *(LAS f32x4*)(ubc + s * 16 + 4), u2 = *(LAS f32x4*)(ubc + s * 16 + 8), u3 = *(LAS f32x4*)(ubc + s * 16 + 12);
;                 float bur = 0.f, bui = 0.f;
; #pragma unroll
;                 for (int j = 0; j < 4; ++j) { bur += br[j] * u0[j]; bui += bi[j] * u0[j]; }
; #pragma unroll
;                 for (int j = 0; j < 4; ++j) { bur += br[4 + j] * u1[j]; bui += bi[4 + j] * u1[j]; }
; #pragma unroll
;                 for (int j = 0; j < 4; ++j) { bur += br[8 + j] * u2[j]; bui += bi[8 + j] * u2[j]; }
; #pragma unroll
;                 for (int j = 0; j < 4; ++j) { bur += br[12 + j] * u3[j]; bui += bi[12 + j] * u3[j]; }
;                 const float nxr = ar * xr - ai * xi + bur, nxi = ar * xi + ai * xr + bui; xr = nxr; xi = nxi;
	v_pk_fma_f32 v[68:69], v[4:5], v[52:53], 0 op_sel_hi:[1,0,0]
	s_nop 0
	v_pk_fma_f32 v[52:53], v[6:7], v[52:53], v[68:69] op_sel:[0,1,0]
	v_mov_b32_e32 v48, v55
	v_pk_fma_f32 v[52:53], v[8:9], v[54:55], v[52:53] op_sel_hi:[1,0,1]
	v_pk_mul_f32 v[54:55], v[40:41], v[42:43] op_sel:[0,1]
	v_pk_fma_f32 v[52:53], v[10:11], v[48:49], v[52:53] op_sel_hi:[1,0,1]
	s_waitcnt lgkmcnt(2)
	v_mov_b32_e32 v48, v59
	v_pk_fma_f32 v[52:53], v[12:13], v[56:57], v[52:53] op_sel_hi:[1,0,1]
	s_nop 0
	v_pk_fma_f32 v[52:53], v[14:15], v[56:57], v[52:53] op_sel:[0,1,0]
	v_pk_fma_f32 v[56:57], v[38:39], v[42:43], v[54:55] neg_lo:[0,0,1] neg_hi:[0,0,1]
	v_pk_fma_f32 v[52:53], v[0:1], v[58:59], v[52:53] op_sel_hi:[1,0,1]
	v_pk_fma_f32 v[42:43], v[38:39], v[42:43], v[54:55] op_sel_hi:[1,0,1]
	v_pk_fma_f32 v[52:53], v[2:3], v[48:49], v[52:53] op_sel_hi:[1,0,1]
	s_waitcnt lgkmcnt(1)
	v_mov_b32_e32 v48, v63
	v_pk_fma_f32 v[70:71], v[16:17], v[60:61], 0 op_sel_hi:[1,0,0]
	v_mov_b32_e32 v57, v43
	v_pk_fma_f32 v[70:71], v[18:19], v[60:61], v[70:71] op_sel:[0,1,0]
	s_nop 0
	v_pk_fma_f32 v[70:71], v[20:21], v[62:63], v[70:71] op_sel_hi:[1,0,1]
	s_nop 0
	v_pk_fma_f32 v[70:71], v[22:23], v[48:49], v[70:71] op_sel_hi:[1,0,1]
	s_waitcnt lgkmcnt(0)
	v_mov_b32_e32 v48, v67
	v_pk_fma_f32 v[70:71], v[24:25], v[64:65], v[70:71] op_sel_hi:[1,0,1]
	s_nop 0
	v_pk_fma_f32 v[70:71], v[26:27], v[64:65], v[70:71] op_sel:[0,1,0]
	s_nop 0
	v_pk_fma_f32 v[70:71], v[28:29], v[66:67], v[70:71] op_sel_hi:[1,0,1]
	s_nop 0
	v_pk_fma_f32 v[70:71], v[30:31], v[48:49], v[70:71] op_sel_hi:[1,0,1]
	s_nop 0
	v_pk_add_f32 v[52:53], v[52:53], v[70:71]
	s_nop 0
	v_pk_add_f32 v[42:43], v[56:57], v[52:53]
	ds_read_b128 v[52:55], v45 offset:128
	ds_read_b128 v[56:59], v45 offset:144
	ds_read_b128 v[60:63], v45 offset:160
	ds_read_b128 v[64:67], v45 offset:176
	s_waitcnt lgkmcnt(3)
	v_pk_fma_f32 v[68:69], v[4:5], v[52:53], 0 op_sel_hi:[1,0,0]
	s_nop 0
	v_pk_fma_f32 v[52:53], v[6:7], v[52:53], v[68:69] op_sel:[0,1,0]
	v_mov_b32_e32 v48, v55
	v_pk_fma_f32 v[52:53], v[8:9], v[54:55], v[52:53] op_sel_hi:[1,0,1]
	v_pk_mul_f32 v[54:55], v[40:41], v[42:43] op_sel:[0,1]
	v_pk_fma_f32 v[52:53], v[10:11], v[48:49], v[52:53] op_sel_hi:[1,0,1]
	s_waitcnt lgkmcnt(2)
	v_mov_b32_e32 v48, v59
	v_pk_fma_f32 v[52:53], v[12:13], v[56:57], v[52:53] op_sel_hi:[1,0,1]
	s_nop 0
	v_pk_fma_f32 v[52:53], v[14:15], v[56:57], v[52:53] op_sel:[0,1,0]
	v_pk_fma_f32 v[56:57], v[38:39], v[42:43], v[54:55] neg_lo:[0,0,1] neg_hi:[0,0,1]
	v_pk_fma_f32 v[52:53], v[0:1], v[58:59], v[52:53] op_sel_hi:[1,0,1]
	v_pk_fma_f32 v[42:43], v[38:39], v[42:43], v[54:55] op_sel_hi:[1,0,1]
	v_pk_fma_f32 v[52:53], v[2:3], v[48:49], v[52:53] op_sel_hi:[1,0,1]
	s_waitcnt lgkmcnt(1)
	v_mov_b32_e32 v48, v63
	v_pk_fma_f32 v[70:71], v[16:17], v[60:61], 0 op_sel_hi:[1,0,0]
	v_mov_b32_e32 v57, v43
	v_pk_fma_f32 v[70:71], v[18:19], v[60:61], v[70:71] op_sel:[0,1,0]
	s_nop 0
	v_pk_fma_f32 v[70:71], v[20:21], v[62:63], v[70:71] op_sel_hi:[1,0,1]
	s_nop 0
	v_pk_fma_f32 v[70:71], v[22:23], v[48:49], v[70:71] op_sel_hi:[1,0,1]
	s_waitcnt lgkmcnt(0)
	v_mov_b32_e32 v48, v67
	v_pk_fma_f32 v[70:71], v[24:25], v[64:65], v[70:71] op_sel_hi:[1,0,1]
	s_nop 0
	v_pk_fma_f32 v[70:71], v[26:27], v[64:65], v[70:71] op_sel:[0,1,0]
	s_nop 0
	v_pk_fma_f32 v[70:71], v[28:29], v[66:67], v[70:71] op_sel_hi:[1,0,1]
	s_nop 0
	v_pk_fma_f32 v[70:71], v[30:31], v[48:49], v[70:71] op_sel_hi:[1,0,1]
	s_nop 0
	v_pk_add_f32 v[52:53], v[52:53], v[70:71]
	s_nop 0
	v_pk_add_f32 v[42:43], v[56:57], v[52:53]
	ds_read_b128 v[52:55], v45 offset:192
	ds_read_b128 v[56:59], v45 offset:208
	ds_read_b128 v[60:63], v45 offset:224
	ds_read_b128 v[64:67], v45 offset:240
	s_waitcnt lgkmcnt(3)
	v_pk_fma_f32 v[68:69], v[4:5], v[52:53], 0 op_sel_hi:[1,0,0]
	s_nop 0
	v_pk_fma_f32 v[52:53], v[6:7], v[52:53], v[68:69] op_sel:[0,1,0]
	v_mov_b32_e32 v48, v55
	v_pk_fma_f32 v[52:53], v[8:9], v[54:55], v[52:53] op_sel_hi:[1,0,1]
	v_pk_mul_f32 v[54:55], v[40:41], v[42:43] op_sel:[0,1]
	v_pk_fma_f32 v[52:53], v[10:11], v[48:49], v[52:53] op_sel_hi:[1,0,1]
	s_waitcnt lgkmcnt(2)
	v_mov_b32_e32 v48, v59
	v_pk_fma_f32 v[52:53], v[12:13], v[56:57], v[52:53] op_sel_hi:[1,0,1]
	s_nop 0
	v_pk_fma_f32 v[52:53], v[14:15], v[56:57], v[52:53] op_sel:[0,1,0]
	v_pk_fma_f32 v[56:57], v[38:39], v[42:43], v[54:55] neg_lo:[0,0,1] neg_hi:[0,0,1]
	v_pk_fma_f32 v[52:53], v[0:1], v[58:59], v[52:53] op_sel_hi:[1,0,1]
	v_pk_fma_f32 v[42:43], v[38:39], v[42:43], v[54:55] op_sel_hi:[1,0,1]
	v_pk_fma_f32 v[52:53], v[2:3], v[48:49], v[52:53] op_sel_hi:[1,0,1]
	s_waitcnt lgkmcnt(1)
	v_mov_b32_e32 v48, v63
	v_pk_fma_f32 v[70:71], v[16:17], v[60:61], 0 op_sel_hi:[1,0,0]
	v_mov_b32_e32 v57, v43
	v_pk_fma_f32 v[70:71], v[18:19], v[60:61], v[70:71] op_sel:[0,1,0]
	s_nop 0
	v_pk_fma_f32 v[70:71], v[20:21], v[62:63], v[70:71] op_sel_hi:[1,0,1]
	s_nop 0
	v_pk_fma_f32 v[70:71], v[22:23], v[48:49], v[70:71] op_sel_hi:[1,0,1]
	s_waitcnt lgkmcnt(0)
	v_mov_b32_e32 v48, v67
	v_pk_fma_f32 v[70:71], v[24:25], v[64:65], v[70:71] op_sel_hi:[1,0,1]
	s_nop 0
	v_pk_fma_f32 v[70:71], v[26:27], v[64:65], v[70:71] op_sel:[0,1,0]
	s_nop 0
	v_pk_fma_f32 v[70:71], v[28:29], v[66:67], v[70:71] op_sel_hi:[1,0,1]
	s_nop 0
	v_pk_fma_f32 v[70:71], v[30:31], v[48:49], v[70:71] op_sel_hi:[1,0,1]
	s_nop 0
	v_pk_add_f32 v[52:53], v[52:53], v[70:71]
	s_nop 0
	v_pk_add_f32 v[42:43], v[56:57], v[52:53]
	s_cbranch_scc1 .LBB0_418
	s_waitcnt vmcnt(0)
	ds_write_b128 v51, v[32:35]
	v_or_b32_e32 v32, 0xf0, v44
	v_ashrrev_i32_e32 v33, 31, v32
	v_lshlrev_b64 v[32:33], 11, v[32:33]
	v_lshl_add_u64 v[32:33], v[46:47], 0, v[32:33]
	global_load_dwordx4 v[32:35], v[32:33], off
	s_waitcnt lgkmcnt(0)
	s_mov_b32 s7, 0
; #define LAS __attribute__((address_space(3)))
; #define WAVE_SYNC() asm volatile("s_waitcnt lgkmcnt(0)" ::: "memory")
; template <int PASS>
; __device__ __forceinline__ void s5_scan(const Params& p, int l, int widx, int nw, int beff, int nblk, int lane, LAS unsigned char* lds) {
;     ...
;         for (int bt = 0; bt < 16; ++bt) {
;             LAS float* ubc = ub + (bt & 1) * 256;
;             *(LAS f32x4*)(ubc + lane * 4) = un;
;             if (bt + 1 < 16) un = *(const f32x4*)(ZS + (size_t)(m0 + (bt + 1) * 16 + (lane >> 2)) * 512 + g * 16 + (lane & 3) * 4);
;             WAVE_SYNC();
; #pragma unroll 4
;             for (int s = 0; s < 16; ++s) {
;                 const f32x4 u0 = *(LAS f32x4*)(ubc + s * 16), u1 = *(LAS f32x4*)(ubc + s * 16 + 4), u2 = *(LAS f32x4*)(ubc + s * 16 + 8), u3 = *(LAS f32x4*)(ubc + s * 16 + 12);
;                 float bur = 0.f, bui = 0.f;
; #pragma unroll
;                 for (int j = 0; j < 4; ++j) { bur += br[j] * u0[j]; bui += bi[j] * u0[j]; }
; #pragma unroll
;                 for (int j = 0; j < 4; ++j) { bur += br[4 + j] * u1[j]; bui += bi[4 + j] * u1[j]; }
; #pragma unroll
;                 for (int j = 0; j < 4; ++j) { bur += br[8 + j] * u2[j]; bui += bi[8 + j] * u2[j]; }
; #pragma unroll
;                 for (int j = 0; j < 4; ++j) { bur += br[12 + j] * u3[j]; bui += bi[12 + j] * u3[j]; }
;                 const float nxr = ar * xr - ai * xi + bur, nxi = ar * xi + ai * xr + bui; xr = nxr; xi = nxi;
.LBB0_420:
	s_add_i32 s8, s5, s7
	v_mov_b32_e32 v48, s8
	ds_read_b128 v[44:47], v48
	ds_read_b128 v[52:55], v48 offset:16
	ds_read_b128 v[56:59], v48 offset:32
	ds_read_b128 v[60:63], v48 offset:48
	s_addk_i32 s7, 0x100
	s_waitcnt lgkmcnt(3)
	v_pk_fma_f32 v[64:65], v[4:5], v[44:45], 0 op_sel_hi:[1,0,0]
	s_cmpk_lg_i32 s7, 0x400
	v_pk_fma_f32 v[44:45], v[6:7], v[44:45], v[64:65] op_sel:[0,1,0]
	s_nop 0
	v_pk_fma_f32 v[44:45], v[8:9], v[46:47], v[44:45] op_sel_hi:[1,0,1]
	v_mov_b32_e32 v46, v47
	v_pk_fma_f32 v[44:45], v[10:11], v[46:47], v[44:45] op_sel_hi:[1,0,1]
	s_waitcnt lgkmcnt(2)
	v_mov_b32_e32 v46, v55
	v_pk_fma_f32 v[44:45], v[12:13], v[52:53], v[44:45] op_sel_hi:[1,0,1]
	s_nop 0
	v_pk_fma_f32 v[44:45], v[14:15], v[52:53], v[44:45] op_sel:[0,1,0]
	s_nop 0
	v_pk_fma_f32 v[44:45], v[0:1], v[54:55], v[44:45] op_sel_hi:[1,0,1]
	s_nop 0
	v_pk_fma_f32 v[44:45], v[2:3], v[46:47], v[44:45] op_sel_hi:[1,0,1]
	s_waitcnt lgkmcnt(1)
	v_mov_b32_e32 v46, v59
	v_pk_fma_f32 v[70:71], v[16:17], v[56:57], 0 op_sel_hi:[1,0,0]
	s_nop 0
	v_pk_fma_f32 v[70:71], v[18:19], v[56:57], v[70:71] op_sel:[0,1,0]
	s_nop 0
	v_pk_fma_f32 v[70:71], v[20:21], v[58:59], v[70:71] op_sel_hi:[1,0,1]
	s_nop 0
	v_pk_fma_f32 v[70:71], v[22:23], v[46:47], v[70:71] op_sel_hi:[1,0,1]
	s_waitcnt lgkmcnt(0)
	v_mov_b32_e32 v46, v63
	v_pk_fma_f32 v[70:71], v[24:25], v[60:61], v[70:71] op_sel_hi:[1,0,1]
	s_nop 0
	v_pk_fma_f32 v[70:71], v[26:27], v[60:61], v[70:71] op_sel:[0,1,0]
	s_nop 0
	v_pk_fma_f32 v[70:71], v[28:29], v[62:63], v[70:71] op_sel_hi:[1,0,1]
	s_nop 0
	v_pk_fma_f32 v[70:71], v[30:31], v[46:47], v[70:71] op_sel_hi:[1,0,1]
	s_nop 0
	v_pk_add_f32 v[44:45], v[44:45], v[70:71]
	v_pk_mul_f32 v[46:47], v[40:41], v[42:43] op_sel:[0,1]
	s_nop 0
	v_pk_fma_f32 v[52:53], v[38:39], v[42:43], v[46:47] neg_lo:[0,0,1] neg_hi:[0,0,1]
	v_pk_fma_f32 v[42:43], v[38:39], v[42:43], v[46:47] op_sel_hi:[1,0,1]
	s_nop 0
	v_mov_b32_e32 v53, v43
	v_pk_add_f32 v[46:47], v[52:53], v[44:45]
	ds_read_b128 v[42:45], v48 offset:64
	ds_read_b128 v[52:55], v48 offset:80
	ds_read_b128 v[56:59], v48 offset:96
	ds_read_b128 v[60:63], v48 offset:112
	s_waitcnt lgkmcnt(3)
	v_pk_fma_f32 v[64:65], v[4:5], v[42:43], 0 op_sel_hi:[1,0,0]
	s_nop 0
	v_pk_fma_f32 v[42:43], v[6:7], v[42:43], v[64:65] op_sel:[0,1,0]
	s_nop 0
	v_pk_fma_f32 v[42:43], v[8:9], v[44:45], v[42:43] op_sel_hi:[1,0,1]
	v_mov_b32_e32 v44, v45
	v_pk_fma_f32 v[42:43], v[10:11], v[44:45], v[42:43] op_sel_hi:[1,0,1]
	s_waitcnt lgkmcnt(2)
	v_mov_b32_e32 v44, v55
	v_pk_fma_f32 v[42:43], v[12:13], v[52:53], v[42:43] op_sel_hi:[1,0,1]
	s_nop 0
	v_pk_fma_f32 v[42:43], v[14:15], v[52:53], v[42:43] op_sel:[0,1,0]
	s_nop 0
	v_pk_fma_f32 v[42:43], v[0:1], v[54:55], v[42:43] op_sel_hi:[1,0,1]
	s_nop 0
	v_pk_fma_f32 v[42:43], v[2:3], v[44:45], v[42:43] op_sel_hi:[1,0,1]
	s_waitcnt lgkmcnt(1)
	v_mov_b32_e32 v44, v59
	v_pk_fma_f32 v[70:71], v[16:17], v[56:57], 0 op_sel_hi:[1,0,0]
	s_nop 0
	v_pk_fma_f32 v[70:71], v[18:19], v[56:57], v[70:71] op_sel:[0,1,0]
	s_nop 0
	v_pk_fma_f32 v[70:71], v[20:21], v[58:59], v[70:71] op_sel_hi:[1,0,1]
	s_nop 0
	v_pk_fma_f32 v[70:71], v[22:23], v[44:45], v[70:71] op_sel_hi:[1,0,1]
	s_waitcnt lgkmcnt(0)
	v_mov_b32_e32 v44, v63
	v_pk_fma_f32 v[70:71], v[24:25], v[60:61], v[70:71] op_sel_hi:[1,0,1]
	s_nop 0
	v_pk_fma_f32 v[70:71], v[26:27], v[60:61], v[70:71] op_sel:[0,1,0]
	s_nop 0
	v_pk_fma_f32 v[70:71], v[28:29], v[62:63], v[70:71] op_sel_hi:[1,0,1]
	s_nop 0
	v_pk_fma_f32 v[70:71], v[30:31], v[44:45], v[70:71] op_sel_hi:[1,0,1]
	s_nop 0
	v_pk_add_f32 v[42:43], v[42:43], v[70:71]
	v_pk_mul_f32 v[44:45], v[40:41], v[46:47] op_sel:[0,1]
	s_nop 0
	v_pk_fma_f32 v[52:53], v[38:39], v[46:47], v[44:45] neg_lo:[0,0,1] neg_hi:[0,0,1]
	v_pk_fma_f32 v[44:45], v[38:39], v[46:47], v[44:45] op_sel_hi:[1,0,1]
	s_nop 0
	v_mov_b32_e32 v53, v45
	v_pk_add_f32 v[46:47], v[52:53], v[42:43]
	ds_read_b128 v[42:45], v48 offset:128
	ds_read_b128 v[52:55], v48 offset:144
	ds_read_b128 v[56:59], v48 offset:160
	ds_read_b128 v[60:63], v48 offset:176
	s_waitcnt lgkmcnt(3)
	v_pk_fma_f32 v[64:65], v[4:5], v[42:43], 0 op_sel_hi:[1,0,0]
	s_nop 0
	v_pk_fma_f32 v[42:43], v[6:7], v[42:43], v[64:65] op_sel:[0,1,0]
	s_nop 0
	v_pk_fma_f32 v[42:43], v[8:9], v[44:45], v[42:43] op_sel_hi:[1,0,1]
	v_mov_b32_e32 v44, v45
	v_pk_fma_f32 v[42:43], v[10:11], v[44:45], v[42:43] op_sel_hi:[1,0,1]
	s_waitcnt lgkmcnt(2)
	v_mov_b32_e32 v44, v55
	v_pk_fma_f32 v[42:43], v[12:13], v[52:53], v[42:43] op_sel_hi:[1,0,1]
	s_nop 0
	v_pk_fma_f32 v[42:43], v[14:15], v[52:53], v[42:43] op_sel:[0,1,0]
	s_nop 0
	v_pk_fma_f32 v[42:43], v[0:1], v[54:55], v[42:43] op_sel_hi:[1,0,1]
	s_nop 0
	v_pk_fma_f32 v[42:43], v[2:3], v[44:45], v[42:43] op_sel_hi:[1,0,1]
	s_waitcnt lgkmcnt(1)
	v_mov_b32_e32 v44, v59
	v_pk_fma_f32 v[70:71], v[16:17], v[56:57], 0 op_sel_hi:[1,0,0]
	s_nop 0
	v_pk_fma_f32 v[70:71], v[18:19], v[56:57], v[70:71] op_sel:[0,1,0]
	s_nop 0
	v_pk_fma_f32 v[70:71], v[20:21], v[58:59], v[70:71] op_sel_hi:[1,0,1]
	s_nop 0
	v_pk_fma_f32 v[70:71], v[22:23], v[44:45], v[70:71] op_sel_hi:[1,0,1]
	s_waitcnt lgkmcnt(0)
	v_mov_b32_e32 v44, v63
	v_pk_fma_f32 v[70:71], v[24:25], v[60:61], v[70:71] op_sel_hi:[1,0,1]
	s_nop 0
	v_pk_fma_f32 v[70:71], v[26:27], v[60:61], v[70:71] op_sel:[0,1,0]
	s_nop 0
	v_pk_fma_f32 v[70:71], v[28:29], v[62:63], v[70:71] op_sel_hi:[1,0,1]
	s_nop 0
	v_pk_fma_f32 v[70:71], v[30:31], v[44:45], v[70:71] op_sel_hi:[1,0,1]
	s_nop 0
	v_pk_add_f32 v[42:43], v[42:43], v[70:71]
	v_pk_mul_f32 v[44:45], v[40:41], v[46:47] op_sel:[0,1]
	s_nop 0
	v_pk_fma_f32 v[52:53], v[38:39], v[46:47], v[44:45] neg_lo:[0,0,1] neg_hi:[0,0,1]
	v_pk_fma_f32 v[44:45], v[38:39], v[46:47], v[44:45] op_sel_hi:[1,0,1]
	s_nop 0
	v_mov_b32_e32 v53, v45
	v_pk_add_f32 v[46:47], v[52:53], v[42:43]
	ds_read_b128 v[42:45], v48 offset:192
	ds_read_b128 v[52:55], v48 offset:208
	ds_read_b128 v[56:59], v48 offset:224
	ds_read_b128 v[60:63], v48 offset:240
	s_waitcnt lgkmcnt(3)
; #define LAS __attribute__((address_space(3)))
; #define WAVE_SYNC() asm volatile("s_waitcnt lgkmcnt(0)" ::: "memory")
; template <int PASS>
; __device__ __forceinline__ void s5_scan(const Params& p, int l, int widx, int nw, int beff, int nblk, int lane, LAS unsigned char* lds) {
;     ...
;         for (int bt = 0; bt < 16; ++bt) {
;             LAS float* ubc = ub + (bt & 1) * 256;
;             *(LAS f32x4*)(ubc + lane * 4) = un;
;             if (bt + 1 < 16) un = *(const f32x4*)(ZS + (size_t)(m0 + (bt + 1) * 16 + (lane >> 2)) * 512 + g * 16 + (lane & 3) * 4);
;             WAVE_SYNC();
; #pragma unroll 4
;             for (int s = 0; s < 16; ++s) {
;                 const f32x4 u0 = *(LAS f32x4*)(ubc + s * 16), u1 = *(LAS f32x4*)(ubc + s * 16 + 4), u2 = *(LAS f32x4*)(ubc + s * 16 + 8), u3 = *(LAS f32x4*)(ubc + s * 16 + 12);
;                 float bur = 0.f, bui = 0.f;
; #pragma unroll
;                 for (int j = 0; j < 4; ++j) { bur += br[j] * u0[j]; bui += bi[j] * u0[j]; }
; #pragma unroll
;                 for (int j = 0; j < 4; ++j) { bur += br[4 + j] * u1[j]; bui += bi[4 + j] * u1[j]; }
; #pragma unroll
;                 for (int j = 0; j < 4; ++j) { bur += br[8 + j] * u2[j]; bui += bi[8 + j] * u2[j]; }
; #pragma unroll
;                 for (int j = 0; j < 4; ++j) { bur += br[12 + j] * u3[j]; bui += bi[12 + j] * u3[j]; }
;                 const float nxr = ar * xr - ai * xi + bur, nxi = ar * xi + ai * xr + bui; xr = nxr; xi = nxi;
	v_pk_fma_f32 v[64:65], v[4:5], v[42:43], 0 op_sel_hi:[1,0,0]
	s_nop 0
	v_pk_fma_f32 v[42:43], v[6:7], v[42:43], v[64:65] op_sel:[0,1,0]
	s_nop 0
	v_pk_fma_f32 v[42:43], v[8:9], v[44:45], v[42:43] op_sel_hi:[1,0,1]
	v_mov_b32_e32 v44, v45
	v_pk_fma_f32 v[42:43], v[10:11], v[44:45], v[42:43] op_sel_hi:[1,0,1]
	s_waitcnt lgkmcnt(2)
	v_mov_b32_e32 v44, v55
	v_pk_fma_f32 v[42:43], v[12:13], v[52:53], v[42:43] op_sel_hi:[1,0,1]
	s_nop 0
	v_pk_fma_f32 v[42:43], v[14:15], v[52:53], v[42:43] op_sel:[0,1,0]
	s_nop 0
	v_pk_fma_f32 v[42:43], v[0:1], v[54:55], v[42:43] op_sel_hi:[1,0,1]
	s_nop 0
	v_pk_fma_f32 v[42:43], v[2:3], v[44:45], v[42:43] op_sel_hi:[1,0,1]
	s_waitcnt lgkmcnt(1)
	v_mov_b32_e32 v44, v59
	v_pk_fma_f32 v[70:71], v[16:17], v[56:57], 0 op_sel_hi:[1,0,0]
	s_nop 0
	v_pk_fma_f32 v[70:71], v[18:19], v[56:57], v[70:71] op_sel:[0,1,0]
	s_nop 0
	v_pk_fma_f32 v[70:71], v[20:21], v[58:59], v[70:71] op_sel_hi:[1,0,1]
	s_nop 0
	v_pk_fma_f32 v[70:71], v[22:23], v[44:45], v[70:71] op_sel_hi:[1,0,1]
	s_waitcnt lgkmcnt(0)
	v_mov_b32_e32 v44, v63
	v_pk_fma_f32 v[70:71], v[24:25], v[60:61], v[70:71] op_sel_hi:[1,0,1]
	s_nop 0
	v_pk_fma_f32 v[70:71], v[26:27], v[60:61], v[70:71] op_sel:[0,1,0]
	s_nop 0
	v_pk_fma_f32 v[70:71], v[28:29], v[62:63], v[70:71] op_sel_hi:[1,0,1]
	s_nop 0
	v_pk_fma_f32 v[70:71], v[30:31], v[44:45], v[70:71] op_sel_hi:[1,0,1]
	s_nop 0
	v_pk_add_f32 v[42:43], v[42:43], v[70:71]
	v_pk_mul_f32 v[44:45], v[40:41], v[46:47] op_sel:[0,1]
	s_nop 0
	v_pk_fma_f32 v[52:53], v[38:39], v[46:47], v[44:45] neg_lo:[0,0,1] neg_hi:[0,0,1]
	v_pk_fma_f32 v[44:45], v[38:39], v[46:47], v[44:45] op_sel_hi:[1,0,1]
	s_nop 0
	v_mov_b32_e32 v53, v45
	v_pk_add_f32 v[42:43], v[52:53], v[42:43]
	s_cbranch_scc1 .LBB0_420
	s_waitcnt vmcnt(0)
	ds_write_b128 v51, v[32:35] offset:1024
	s_waitcnt lgkmcnt(0)
	s_mov_b32 s7, 0
.LBB0_422:
	s_add_i32 s8, s6, s7
	v_mov_b32_e32 v48, s8
	ds_read_b128 v[32:35], v48
	ds_read_b128 v[44:47], v48 offset:16
	ds_read_b128 v[52:55], v48 offset:32
	ds_read_b128 v[56:59], v48 offset:48
	s_addk_i32 s7, 0x100
	s_waitcnt lgkmcnt(3)
	v_pk_fma_f32 v[60:61], v[4:5], v[32:33], 0 op_sel_hi:[1,0,0]
	s_cmpk_lg_i32 s7, 0x400
	v_pk_fma_f32 v[32:33], v[6:7], v[32:33], v[60:61] op_sel:[0,1,0]
	s_nop 0
	v_pk_fma_f32 v[32:33], v[8:9], v[34:35], v[32:33] op_sel_hi:[1,0,1]
	v_mov_b32_e32 v34, v35
	v_pk_fma_f32 v[32:33], v[10:11], v[34:35], v[32:33] op_sel_hi:[1,0,1]
	v_pk_mul_f32 v[34:35], v[40:41], v[42:43] op_sel:[0,1]
	s_waitcnt lgkmcnt(2)
	v_pk_fma_f32 v[32:33], v[12:13], v[44:45], v[32:33] op_sel_hi:[1,0,1]
	s_nop 0
	v_pk_fma_f32 v[32:33], v[14:15], v[44:45], v[32:33] op_sel:[0,1,0]
	v_mov_b32_e32 v44, v47
	v_pk_fma_f32 v[32:33], v[0:1], v[46:47], v[32:33] op_sel_hi:[1,0,1]
	s_nop 0
	v_pk_fma_f32 v[32:33], v[2:3], v[44:45], v[32:33] op_sel_hi:[1,0,1]
	s_waitcnt lgkmcnt(1)
	v_mov_b32_e32 v44, v55
	v_pk_fma_f32 v[70:71], v[16:17], v[52:53], 0 op_sel_hi:[1,0,0]
	s_nop 0
	v_pk_fma_f32 v[70:71], v[18:19], v[52:53], v[70:71] op_sel:[0,1,0]
	s_nop 0
	v_pk_fma_f32 v[70:71], v[20:21], v[54:55], v[70:71] op_sel_hi:[1,0,1]
	s_nop 0
	v_pk_fma_f32 v[70:71], v[22:23], v[44:45], v[70:71] op_sel_hi:[1,0,1]
	s_waitcnt lgkmcnt(0)
	v_mov_b32_e32 v44, v59
	v_pk_fma_f32 v[70:71], v[24:25], v[56:57], v[70:71] op_sel_hi:[1,0,1]
	s_nop 0
	v_pk_fma_f32 v[70:71], v[26:27], v[56:57], v[70:71] op_sel:[0,1,0]
	s_nop 0
	v_pk_fma_f32 v[70:71], v[28:29], v[58:59], v[70:71] op_sel_hi:[1,0,1]
	s_nop 0
	v_pk_fma_f32 v[70:71], v[30:31], v[44:45], v[70:71] op_sel_hi:[1,0,1]
	s_nop 0
	v_pk_add_f32 v[32:33], v[32:33], v[70:71]
	v_pk_fma_f32 v[44:45], v[38:39], v[42:43], v[34:35] neg_lo:[0,0,1] neg_hi:[0,0,1]
	v_pk_fma_f32 v[34:35], v[38:39], v[42:43], v[34:35] op_sel_hi:[1,0,1]
	s_nop 0
	v_mov_b32_e32 v45, v35
	v_pk_add_f32 v[46:47], v[44:45], v[32:33]
	ds_read_b128 v[32:35], v48 offset:64
	ds_read_b128 v[42:45], v48 offset:80
	ds_read_b128 v[52:55], v48 offset:96
	ds_read_b128 v[56:59], v48 offset:112
	s_waitcnt lgkmcnt(3)
	v_pk_fma_f32 v[60:61], v[4:5], v[32:33], 0 op_sel_hi:[1,0,0]
	s_nop 0
	v_pk_fma_f32 v[32:33], v[6:7], v[32:33], v[60:61] op_sel:[0,1,0]
	s_nop 0
	v_pk_fma_f32 v[32:33], v[8:9], v[34:35], v[32:33] op_sel_hi:[1,0,1]
	v_mov_b32_e32 v34, v35
	v_pk_fma_f32 v[32:33], v[10:11], v[34:35], v[32:33] op_sel_hi:[1,0,1]
	v_pk_mul_f32 v[34:35], v[40:41], v[46:47] op_sel:[0,1]
	s_waitcnt lgkmcnt(2)
	v_pk_fma_f32 v[32:33], v[12:13], v[42:43], v[32:33] op_sel_hi:[1,0,1]
	s_nop 0
	v_pk_fma_f32 v[32:33], v[14:15], v[42:43], v[32:33] op_sel:[0,1,0]
	v_mov_b32_e32 v42, v45
	v_pk_fma_f32 v[32:33], v[0:1], v[44:45], v[32:33] op_sel_hi:[1,0,1]
	s_nop 0
	v_pk_fma_f32 v[32:33], v[2:3], v[42:43], v[32:33] op_sel_hi:[1,0,1]
	s_waitcnt lgkmcnt(1)
; #define LAS __attribute__((address_space(3)))
; template <int PASS>
; __device__ __forceinline__ void s5_scan(const Params& p, int l, int widx, int nw, int beff, int nblk, int lane, LAS unsigned char* lds) {
;     ...
;     for (int u = widx * nblk + beff; u < 1024; u += nw * nblk) {
;     ...
;             for (int s = 0; s < 16; ++s) {
;                 const f32x4 u0 = *(LAS f32x4*)(ubc + s * 16), u1 = *(LAS f32x4*)(ubc + s * 16 + 4), u2 = *(LAS f32x4*)(ubc + s * 16 + 8), u3 = *(LAS f32x4*)(ubc + s * 16 + 12);
;                 float bur = 0.f, bui = 0.f;
; #pragma unroll
;                 for (int j = 0; j < 4; ++j) { bur += br[j] * u0[j]; bui += bi[j] * u0[j]; }
; #pragma unroll
;                 for (int j = 0; j < 4; ++j) { bur += br[4 + j] * u1[j]; bui += bi[4 + j] * u1[j]; }
; #pragma unroll
;                 for (int j = 0; j < 4; ++j) { bur += br[8 + j] * u2[j]; bui += bi[8 + j] * u2[j]; }
; #pragma unroll
;                 for (int j = 0; j < 4; ++j) { bur += br[12 + j] * u3[j]; bui += bi[12 + j] * u3[j]; }
;                 const float nxr = ar * xr - ai * xi + bur, nxi = ar * xi + ai * xr + bui; xr = nxr; xi = nxi;
;     ...
;         if (PASS == 1) { XE[(u * 64 + lane) * 2] = xr; XE[(u * 64 + lane) * 2 + 1] = xi; }
	v_mov_b32_e32 v42, v55
	v_pk_fma_f32 v[70:71], v[16:17], v[52:53], 0 op_sel_hi:[1,0,0]
	s_nop 0
	v_pk_fma_f32 v[70:71], v[18:19], v[52:53], v[70:71] op_sel:[0,1,0]
	s_nop 0
	v_pk_fma_f32 v[70:71], v[20:21], v[54:55], v[70:71] op_sel_hi:[1,0,1]
	s_nop 0
	v_pk_fma_f32 v[70:71], v[22:23], v[42:43], v[70:71] op_sel_hi:[1,0,1]
	s_waitcnt lgkmcnt(0)
	v_mov_b32_e32 v42, v59
	v_pk_fma_f32 v[70:71], v[24:25], v[56:57], v[70:71] op_sel_hi:[1,0,1]
	s_nop 0
	v_pk_fma_f32 v[70:71], v[26:27], v[56:57], v[70:71] op_sel:[0,1,0]
	s_nop 0
	v_pk_fma_f32 v[70:71], v[28:29], v[58:59], v[70:71] op_sel_hi:[1,0,1]
	s_nop 0
	v_pk_fma_f32 v[70:71], v[30:31], v[42:43], v[70:71] op_sel_hi:[1,0,1]
	s_nop 0
	v_pk_add_f32 v[32:33], v[32:33], v[70:71]
	v_pk_fma_f32 v[42:43], v[38:39], v[46:47], v[34:35] neg_lo:[0,0,1] neg_hi:[0,0,1]
	v_pk_fma_f32 v[34:35], v[38:39], v[46:47], v[34:35] op_sel_hi:[1,0,1]
	s_nop 0
	v_mov_b32_e32 v43, v35
	v_pk_add_f32 v[46:47], v[42:43], v[32:33]
	ds_read_b128 v[32:35], v48 offset:128
	ds_read_b128 v[42:45], v48 offset:144
	ds_read_b128 v[52:55], v48 offset:160
	ds_read_b128 v[56:59], v48 offset:176
	s_waitcnt lgkmcnt(3)
	v_pk_fma_f32 v[60:61], v[4:5], v[32:33], 0 op_sel_hi:[1,0,0]
	s_nop 0
	v_pk_fma_f32 v[32:33], v[6:7], v[32:33], v[60:61] op_sel:[0,1,0]
	s_nop 0
	v_pk_fma_f32 v[32:33], v[8:9], v[34:35], v[32:33] op_sel_hi:[1,0,1]
	v_mov_b32_e32 v34, v35
	v_pk_fma_f32 v[32:33], v[10:11], v[34:35], v[32:33] op_sel_hi:[1,0,1]
	v_pk_mul_f32 v[34:35], v[40:41], v[46:47] op_sel:[0,1]
	s_waitcnt lgkmcnt(2)
	v_pk_fma_f32 v[32:33], v[12:13], v[42:43], v[32:33] op_sel_hi:[1,0,1]
	s_nop 0
	v_pk_fma_f32 v[32:33], v[14:15], v[42:43], v[32:33] op_sel:[0,1,0]
	v_mov_b32_e32 v42, v45
	v_pk_fma_f32 v[32:33], v[0:1], v[44:45], v[32:33] op_sel_hi:[1,0,1]
	s_nop 0
	v_pk_fma_f32 v[32:33], v[2:3], v[42:43], v[32:33] op_sel_hi:[1,0,1]
	s_waitcnt lgkmcnt(1)
	v_mov_b32_e32 v42, v55
	v_pk_fma_f32 v[70:71], v[16:17], v[52:53], 0 op_sel_hi:[1,0,0]
	s_nop 0
	v_pk_fma_f32 v[70:71], v[18:19], v[52:53], v[70:71] op_sel:[0,1,0]
	s_nop 0
	v_pk_fma_f32 v[70:71], v[20:21], v[54:55], v[70:71] op_sel_hi:[1,0,1]
	s_nop 0
	v_pk_fma_f32 v[70:71], v[22:23], v[42:43], v[70:71] op_sel_hi:[1,0,1]
	s_waitcnt lgkmcnt(0)
	v_mov_b32_e32 v42, v59
	v_pk_fma_f32 v[70:71], v[24:25], v[56:57], v[70:71] op_sel_hi:[1,0,1]
	s_nop 0
	v_pk_fma_f32 v[70:71], v[26:27], v[56:57], v[70:71] op_sel:[0,1,0]
	s_nop 0
	v_pk_fma_f32 v[70:71], v[28:29], v[58:59], v[70:71] op_sel_hi:[1,0,1]
	s_nop 0
	v_pk_fma_f32 v[70:71], v[30:31], v[42:43], v[70:71] op_sel_hi:[1,0,1]
	s_nop 0
	v_pk_add_f32 v[32:33], v[32:33], v[70:71]
	v_pk_fma_f32 v[42:43], v[38:39], v[46:47], v[34:35] neg_lo:[0,0,1] neg_hi:[0,0,1]
	v_pk_fma_f32 v[34:35], v[38:39], v[46:47], v[34:35] op_sel_hi:[1,0,1]
	s_nop 0
	v_mov_b32_e32 v43, v35
	v_pk_add_f32 v[46:47], v[42:43], v[32:33]
	ds_read_b128 v[32:35], v48 offset:192
	ds_read_b128 v[42:45], v48 offset:208
	ds_read_b128 v[52:55], v48 offset:224
	ds_read_b128 v[56:59], v48 offset:240
	s_waitcnt lgkmcnt(3)
	v_pk_fma_f32 v[60:61], v[4:5], v[32:33], 0 op_sel_hi:[1,0,0]
	s_nop 0
	v_pk_fma_f32 v[32:33], v[6:7], v[32:33], v[60:61] op_sel:[0,1,0]
	s_nop 0
	v_pk_fma_f32 v[32:33], v[8:9], v[34:35], v[32:33] op_sel_hi:[1,0,1]
	v_mov_b32_e32 v34, v35
	v_pk_fma_f32 v[32:33], v[10:11], v[34:35], v[32:33] op_sel_hi:[1,0,1]
	v_pk_mul_f32 v[34:35], v[40:41], v[46:47] op_sel:[0,1]
	s_waitcnt lgkmcnt(2)
	v_pk_fma_f32 v[32:33], v[12:13], v[42:43], v[32:33] op_sel_hi:[1,0,1]
	s_nop 0
	v_pk_fma_f32 v[32:33], v[14:15], v[42:43], v[32:33] op_sel:[0,1,0]
	v_mov_b32_e32 v42, v45
	v_pk_fma_f32 v[32:33], v[0:1], v[44:45], v[32:33] op_sel_hi:[1,0,1]
	s_nop 0
	v_pk_fma_f32 v[32:33], v[2:3], v[42:43], v[32:33] op_sel_hi:[1,0,1]
	s_waitcnt lgkmcnt(1)
	v_mov_b32_e32 v42, v55
	v_pk_fma_f32 v[70:71], v[16:17], v[52:53], 0 op_sel_hi:[1,0,0]
	s_nop 0
	v_pk_fma_f32 v[70:71], v[18:19], v[52:53], v[70:71] op_sel:[0,1,0]
	s_nop 0
	v_pk_fma_f32 v[70:71], v[20:21], v[54:55], v[70:71] op_sel_hi:[1,0,1]
	s_nop 0
	v_pk_fma_f32 v[70:71], v[22:23], v[42:43], v[70:71] op_sel_hi:[1,0,1]
	s_waitcnt lgkmcnt(0)
	v_mov_b32_e32 v42, v59
	v_pk_fma_f32 v[70:71], v[24:25], v[56:57], v[70:71] op_sel_hi:[1,0,1]
	s_nop 0
	v_pk_fma_f32 v[70:71], v[26:27], v[56:57], v[70:71] op_sel:[0,1,0]
	s_nop 0
	v_pk_fma_f32 v[70:71], v[28:29], v[58:59], v[70:71] op_sel_hi:[1,0,1]
	s_nop 0
	v_pk_fma_f32 v[70:71], v[30:31], v[42:43], v[70:71] op_sel_hi:[1,0,1]
	s_nop 0
	v_pk_add_f32 v[32:33], v[32:33], v[70:71]
	v_pk_fma_f32 v[42:43], v[38:39], v[46:47], v[34:35] neg_lo:[0,0,1] neg_hi:[0,0,1]
	v_pk_fma_f32 v[34:35], v[38:39], v[46:47], v[34:35] op_sel_hi:[1,0,1]
	s_nop 0
	v_mov_b32_e32 v43, v35
	v_pk_add_f32 v[42:43], v[42:43], v[32:33]
	s_cbranch_scc1 .LBB0_422
	v_lshl_or_b32 v0, s4, 7, v50
	v_ashrrev_i32_e32 v1, 31, v0
	s_add_i32 s4, s4, s3
	v_lshl_add_u64 v[0:1], v[0:1], 2, s[48:49]
	s_cmpk_gt_i32 s4, 0x3ff
	global_store_dwordx2 v[0:1], v[42:43], off
	s_cbranch_scc0 .LBB0_391
